# sc1 write-through stores for all data published across the three grid barriers (P0/P1/P2 outputs)
# baseline (speedup 1.0000x reference)
; __device__ __forceinline__ unsigned cvt_pk_bf16(float lo, float hi) { unsigned r; asm volatile("v_cvt_pk_bf16_f32 %0, %1, %2" : "=v"(r) : "v"(lo), "v"(hi)); return r; }
; #define LAS __attribute__((address_space(3)))
; #define LDS_WAIT() asm volatile("s_waitcnt lgkmcnt(0)" ::: "memory")
; __device__ __forceinline__ void tr_finish(const TrDesc& d, const TrRegs& t, LAS float* scr, int lane) {
;     const int nblk = d.N / 32, kb = d.item / nblk, nb = d.item - kb * nblk, k0 = 64 * kb, n0 = 32 * nb, c = lane & 7;
;     LAS float* sw = scr + (lane >> 5) * 33 + (lane & 31);
; #pragma unroll
;     for (int i = 0; i < 32; ++i) sw[(2 * i) * 33] = t.v[i];
;     LDS_WAIT(); asm volatile("" ::: "memory");
; #pragma unroll
;     for (int j = 0; j < 4; ++j) { const int n = (lane >> 3) + 8 * j; const LAS float* s = scr + (8 * c) * 33 + n;
;         v4u o; o.x = cvt_pk_bf16(s[0 * 33] * t.g0.x, s[1 * 33] * t.g0.y); o.y = cvt_pk_bf16(s[2 * 33] * t.g0.z, s[3 * 33] * t.g0.w); o.z = cvt_pk_bf16(s[4 * 33] * t.g1.x, s[5 * 33] * t.g1.y); o.w = cvt_pk_bf16(s[6 * 33] * t.g1.z, s[7 * 33] * t.g1.w);
;         *(v4u*)(d.WT + (size_t)map_row_rt(d.mode, n0 + n) * d.K + k0 + 8 * c) = o; }
;     LDS_WAIT(); asm volatile("" ::: "memory");
; }
; __global__ void __launch_bounds__(NWAVES * 64, 2) hymba_fwd(Args a) {
;     ...
;             while (it < NITEMS) {
;                 const int nx = it + NCW; const bool more = nx < NITEMS;
;                 if (more) { EARLY_DESC(dn, nx); tr_load(dn, lane, tn); }
;                 tr_finish(dc, tc, scr, lane);
;                 if (more) { dc = dn; tc = tn; }
;                 it = nx;
;             }
.LBB0_23:
	s_or_b64 exec, exec, s[8:9]
	v_ashrrev_i32_e32 v3, 31, v2
	v_lshlrev_b64 v[2:3], 12, v[2:3]
	v_lshl_add_u64 v[2:3], s[12:13], 0, v[2:3]
	v_lshl_add_u64 v[2:3], s[6:7], 1, v[2:3]
	v_lshl_add_u64 v[2:3], v[2:3], 0, v[24:25]
	global_store_dwordx4 v[2:3], v[6:9], off sc1
	s_waitcnt lgkmcnt(0)
	s_add_i32 s16, s16, s3
	s_add_i32 s20, s20, s21
	s_cmpk_lt_i32 s16, 0xa00
	s_mov_b32 s8, s54
	v_mov_b32_e32 v78, v94
	v_mov_b32_e32 v75, v87
	v_mov_b32_e32 v76, v88
	v_mov_b32_e32 v72, v89
	v_mov_b32_e32 v77, v90
	v_mov_b32_e32 v73, v91
	v_mov_b32_e32 v74, v92
	v_mov_b32_e32 v70, v93
	v_mov_b32_e32 v62, v86
	v_mov_b32_e32 v59, v79
	v_mov_b32_e32 v60, v80
	v_mov_b32_e32 v56, v81
	v_mov_b32_e32 v61, v82
	v_mov_b32_e32 v57, v83
	v_mov_b32_e32 v58, v84
	v_mov_b32_e32 v55, v85
	v_mov_b32_e32 v47, v71
	v_mov_b32_e32 v44, v69
	v_mov_b32_e32 v45, v68
	v_mov_b32_e32 v41, v67
	v_mov_b32_e32 v46, v66
	v_mov_b32_e32 v42, v65
	v_mov_b32_e32 v43, v64
	v_mov_b32_e32 v40, v63
	v_mov_b32_e32 v39, v54
	v_mov_b32_e32 v30, v53
	v_mov_b32_e32 v31, v52
	v_mov_b32_e32 v19, v51
	v_mov_b32_e32 v38, v50
	v_mov_b32_e32 v20, v49
	v_mov_b32_e32 v21, v48
	v_mov_b32_e32 v18, v29
	v_mov_b32_e32 v2, v10
	v_mov_b32_e32 v3, v11
	v_mov_b32_e32 v4, v12
	v_mov_b32_e32 v5, v13
	v_mov_b32_e32 v6, v14
	v_mov_b32_e32 v7, v15
	v_mov_b32_e32 v8, v16
	v_mov_b32_e32 v9, v17
	s_cbranch_scc0 .LBB0_61

; __device__ __forceinline__ unsigned cvt_pk_bf16(float lo, float hi) { unsigned r; asm volatile("v_cvt_pk_bf16_f32 %0, %1, %2" : "=v"(r) : "v"(lo), "v"(hi)); return r; }
; #define LAS __attribute__((address_space(3)))
; #define LDS_WAIT() asm volatile("s_waitcnt lgkmcnt(0)" ::: "memory")
; template <int MODE> __device__ __forceinline__ int map_row(int n) {
;     if (MODE == MAP_WIN) {
;         if (n < 1280) { const int d = n & 63; return (n & ~63) + (d < 32 ? 2 * d : 2 * (d - 32) + 1); }
;         if (n < 1536) return 2304 + (n - 1280);
;         return 1280 + (n - 1536);
;     }
; __device__ __forceinline__ void tr_finish(const TrDesc& d, const TrRegs& t, LAS float* scr, int lane) {
;     const int nblk = d.N / 32, kb = d.item / nblk, nb = d.item - kb * nblk, k0 = 64 * kb, n0 = 32 * nb, c = lane & 7;
;     LAS float* sw = scr + (lane >> 5) * 33 + (lane & 31);
; #pragma unroll
;     for (int i = 0; i < 32; ++i) sw[(2 * i) * 33] = t.v[i];
;     LDS_WAIT(); asm volatile("" ::: "memory");
; #pragma unroll
;     for (int j = 0; j < 4; ++j) { const int n = (lane >> 3) + 8 * j; const LAS float* s = scr + (8 * c) * 33 + n;
;         v4u o; o.x = cvt_pk_bf16(s[0 * 33] * t.g0.x, s[1 * 33] * t.g0.y); o.y = cvt_pk_bf16(s[2 * 33] * t.g0.z, s[3 * 33] * t.g0.w); o.z = cvt_pk_bf16(s[4 * 33] * t.g1.x, s[5 * 33] * t.g1.y); o.w = cvt_pk_bf16(s[6 * 33] * t.g1.z, s[7 * 33] * t.g1.w);
;         *(v4u*)(d.WT + (size_t)map_row_rt(d.mode, n0 + n) * d.K + k0 + 8 * c) = o; }
;     LDS_WAIT(); asm volatile("" ::: "memory");
; }
.LBB0_34:
.LBB0_35:
	s_or_saveexec_b64 s[6:7], s[6:7]
	s_and_b32 s60, s55, 0xffffffc0
	s_xor_b64 exec, exec, s[6:7]
	v_and_b32_e32 v30, 39, v31
	v_lshlrev_b32_e32 v31, 1, v30
	v_subrev_u32_e32 v38, 63, v31
	v_cmp_gt_u32_e32 vcc, 32, v30
	s_nop 1
	v_cndmask_b32_e32 v30, v38, v31, vcc
	v_add_u32_e32 v30, s60, v30
	s_or_b64 exec, exec, s[6:7]
	v_ashrrev_i32_e32 v31, 31, v30
	ds_read2_b32 v[38:39], v34 offset0:8 offset1:41
	s_lshl_b32 s6, s10, 6
	v_lshlrev_b64 v[30:31], 12, v[30:31]
	s_ashr_i32 s7, s6, 31
	v_lshl_add_u64 v[30:31], s[12:13], 0, v[30:31]
	v_lshl_add_u64 v[30:31], s[6:7], 1, v[30:31]
	v_lshl_add_u64 v[30:31], v[30:31], 0, v[24:25]
	global_store_dwordx4 v[30:31], v[18:21], off sc1
	v_or_b32_e32 v31, s55, v35
	v_cmp_lt_i32_e32 vcc, s53, v31
	s_waitcnt lgkmcnt(0)
	v_mul_f32_e32 v18, v6, v38
	v_mul_f32_e32 v19, v7, v39
	v_cvt_pk_bf16_f32 v18, v18, v19
	ds_read2_b32 v[20:21], v34 offset0:74 offset1:107
	s_waitcnt lgkmcnt(0)
	v_mul_f32_e32 v19, v8, v20
	v_mul_f32_e32 v20, v9, v21
	v_cvt_pk_bf16_f32 v19, v19, v20
	ds_read2_b32 v[20:21], v34 offset0:140 offset1:173
	s_waitcnt lgkmcnt(0)
	v_mul_f32_e32 v20, v2, v20
	v_mul_f32_e32 v21, v3, v21
	v_cvt_pk_bf16_f32 v20, v20, v21
	ds_read2_b32 v[38:39], v34 offset0:206 offset1:239
	s_waitcnt lgkmcnt(0)
	v_mul_f32_e32 v21, v4, v38
	v_mul_f32_e32 v30, v5, v39
	v_cvt_pk_bf16_f32 v21, v21, v30
	s_and_saveexec_b64 s[8:9], vcc
	s_xor_b64 s[8:9], exec, s[8:9]
	s_cbranch_execz .LBB0_43
	s_cmpk_lt_u32 s55, 0x600
	s_mov_b64 s[10:11], -1
	s_cbranch_scc1 .LBB0_40
	v_add_u32_e32 v30, 0xffffff00, v31
	s_mov_b64 s[10:11], 0

; __device__ __forceinline__ unsigned cvt_pk_bf16(float lo, float hi) { unsigned r; asm volatile("v_cvt_pk_bf16_f32 %0, %1, %2" : "=v"(r) : "v"(lo), "v"(hi)); return r; }
; #define LAS __attribute__((address_space(3)))
; #define LDS_WAIT() asm volatile("s_waitcnt lgkmcnt(0)" ::: "memory")
; template <int MODE> __device__ __forceinline__ int map_row(int n) {
;     if (MODE == MAP_WIN) {
;         if (n < 1280) { const int d = n & 63; return (n & ~63) + (d < 32 ? 2 * d : 2 * (d - 32) + 1); }
;         if (n < 1536) return 2304 + (n - 1280);
;         return 1280 + (n - 1536);
;     }
; __device__ __forceinline__ void tr_finish(const TrDesc& d, const TrRegs& t, LAS float* scr, int lane) {
;     const int nblk = d.N / 32, kb = d.item / nblk, nb = d.item - kb * nblk, k0 = 64 * kb, n0 = 32 * nb, c = lane & 7;
;     LAS float* sw = scr + (lane >> 5) * 33 + (lane & 31);
; #pragma unroll
;     for (int i = 0; i < 32; ++i) sw[(2 * i) * 33] = t.v[i];
;     LDS_WAIT(); asm volatile("" ::: "memory");
; #pragma unroll
;     for (int j = 0; j < 4; ++j) { const int n = (lane >> 3) + 8 * j; const LAS float* s = scr + (8 * c) * 33 + n;
;         v4u o; o.x = cvt_pk_bf16(s[0 * 33] * t.g0.x, s[1 * 33] * t.g0.y); o.y = cvt_pk_bf16(s[2 * 33] * t.g0.z, s[3 * 33] * t.g0.w); o.z = cvt_pk_bf16(s[4 * 33] * t.g1.x, s[5 * 33] * t.g1.y); o.w = cvt_pk_bf16(s[6 * 33] * t.g1.z, s[7 * 33] * t.g1.w);
;         *(v4u*)(d.WT + (size_t)map_row_rt(d.mode, n0 + n) * d.K + k0 + 8 * c) = o; }
;     LDS_WAIT(); asm volatile("" ::: "memory");
; }
.LBB0_42:
.LBB0_43:
	s_andn2_saveexec_b64 s[8:9], s[8:9]
	v_and_b32_e32 v30, 47, v31
	v_lshlrev_b32_e32 v31, 1, v30
	v_subrev_u32_e32 v38, 63, v31
	v_cmp_gt_u32_e32 vcc, 32, v30
	s_nop 1
	v_cndmask_b32_e32 v30, v38, v31, vcc
	v_add_u32_e32 v30, s60, v30
	s_or_b64 exec, exec, s[8:9]
	v_ashrrev_i32_e32 v31, 31, v30
	ds_read2_b32 v[38:39], v34 offset0:16 offset1:49
	v_lshlrev_b64 v[30:31], 12, v[30:31]
	v_lshl_add_u64 v[30:31], s[12:13], 0, v[30:31]
	v_lshl_add_u64 v[30:31], s[6:7], 1, v[30:31]
	v_lshl_add_u64 v[30:31], v[30:31], 0, v[24:25]
	global_store_dwordx4 v[30:31], v[18:21], off sc1
	v_or_b32_e32 v31, s55, v36
	v_cmp_lt_i32_e32 vcc, s53, v31
	s_waitcnt lgkmcnt(0)
	v_mul_f32_e32 v18, v6, v38
	v_mul_f32_e32 v19, v7, v39
	v_cvt_pk_bf16_f32 v18, v18, v19
	ds_read2_b32 v[20:21], v34 offset0:82 offset1:115
	s_waitcnt lgkmcnt(0)
	v_mul_f32_e32 v19, v8, v20
	v_mul_f32_e32 v20, v9, v21
	v_cvt_pk_bf16_f32 v19, v19, v20
	ds_read2_b32 v[20:21], v34 offset0:148 offset1:181
	s_waitcnt lgkmcnt(0)
	v_mul_f32_e32 v20, v2, v20
	v_mul_f32_e32 v21, v3, v21
	v_cvt_pk_bf16_f32 v20, v20, v21
	ds_read2_b32 v[38:39], v34 offset0:214 offset1:247
	s_waitcnt lgkmcnt(0)
	v_mul_f32_e32 v21, v4, v38
	v_mul_f32_e32 v30, v5, v39
	v_cvt_pk_bf16_f32 v21, v21, v30
	s_and_saveexec_b64 s[8:9], vcc
	s_xor_b64 s[8:9], exec, s[8:9]
	s_cbranch_execz .LBB0_51
	s_cmpk_lt_u32 s55, 0x600
	s_mov_b64 s[10:11], -1
	s_cbranch_scc1 .LBB0_48
	v_add_u32_e32 v30, 0xffffff00, v31
	s_mov_b64 s[10:11], 0

; __device__ __forceinline__ unsigned cvt_pk_bf16(float lo, float hi) { unsigned r; asm volatile("v_cvt_pk_bf16_f32 %0, %1, %2" : "=v"(r) : "v"(lo), "v"(hi)); return r; }
; #define LAS __attribute__((address_space(3)))
; #define LDS_WAIT() asm volatile("s_waitcnt lgkmcnt(0)" ::: "memory")
; template <int MODE> __device__ __forceinline__ int map_row(int n) {
;     if (MODE == MAP_WIN) {
;         if (n < 1280) { const int d = n & 63; return (n & ~63) + (d < 32 ? 2 * d : 2 * (d - 32) + 1); }
;         if (n < 1536) return 2304 + (n - 1280);
;         return 1280 + (n - 1536);
;     }
; __device__ __forceinline__ void tr_finish(const TrDesc& d, const TrRegs& t, LAS float* scr, int lane) {
;     const int nblk = d.N / 32, kb = d.item / nblk, nb = d.item - kb * nblk, k0 = 64 * kb, n0 = 32 * nb, c = lane & 7;
;     LAS float* sw = scr + (lane >> 5) * 33 + (lane & 31);
; #pragma unroll
;     for (int i = 0; i < 32; ++i) sw[(2 * i) * 33] = t.v[i];
;     LDS_WAIT(); asm volatile("" ::: "memory");
; #pragma unroll
;     for (int j = 0; j < 4; ++j) { const int n = (lane >> 3) + 8 * j; const LAS float* s = scr + (8 * c) * 33 + n;
;         v4u o; o.x = cvt_pk_bf16(s[0 * 33] * t.g0.x, s[1 * 33] * t.g0.y); o.y = cvt_pk_bf16(s[2 * 33] * t.g0.z, s[3 * 33] * t.g0.w); o.z = cvt_pk_bf16(s[4 * 33] * t.g1.x, s[5 * 33] * t.g1.y); o.w = cvt_pk_bf16(s[6 * 33] * t.g1.z, s[7 * 33] * t.g1.w);
;         *(v4u*)(d.WT + (size_t)map_row_rt(d.mode, n0 + n) * d.K + k0 + 8 * c) = o; }
;     LDS_WAIT(); asm volatile("" ::: "memory");
; }
.LBB0_50:
.LBB0_51:
	s_andn2_saveexec_b64 s[8:9], s[8:9]
	v_and_b32_e32 v30, 55, v31
	v_lshlrev_b32_e32 v31, 1, v30
	v_subrev_u32_e32 v38, 63, v31
	v_cmp_gt_u32_e32 vcc, 32, v30
	s_nop 1
	v_cndmask_b32_e32 v30, v38, v31, vcc
	v_add_u32_e32 v30, s60, v30
	s_or_b64 exec, exec, s[8:9]
	ds_read2_b32 v[38:39], v34 offset0:24 offset1:57
	v_ashrrev_i32_e32 v31, 31, v30
	v_lshlrev_b64 v[30:31], 12, v[30:31]
	v_lshl_add_u64 v[30:31], s[12:13], 0, v[30:31]
	v_lshl_add_u64 v[30:31], s[6:7], 1, v[30:31]
	v_lshl_add_u64 v[30:31], v[30:31], 0, v[24:25]
	s_waitcnt lgkmcnt(0)
	v_mul_f32_e32 v6, v6, v38
	global_store_dwordx4 v[30:31], v[18:21], off sc1
	v_mul_f32_e32 v7, v7, v39
	v_cvt_pk_bf16_f32 v6, v6, v7
	ds_read2_b32 v[18:19], v34 offset0:90 offset1:123
	s_waitcnt lgkmcnt(0)
	v_mul_f32_e32 v7, v8, v18
	v_mul_f32_e32 v8, v9, v19
	v_cvt_pk_bf16_f32 v7, v7, v8
	ds_read2_b32 v[8:9], v34 offset0:156 offset1:189
	s_waitcnt lgkmcnt(0)
	v_mul_f32_e32 v2, v2, v8
	v_mul_f32_e32 v3, v3, v9
	v_cvt_pk_bf16_f32 v8, v2, v3
	ds_read2_b32 v[18:19], v34 offset0:222 offset1:255
	v_or_b32_e32 v3, s55, v37
	v_cmp_lt_i32_e32 vcc, s53, v3
	s_waitcnt lgkmcnt(0)
	v_mul_f32_e32 v2, v4, v18
	v_mul_f32_e32 v4, v5, v19
	v_cvt_pk_bf16_f32 v9, v2, v4
	s_and_saveexec_b64 s[8:9], vcc
	s_xor_b64 s[8:9], exec, s[8:9]
	s_cbranch_execz .LBB0_59
	s_cmpk_lt_u32 s55, 0x600
	s_mov_b64 s[10:11], -1
	s_cbranch_scc1 .LBB0_56
	v_add_u32_e32 v2, 0xffffff00, v3
	s_mov_b64 s[10:11], 0

; __device__ __forceinline__ unsigned cvt_pk_bf16(float lo, float hi) { unsigned r; asm volatile("v_cvt_pk_bf16_f32 %0, %1, %2" : "=v"(r) : "v"(lo), "v"(hi)); return r; }
; __device__ __forceinline__ void ssm_precompute(const Args& a, int g, LAS unsigned char* lds, int tid) {
;     ...
;     bf16* TC = (bf16*)(a.ws + WS_TC) + (size_t)g * 256 * A2LD;
;     bf16* BZ = (bf16*)(a.ws + WS_BZ) + (size_t)g * 256 * 256;
;     {
;         const int row = tid >> 1, j = row >> 4, p = row & 15; const float dp = a.d_skip[g * 16 + p];
;         for (int ci = 0; ci < 16; ++ci) { const int col0 = 128 * (tid & 1) + 8 * ci, i = col0 >> 4, q0 = col0 & 15; float v[8];
; #pragma unroll
;             for (int e = 0; e < 8; ++e) { float t = 0.f; if (i <= j) { t = Kk[((j - i) * 16 + p) * 16 + q0 + e]; if (i == j && q0 + e == p) t += dp; } v[e] = t; }
;             v4u o; o.x = cvt_pk_bf16(v[0], v[1]); o.y = cvt_pk_bf16(v[2], v[3]); o.z = cvt_pk_bf16(v[4], v[5]); o.w = cvt_pk_bf16(v[6], v[7]);
;             *(v4u*)(TC + (size_t)row * A2LD + col0) = o; }
.LBB0_88:
	s_or_b64 exec, exec, s[4:5]
	s_mul_i32 s5, s2, 0x30000
	s_mul_hi_i32 s4, s2, 0x30000
	s_add_u32 s5, s94, s5
	s_addc_u32 s8, s95, s4
	s_add_u32 s4, s5, 0x5800000
	s_addc_u32 s5, s8, 0
	s_movk_i32 s8, 0x300
	v_mov_b64_e32 v[18:19], s[4:5]
	v_mad_i64_i32 v[2:3], s[4:5], v2, s8, v[18:19]
	v_cvt_pk_bf16_f32 v18, v5, v4
	v_cvt_pk_bf16_f32 v19, v7, v6
	v_lshlrev_b32_e32 v6, 1, v12
	v_mov_b32_e32 v7, 0
	v_lshl_add_u64 v[4:5], v[2:3], 0, v[6:7]
	v_mov_b32_e32 v6, 0
	v_cvt_pk_bf16_f32 v20, v15, v14
	v_cvt_pk_bf16_f32 v21, v17, v16
	global_store_dwordx4 v[4:5], v[18:21], off sc1
	s_and_saveexec_b64 s[4:5], s[6:7]
	s_cbranch_execz .LBB0_90
	ds_read_b32 v6, v13 offset:25120
	v_cmp_eq_u32_e64 s[8:9], 8, v8
	s_and_b64 s[8:9], s[8:9], vcc
	s_waitcnt vmcnt(1) lgkmcnt(0)
	v_add_f32_e32 v14, v10, v6
	v_cndmask_b32_e64 v6, v6, v14, s[8:9]

; __device__ __forceinline__ unsigned cvt_pk_bf16(float lo, float hi) { unsigned r; asm volatile("v_cvt_pk_bf16_f32 %0, %1, %2" : "=v"(r) : "v"(lo), "v"(hi)); return r; }
; __device__ __forceinline__ void ssm_precompute(const Args& a, int g, LAS unsigned char* lds, int tid) {
;     ...
;         const int row = tid >> 1, j = row >> 4, p = row & 15; const float dp = a.d_skip[g * 16 + p];
;         for (int ci = 0; ci < 16; ++ci) { const int col0 = 128 * (tid & 1) + 8 * ci, i = col0 >> 4, q0 = col0 & 15; float v[8];
; #pragma unroll
;             for (int e = 0; e < 8; ++e) { float t = 0.f; if (i <= j) { t = Kk[((j - i) * 16 + p) * 16 + q0 + e]; if (i == j && q0 + e == p) t += dp; } v[e] = t; }
;             v4u o; o.x = cvt_pk_bf16(v[0], v[1]); o.y = cvt_pk_bf16(v[2], v[3]); o.z = cvt_pk_bf16(v[4], v[5]); o.w = cvt_pk_bf16(v[6], v[7]);
;             *(v4u*)(TC + (size_t)row * A2LD + col0) = o; }
.LBB0_104:
	s_or_b64 exec, exec, s[4:5]
	v_cvt_pk_bf16_f32 v24, v6, v7
	v_or_b32_e32 v6, 16, v12
	v_lshrrev_b32_e32 v7, 4, v6
	v_sub_u32_e32 v6, v9, v7
	v_lshlrev_b32_e32 v6, 10, v6
	v_cvt_pk_bf16_f32 v25, v15, v14
	v_cmp_ge_i32_e64 s[6:7], v9, v7
	v_cmp_eq_u32_e32 vcc, v9, v7
	v_mov_b32_e32 v13, 0
	v_add_u32_e32 v6, v11, v6
	v_mov_b32_e32 v14, 0
	v_cvt_pk_bf16_f32 v26, v17, v16
	v_cvt_pk_bf16_f32 v27, v19, v18
	global_store_dwordx4 v[4:5], v[24:27], off offset:16 sc1
	s_and_saveexec_b64 s[4:5], s[6:7]
	s_cbranch_execz .LBB0_106
	ds_read_b32 v14, v6 offset:25088
	v_cmp_eq_u32_e64 s[8:9], 0, v8
	s_and_b64 s[8:9], s[8:9], vcc
	s_waitcnt vmcnt(2) lgkmcnt(0)
	v_add_f32_e32 v15, v10, v14
	v_cndmask_b32_e64 v14, v14, v15, s[8:9]

; __device__ __forceinline__ unsigned cvt_pk_bf16(float lo, float hi) { unsigned r; asm volatile("v_cvt_pk_bf16_f32 %0, %1, %2" : "=v"(r) : "v"(lo), "v"(hi)); return r; }
; __device__ __forceinline__ void ssm_precompute(const Args& a, int g, LAS unsigned char* lds, int tid) {
;     ...
;         const int row = tid >> 1, j = row >> 4, p = row & 15; const float dp = a.d_skip[g * 16 + p];
;         for (int ci = 0; ci < 16; ++ci) { const int col0 = 128 * (tid & 1) + 8 * ci, i = col0 >> 4, q0 = col0 & 15; float v[8];
; #pragma unroll
;             for (int e = 0; e < 8; ++e) { float t = 0.f; if (i <= j) { t = Kk[((j - i) * 16 + p) * 16 + q0 + e]; if (i == j && q0 + e == p) t += dp; } v[e] = t; }
;             v4u o; o.x = cvt_pk_bf16(v[0], v[1]); o.y = cvt_pk_bf16(v[2], v[3]); o.z = cvt_pk_bf16(v[4], v[5]); o.w = cvt_pk_bf16(v[6], v[7]);
;             *(v4u*)(TC + (size_t)row * A2LD + col0) = o; }
.LBB0_120:
	s_or_b64 exec, exec, s[4:5]
	v_cvt_pk_bf16_f32 v14, v14, v13
	v_cmp_ge_i32_e64 s[6:7], v9, v7
	v_cmp_eq_u32_e32 vcc, v9, v7
	v_mov_b32_e32 v7, 0
	v_mov_b32_e32 v13, 0
	v_cvt_pk_bf16_f32 v15, v16, v15
	v_cvt_pk_bf16_f32 v16, v18, v17
	v_cvt_pk_bf16_f32 v17, v20, v19
	global_store_dwordx4 v[4:5], v[14:17], off offset:32 sc1
	s_and_saveexec_b64 s[4:5], s[6:7]
	s_cbranch_execz .LBB0_122
	ds_read_b32 v13, v6 offset:25120
	v_cmp_eq_u32_e64 s[8:9], 8, v8
	s_and_b64 s[8:9], s[8:9], vcc
	s_waitcnt vmcnt(3) lgkmcnt(0)
	v_add_f32_e32 v14, v10, v13
	v_cndmask_b32_e64 v13, v13, v14, s[8:9]

; __device__ __forceinline__ unsigned cvt_pk_bf16(float lo, float hi) { unsigned r; asm volatile("v_cvt_pk_bf16_f32 %0, %1, %2" : "=v"(r) : "v"(lo), "v"(hi)); return r; }
; __device__ __forceinline__ void ssm_precompute(const Args& a, int g, LAS unsigned char* lds, int tid) {
;     ...
;         const int row = tid >> 1, j = row >> 4, p = row & 15; const float dp = a.d_skip[g * 16 + p];
;         for (int ci = 0; ci < 16; ++ci) { const int col0 = 128 * (tid & 1) + 8 * ci, i = col0 >> 4, q0 = col0 & 15; float v[8];
; #pragma unroll
;             for (int e = 0; e < 8; ++e) { float t = 0.f; if (i <= j) { t = Kk[((j - i) * 16 + p) * 16 + q0 + e]; if (i == j && q0 + e == p) t += dp; } v[e] = t; }
;             v4u o; o.x = cvt_pk_bf16(v[0], v[1]); o.y = cvt_pk_bf16(v[2], v[3]); o.z = cvt_pk_bf16(v[4], v[5]); o.w = cvt_pk_bf16(v[6], v[7]);
;             *(v4u*)(TC + (size_t)row * A2LD + col0) = o; }
.LBB0_136:
	s_or_b64 exec, exec, s[4:5]
	v_or_b32_e32 v6, 32, v12
	v_cvt_pk_bf16_f32 v24, v13, v7
	v_lshrrev_b32_e32 v7, 4, v6
	v_sub_u32_e32 v6, v9, v7
	v_lshlrev_b32_e32 v6, 10, v6
	v_cvt_pk_bf16_f32 v25, v15, v14
	v_cmp_ge_i32_e64 s[6:7], v9, v7
	v_cmp_eq_u32_e32 vcc, v9, v7
	v_mov_b32_e32 v13, 0
	v_add_u32_e32 v6, v11, v6
	v_mov_b32_e32 v14, 0
	v_cvt_pk_bf16_f32 v26, v17, v16
	v_cvt_pk_bf16_f32 v27, v19, v18
	global_store_dwordx4 v[4:5], v[24:27], off offset:48 sc1
	s_and_saveexec_b64 s[4:5], s[6:7]
	s_cbranch_execz .LBB0_138
	ds_read_b32 v14, v6 offset:25088
	v_cmp_eq_u32_e64 s[8:9], 0, v8
	s_and_b64 s[8:9], s[8:9], vcc
	s_waitcnt vmcnt(4) lgkmcnt(0)
	v_add_f32_e32 v15, v10, v14
	v_cndmask_b32_e64 v14, v14, v15, s[8:9]

; __device__ __forceinline__ unsigned cvt_pk_bf16(float lo, float hi) { unsigned r; asm volatile("v_cvt_pk_bf16_f32 %0, %1, %2" : "=v"(r) : "v"(lo), "v"(hi)); return r; }
; __device__ __forceinline__ void ssm_precompute(const Args& a, int g, LAS unsigned char* lds, int tid) {
;     ...
;         const int row = tid >> 1, j = row >> 4, p = row & 15; const float dp = a.d_skip[g * 16 + p];
;         for (int ci = 0; ci < 16; ++ci) { const int col0 = 128 * (tid & 1) + 8 * ci, i = col0 >> 4, q0 = col0 & 15; float v[8];
; #pragma unroll
;             for (int e = 0; e < 8; ++e) { float t = 0.f; if (i <= j) { t = Kk[((j - i) * 16 + p) * 16 + q0 + e]; if (i == j && q0 + e == p) t += dp; } v[e] = t; }
;             v4u o; o.x = cvt_pk_bf16(v[0], v[1]); o.y = cvt_pk_bf16(v[2], v[3]); o.z = cvt_pk_bf16(v[4], v[5]); o.w = cvt_pk_bf16(v[6], v[7]);
;             *(v4u*)(TC + (size_t)row * A2LD + col0) = o; }
.LBB0_152:
	s_or_b64 exec, exec, s[4:5]
	v_cvt_pk_bf16_f32 v14, v14, v13
	v_cmp_ge_i32_e64 s[6:7], v9, v7
	v_cmp_eq_u32_e32 vcc, v9, v7
	v_mov_b32_e32 v7, 0
	v_mov_b32_e32 v13, 0
	v_cvt_pk_bf16_f32 v15, v16, v15
	v_cvt_pk_bf16_f32 v16, v18, v17
	v_cvt_pk_bf16_f32 v17, v20, v19
	global_store_dwordx4 v[4:5], v[14:17], off offset:64 sc1
	s_and_saveexec_b64 s[4:5], s[6:7]
	s_cbranch_execz .LBB0_154
	ds_read_b32 v13, v6 offset:25120
	v_cmp_eq_u32_e64 s[8:9], 8, v8
	s_and_b64 s[8:9], s[8:9], vcc
	s_waitcnt vmcnt(5) lgkmcnt(0)
	v_add_f32_e32 v14, v10, v13
	v_cndmask_b32_e64 v13, v13, v14, s[8:9]

; __device__ __forceinline__ unsigned cvt_pk_bf16(float lo, float hi) { unsigned r; asm volatile("v_cvt_pk_bf16_f32 %0, %1, %2" : "=v"(r) : "v"(lo), "v"(hi)); return r; }
; __device__ __forceinline__ void ssm_precompute(const Args& a, int g, LAS unsigned char* lds, int tid) {
;     ...
;         const int row = tid >> 1, j = row >> 4, p = row & 15; const float dp = a.d_skip[g * 16 + p];
;         for (int ci = 0; ci < 16; ++ci) { const int col0 = 128 * (tid & 1) + 8 * ci, i = col0 >> 4, q0 = col0 & 15; float v[8];
; #pragma unroll
;             for (int e = 0; e < 8; ++e) { float t = 0.f; if (i <= j) { t = Kk[((j - i) * 16 + p) * 16 + q0 + e]; if (i == j && q0 + e == p) t += dp; } v[e] = t; }
;             v4u o; o.x = cvt_pk_bf16(v[0], v[1]); o.y = cvt_pk_bf16(v[2], v[3]); o.z = cvt_pk_bf16(v[4], v[5]); o.w = cvt_pk_bf16(v[6], v[7]);
;             *(v4u*)(TC + (size_t)row * A2LD + col0) = o; }
.LBB0_168:
	s_or_b64 exec, exec, s[4:5]
	v_or_b32_e32 v6, 48, v12
	v_cvt_pk_bf16_f32 v24, v13, v7
	v_lshrrev_b32_e32 v7, 4, v6
	v_sub_u32_e32 v6, v9, v7
	v_lshlrev_b32_e32 v6, 10, v6
	v_cvt_pk_bf16_f32 v25, v15, v14
	v_cmp_ge_i32_e64 s[6:7], v9, v7
	v_cmp_eq_u32_e32 vcc, v9, v7
	v_mov_b32_e32 v13, 0
	v_add_u32_e32 v6, v11, v6
	v_mov_b32_e32 v14, 0
	v_cvt_pk_bf16_f32 v26, v17, v16
	v_cvt_pk_bf16_f32 v27, v19, v18
	global_store_dwordx4 v[4:5], v[24:27], off offset:80 sc1
	s_and_saveexec_b64 s[4:5], s[6:7]
	s_cbranch_execz .LBB0_170
	ds_read_b32 v14, v6 offset:25088
	v_cmp_eq_u32_e64 s[8:9], 0, v8
	s_and_b64 s[8:9], s[8:9], vcc
	s_waitcnt vmcnt(6) lgkmcnt(0)
	v_add_f32_e32 v15, v10, v14
	v_cndmask_b32_e64 v14, v14, v15, s[8:9]

; __device__ __forceinline__ unsigned cvt_pk_bf16(float lo, float hi) { unsigned r; asm volatile("v_cvt_pk_bf16_f32 %0, %1, %2" : "=v"(r) : "v"(lo), "v"(hi)); return r; }
; __device__ __forceinline__ void ssm_precompute(const Args& a, int g, LAS unsigned char* lds, int tid) {
;     ...
;         const int row = tid >> 1, j = row >> 4, p = row & 15; const float dp = a.d_skip[g * 16 + p];
;         for (int ci = 0; ci < 16; ++ci) { const int col0 = 128 * (tid & 1) + 8 * ci, i = col0 >> 4, q0 = col0 & 15; float v[8];
; #pragma unroll
;             for (int e = 0; e < 8; ++e) { float t = 0.f; if (i <= j) { t = Kk[((j - i) * 16 + p) * 16 + q0 + e]; if (i == j && q0 + e == p) t += dp; } v[e] = t; }
;             v4u o; o.x = cvt_pk_bf16(v[0], v[1]); o.y = cvt_pk_bf16(v[2], v[3]); o.z = cvt_pk_bf16(v[4], v[5]); o.w = cvt_pk_bf16(v[6], v[7]);
;             *(v4u*)(TC + (size_t)row * A2LD + col0) = o; }
.LBB0_184:
	s_or_b64 exec, exec, s[4:5]
	v_cvt_pk_bf16_f32 v14, v14, v13
	v_cmp_ge_i32_e64 s[6:7], v9, v7
	v_cmp_eq_u32_e32 vcc, v9, v7
	v_mov_b32_e32 v7, 0
	v_mov_b32_e32 v13, 0
	v_cvt_pk_bf16_f32 v15, v16, v15
	v_cvt_pk_bf16_f32 v16, v18, v17
	v_cvt_pk_bf16_f32 v17, v20, v19
	global_store_dwordx4 v[4:5], v[14:17], off offset:96 sc1
	s_and_saveexec_b64 s[4:5], s[6:7]
	s_cbranch_execz .LBB0_186
	ds_read_b32 v13, v6 offset:25120
	v_cmp_eq_u32_e64 s[8:9], 8, v8
	s_and_b64 s[8:9], s[8:9], vcc
	s_waitcnt vmcnt(7) lgkmcnt(0)
	v_add_f32_e32 v14, v10, v13
	v_cndmask_b32_e64 v13, v13, v14, s[8:9]

; __device__ __forceinline__ unsigned cvt_pk_bf16(float lo, float hi) { unsigned r; asm volatile("v_cvt_pk_bf16_f32 %0, %1, %2" : "=v"(r) : "v"(lo), "v"(hi)); return r; }
; __device__ __forceinline__ void ssm_precompute(const Args& a, int g, LAS unsigned char* lds, int tid) {
;     ...
;         const int row = tid >> 1, j = row >> 4, p = row & 15; const float dp = a.d_skip[g * 16 + p];
;         for (int ci = 0; ci < 16; ++ci) { const int col0 = 128 * (tid & 1) + 8 * ci, i = col0 >> 4, q0 = col0 & 15; float v[8];
; #pragma unroll
;             for (int e = 0; e < 8; ++e) { float t = 0.f; if (i <= j) { t = Kk[((j - i) * 16 + p) * 16 + q0 + e]; if (i == j && q0 + e == p) t += dp; } v[e] = t; }
;             v4u o; o.x = cvt_pk_bf16(v[0], v[1]); o.y = cvt_pk_bf16(v[2], v[3]); o.z = cvt_pk_bf16(v[4], v[5]); o.w = cvt_pk_bf16(v[6], v[7]);
;             *(v4u*)(TC + (size_t)row * A2LD + col0) = o; }
.LBB0_200:
	s_or_b64 exec, exec, s[4:5]
	v_or_b32_e32 v6, 64, v12
	v_cvt_pk_bf16_f32 v24, v13, v7
	v_lshrrev_b32_e32 v7, 4, v6
	v_sub_u32_e32 v6, v9, v7
	v_lshlrev_b32_e32 v6, 10, v6
	v_cvt_pk_bf16_f32 v25, v15, v14
	v_cmp_ge_i32_e64 s[6:7], v9, v7
	v_cmp_eq_u32_e32 vcc, v9, v7
	v_mov_b32_e32 v13, 0
	v_add_u32_e32 v6, v11, v6
	v_mov_b32_e32 v14, 0
	v_cvt_pk_bf16_f32 v26, v17, v16
	v_cvt_pk_bf16_f32 v27, v19, v18
	global_store_dwordx4 v[4:5], v[24:27], off offset:112 sc1
	s_and_saveexec_b64 s[4:5], s[6:7]
	s_cbranch_execz .LBB0_202
	ds_read_b32 v14, v6 offset:25088
	v_cmp_eq_u32_e64 s[8:9], 0, v8
	s_and_b64 s[8:9], s[8:9], vcc
	s_waitcnt vmcnt(8) lgkmcnt(0)
	v_add_f32_e32 v15, v10, v14
	v_cndmask_b32_e64 v14, v14, v15, s[8:9]

; __device__ __forceinline__ unsigned cvt_pk_bf16(float lo, float hi) { unsigned r; asm volatile("v_cvt_pk_bf16_f32 %0, %1, %2" : "=v"(r) : "v"(lo), "v"(hi)); return r; }
; __device__ __forceinline__ void ssm_precompute(const Args& a, int g, LAS unsigned char* lds, int tid) {
;     ...
;         const int row = tid >> 1, j = row >> 4, p = row & 15; const float dp = a.d_skip[g * 16 + p];
;         for (int ci = 0; ci < 16; ++ci) { const int col0 = 128 * (tid & 1) + 8 * ci, i = col0 >> 4, q0 = col0 & 15; float v[8];
; #pragma unroll
;             for (int e = 0; e < 8; ++e) { float t = 0.f; if (i <= j) { t = Kk[((j - i) * 16 + p) * 16 + q0 + e]; if (i == j && q0 + e == p) t += dp; } v[e] = t; }
;             v4u o; o.x = cvt_pk_bf16(v[0], v[1]); o.y = cvt_pk_bf16(v[2], v[3]); o.z = cvt_pk_bf16(v[4], v[5]); o.w = cvt_pk_bf16(v[6], v[7]);
;             *(v4u*)(TC + (size_t)row * A2LD + col0) = o; }
.LBB0_216:
	s_or_b64 exec, exec, s[4:5]
	v_cvt_pk_bf16_f32 v14, v14, v13
	v_cmp_ge_i32_e64 s[6:7], v9, v7
	v_cmp_eq_u32_e32 vcc, v9, v7
	v_mov_b32_e32 v7, 0
	v_mov_b32_e32 v13, 0
	v_cvt_pk_bf16_f32 v15, v16, v15
	v_cvt_pk_bf16_f32 v16, v18, v17
	v_cvt_pk_bf16_f32 v17, v20, v19
	global_store_dwordx4 v[4:5], v[14:17], off offset:128 sc1
	s_and_saveexec_b64 s[4:5], s[6:7]
	s_cbranch_execz .LBB0_218
	ds_read_b32 v13, v6 offset:25120
	v_cmp_eq_u32_e64 s[8:9], 8, v8
	s_and_b64 s[8:9], s[8:9], vcc
	s_waitcnt vmcnt(9) lgkmcnt(0)
	v_add_f32_e32 v14, v10, v13
	v_cndmask_b32_e64 v13, v13, v14, s[8:9]

; __device__ __forceinline__ unsigned cvt_pk_bf16(float lo, float hi) { unsigned r; asm volatile("v_cvt_pk_bf16_f32 %0, %1, %2" : "=v"(r) : "v"(lo), "v"(hi)); return r; }
; __device__ __forceinline__ void ssm_precompute(const Args& a, int g, LAS unsigned char* lds, int tid) {
;     ...
;         const int row = tid >> 1, j = row >> 4, p = row & 15; const float dp = a.d_skip[g * 16 + p];
;         for (int ci = 0; ci < 16; ++ci) { const int col0 = 128 * (tid & 1) + 8 * ci, i = col0 >> 4, q0 = col0 & 15; float v[8];
; #pragma unroll
;             for (int e = 0; e < 8; ++e) { float t = 0.f; if (i <= j) { t = Kk[((j - i) * 16 + p) * 16 + q0 + e]; if (i == j && q0 + e == p) t += dp; } v[e] = t; }
;             v4u o; o.x = cvt_pk_bf16(v[0], v[1]); o.y = cvt_pk_bf16(v[2], v[3]); o.z = cvt_pk_bf16(v[4], v[5]); o.w = cvt_pk_bf16(v[6], v[7]);
;             *(v4u*)(TC + (size_t)row * A2LD + col0) = o; }
.LBB0_232:
	s_or_b64 exec, exec, s[4:5]
	v_or_b32_e32 v6, 0x50, v12
	v_lshrrev_b32_e32 v6, 4, v6
	v_cvt_pk_bf16_f32 v24, v13, v7
	v_sub_u32_e32 v7, v9, v6
	v_lshlrev_b32_e32 v7, 10, v7
	v_cmp_ge_i32_e64 s[6:7], v9, v6
	v_cmp_eq_u32_e32 vcc, v9, v6
	v_mov_b32_e32 v6, 0
	v_add_u32_e32 v13, v11, v7
	v_mov_b32_e32 v7, 0
	v_cvt_pk_bf16_f32 v25, v15, v14
	v_cvt_pk_bf16_f32 v26, v17, v16
	v_cvt_pk_bf16_f32 v27, v19, v18
	global_store_dwordx4 v[4:5], v[24:27], off offset:144 sc1
	s_and_saveexec_b64 s[4:5], s[6:7]
	s_cbranch_execz .LBB0_234
	ds_read_b32 v7, v13 offset:25088
	v_cmp_eq_u32_e64 s[8:9], 0, v8
	s_and_b64 s[8:9], s[8:9], vcc
	s_waitcnt vmcnt(10) lgkmcnt(0)
	v_add_f32_e32 v14, v10, v7
	v_cndmask_b32_e64 v7, v7, v14, s[8:9]

; __device__ __forceinline__ unsigned cvt_pk_bf16(float lo, float hi) { unsigned r; asm volatile("v_cvt_pk_bf16_f32 %0, %1, %2" : "=v"(r) : "v"(lo), "v"(hi)); return r; }
; __device__ __forceinline__ void ssm_precompute(const Args& a, int g, LAS unsigned char* lds, int tid) {
;     ...
;         const int row = tid >> 1, j = row >> 4, p = row & 15; const float dp = a.d_skip[g * 16 + p];
;         for (int ci = 0; ci < 16; ++ci) { const int col0 = 128 * (tid & 1) + 8 * ci, i = col0 >> 4, q0 = col0 & 15; float v[8];
; #pragma unroll
;             for (int e = 0; e < 8; ++e) { float t = 0.f; if (i <= j) { t = Kk[((j - i) * 16 + p) * 16 + q0 + e]; if (i == j && q0 + e == p) t += dp; } v[e] = t; }
;             v4u o; o.x = cvt_pk_bf16(v[0], v[1]); o.y = cvt_pk_bf16(v[2], v[3]); o.z = cvt_pk_bf16(v[4], v[5]); o.w = cvt_pk_bf16(v[6], v[7]);
;             *(v4u*)(TC + (size_t)row * A2LD + col0) = o; }
.LBB0_248:
	s_or_b64 exec, exec, s[4:5]
	v_cvt_pk_bf16_f32 v24, v7, v6
	v_or_b32_e32 v6, 0x50, v12
	v_lshrrev_b32_e32 v6, 4, v6
	v_sub_u32_e32 v7, v9, v6
	v_lshlrev_b32_e32 v7, 10, v7
	v_cmp_ge_i32_e64 s[6:7], v9, v6
	v_cmp_eq_u32_e32 vcc, v9, v6
	v_mov_b32_e32 v6, 0
	v_add_u32_e32 v13, v11, v7
	v_mov_b32_e32 v7, 0
	v_cvt_pk_bf16_f32 v25, v15, v14
	v_cvt_pk_bf16_f32 v26, v17, v16
	v_cvt_pk_bf16_f32 v27, v19, v18
	global_store_dwordx4 v[4:5], v[24:27], off offset:160 sc1
	s_and_saveexec_b64 s[4:5], s[6:7]
	s_cbranch_execz .LBB0_250
	ds_read_b32 v7, v13 offset:25120
	v_cmp_eq_u32_e64 s[8:9], 8, v8
	s_and_b64 s[8:9], s[8:9], vcc
	s_waitcnt vmcnt(11) lgkmcnt(0)
	v_add_f32_e32 v14, v10, v7
	v_cndmask_b32_e64 v7, v7, v14, s[8:9]

; __device__ __forceinline__ unsigned cvt_pk_bf16(float lo, float hi) { unsigned r; asm volatile("v_cvt_pk_bf16_f32 %0, %1, %2" : "=v"(r) : "v"(lo), "v"(hi)); return r; }
; __device__ __forceinline__ void ssm_precompute(const Args& a, int g, LAS unsigned char* lds, int tid) {
;     ...
;         const int row = tid >> 1, j = row >> 4, p = row & 15; const float dp = a.d_skip[g * 16 + p];
;         for (int ci = 0; ci < 16; ++ci) { const int col0 = 128 * (tid & 1) + 8 * ci, i = col0 >> 4, q0 = col0 & 15; float v[8];
; #pragma unroll
;             for (int e = 0; e < 8; ++e) { float t = 0.f; if (i <= j) { t = Kk[((j - i) * 16 + p) * 16 + q0 + e]; if (i == j && q0 + e == p) t += dp; } v[e] = t; }
;             v4u o; o.x = cvt_pk_bf16(v[0], v[1]); o.y = cvt_pk_bf16(v[2], v[3]); o.z = cvt_pk_bf16(v[4], v[5]); o.w = cvt_pk_bf16(v[6], v[7]);
;             *(v4u*)(TC + (size_t)row * A2LD + col0) = o; }
.LBB0_264:
	s_or_b64 exec, exec, s[4:5]
	v_cvt_pk_bf16_f32 v24, v7, v6
	v_or_b32_e32 v6, 0x60, v12
	v_lshrrev_b32_e32 v6, 4, v6
	v_sub_u32_e32 v7, v9, v6
	v_lshlrev_b32_e32 v7, 10, v7
	v_cmp_ge_i32_e64 s[6:7], v9, v6
	v_cmp_eq_u32_e32 vcc, v9, v6
	v_mov_b32_e32 v6, 0
	v_add_u32_e32 v13, v11, v7
	v_mov_b32_e32 v7, 0
	v_cvt_pk_bf16_f32 v25, v15, v14
	v_cvt_pk_bf16_f32 v26, v17, v16
	v_cvt_pk_bf16_f32 v27, v19, v18
	global_store_dwordx4 v[4:5], v[24:27], off offset:176 sc1
	s_and_saveexec_b64 s[4:5], s[6:7]
	s_cbranch_execz .LBB0_266
	ds_read_b32 v7, v13 offset:25088
	v_cmp_eq_u32_e64 s[8:9], 0, v8
	s_and_b64 s[8:9], s[8:9], vcc
	s_waitcnt vmcnt(12) lgkmcnt(0)
	v_add_f32_e32 v14, v10, v7
	v_cndmask_b32_e64 v7, v7, v14, s[8:9]

; __device__ __forceinline__ unsigned cvt_pk_bf16(float lo, float hi) { unsigned r; asm volatile("v_cvt_pk_bf16_f32 %0, %1, %2" : "=v"(r) : "v"(lo), "v"(hi)); return r; }
; __device__ __forceinline__ void ssm_precompute(const Args& a, int g, LAS unsigned char* lds, int tid) {
;     ...
;         const int row = tid >> 1, j = row >> 4, p = row & 15; const float dp = a.d_skip[g * 16 + p];
;         for (int ci = 0; ci < 16; ++ci) { const int col0 = 128 * (tid & 1) + 8 * ci, i = col0 >> 4, q0 = col0 & 15; float v[8];
; #pragma unroll
;             for (int e = 0; e < 8; ++e) { float t = 0.f; if (i <= j) { t = Kk[((j - i) * 16 + p) * 16 + q0 + e]; if (i == j && q0 + e == p) t += dp; } v[e] = t; }
;             v4u o; o.x = cvt_pk_bf16(v[0], v[1]); o.y = cvt_pk_bf16(v[2], v[3]); o.z = cvt_pk_bf16(v[4], v[5]); o.w = cvt_pk_bf16(v[6], v[7]);
;             *(v4u*)(TC + (size_t)row * A2LD + col0) = o; }
.LBB0_280:
	s_or_b64 exec, exec, s[4:5]
	v_cvt_pk_bf16_f32 v24, v7, v6
	v_or_b32_e32 v6, 0x60, v12
	v_lshrrev_b32_e32 v6, 4, v6
	v_sub_u32_e32 v7, v9, v6
	v_lshlrev_b32_e32 v7, 10, v7
	v_cmp_ge_i32_e64 s[6:7], v9, v6
	v_cmp_eq_u32_e32 vcc, v9, v6
	v_mov_b32_e32 v6, 0
	v_add_u32_e32 v13, v11, v7
	v_mov_b32_e32 v7, 0
	v_cvt_pk_bf16_f32 v25, v15, v14
	v_cvt_pk_bf16_f32 v26, v17, v16
	v_cvt_pk_bf16_f32 v27, v19, v18
	global_store_dwordx4 v[4:5], v[24:27], off offset:192 sc1
	s_and_saveexec_b64 s[4:5], s[6:7]
	s_cbranch_execz .LBB0_282
	ds_read_b32 v7, v13 offset:25120
	v_cmp_eq_u32_e64 s[8:9], 8, v8
	s_and_b64 s[8:9], s[8:9], vcc
	s_waitcnt vmcnt(13) lgkmcnt(0)
	v_add_f32_e32 v14, v10, v7
	v_cndmask_b32_e64 v7, v7, v14, s[8:9]

; __device__ __forceinline__ unsigned cvt_pk_bf16(float lo, float hi) { unsigned r; asm volatile("v_cvt_pk_bf16_f32 %0, %1, %2" : "=v"(r) : "v"(lo), "v"(hi)); return r; }
; __device__ __forceinline__ void ssm_precompute(const Args& a, int g, LAS unsigned char* lds, int tid) {
;     ...
;         const int row = tid >> 1, j = row >> 4, p = row & 15; const float dp = a.d_skip[g * 16 + p];
;         for (int ci = 0; ci < 16; ++ci) { const int col0 = 128 * (tid & 1) + 8 * ci, i = col0 >> 4, q0 = col0 & 15; float v[8];
; #pragma unroll
;             for (int e = 0; e < 8; ++e) { float t = 0.f; if (i <= j) { t = Kk[((j - i) * 16 + p) * 16 + q0 + e]; if (i == j && q0 + e == p) t += dp; } v[e] = t; }
;             v4u o; o.x = cvt_pk_bf16(v[0], v[1]); o.y = cvt_pk_bf16(v[2], v[3]); o.z = cvt_pk_bf16(v[4], v[5]); o.w = cvt_pk_bf16(v[6], v[7]);
;             *(v4u*)(TC + (size_t)row * A2LD + col0) = o; }
.LBB0_296:
	s_or_b64 exec, exec, s[4:5]
	v_cvt_pk_bf16_f32 v24, v7, v6
	v_or_b32_e32 v6, 0x70, v12
	v_lshrrev_b32_e32 v6, 4, v6
	v_sub_u32_e32 v7, v9, v6
	v_lshlrev_b32_e32 v7, 10, v7
	v_cmp_ge_i32_e64 s[6:7], v9, v6
	v_cmp_eq_u32_e32 vcc, v9, v6
	v_mov_b32_e32 v6, 0
	v_add_u32_e32 v13, v11, v7
	v_mov_b32_e32 v7, 0
	v_cvt_pk_bf16_f32 v25, v15, v14
	v_cvt_pk_bf16_f32 v26, v17, v16
	v_cvt_pk_bf16_f32 v27, v19, v18
	global_store_dwordx4 v[4:5], v[24:27], off offset:208 sc1
	s_and_saveexec_b64 s[4:5], s[6:7]
	s_cbranch_execz .LBB0_298
	ds_read_b32 v7, v13 offset:25088
	v_cmp_eq_u32_e64 s[8:9], 0, v8
	s_and_b64 s[8:9], s[8:9], vcc
	s_waitcnt vmcnt(14) lgkmcnt(0)
	v_add_f32_e32 v14, v10, v7
	v_cndmask_b32_e64 v7, v7, v14, s[8:9]

; __device__ __forceinline__ unsigned cvt_pk_bf16(float lo, float hi) { unsigned r; asm volatile("v_cvt_pk_bf16_f32 %0, %1, %2" : "=v"(r) : "v"(lo), "v"(hi)); return r; }
; __device__ __forceinline__ void ssm_precompute(const Args& a, int g, LAS unsigned char* lds, int tid) {
;     ...
;         const int row = tid >> 1, j = row >> 4, p = row & 15; const float dp = a.d_skip[g * 16 + p];
;         for (int ci = 0; ci < 16; ++ci) { const int col0 = 128 * (tid & 1) + 8 * ci, i = col0 >> 4, q0 = col0 & 15; float v[8];
; #pragma unroll
;             for (int e = 0; e < 8; ++e) { float t = 0.f; if (i <= j) { t = Kk[((j - i) * 16 + p) * 16 + q0 + e]; if (i == j && q0 + e == p) t += dp; } v[e] = t; }
;             v4u o; o.x = cvt_pk_bf16(v[0], v[1]); o.y = cvt_pk_bf16(v[2], v[3]); o.z = cvt_pk_bf16(v[4], v[5]); o.w = cvt_pk_bf16(v[6], v[7]);
;             *(v4u*)(TC + (size_t)row * A2LD + col0) = o; }
.LBB0_312:
	s_or_b64 exec, exec, s[4:5]
	v_cvt_pk_bf16_f32 v24, v7, v6
	v_or_b32_e32 v6, 0x70, v12
	v_lshrrev_b32_e32 v6, 4, v6
	v_sub_u32_e32 v7, v9, v6
	v_lshlrev_b32_e32 v7, 10, v7
	v_cmp_ge_i32_e64 s[6:7], v9, v6
	v_cmp_eq_u32_e32 vcc, v9, v6
	v_mov_b32_e32 v6, 0
	v_add_u32_e32 v11, v11, v7
	v_mov_b32_e32 v7, 0
	v_cvt_pk_bf16_f32 v25, v15, v14
	v_cvt_pk_bf16_f32 v26, v17, v16
	v_cvt_pk_bf16_f32 v27, v19, v18
	global_store_dwordx4 v[4:5], v[24:27], off offset:224 sc1
	s_and_saveexec_b64 s[4:5], s[6:7]
	s_cbranch_execz .LBB0_314
	ds_read_b32 v7, v11 offset:25120
	v_cmp_eq_u32_e64 s[8:9], 8, v8
	s_and_b64 s[8:9], s[8:9], vcc
	s_waitcnt vmcnt(15) lgkmcnt(0)
	v_add_f32_e32 v12, v10, v7
	v_cndmask_b32_e64 v7, v7, v12, s[8:9]

; __device__ __forceinline__ unsigned cvt_pk_bf16(float lo, float hi) { unsigned r; asm volatile("v_cvt_pk_bf16_f32 %0, %1, %2" : "=v"(r) : "v"(lo), "v"(hi)); return r; }
; __device__ __forceinline__ void ssm_precompute(const Args& a, int g, LAS unsigned char* lds, int tid) {
;     ...
;         const int row = tid >> 1, j = row >> 4, p = row & 15; const float dp = a.d_skip[g * 16 + p];
;         for (int ci = 0; ci < 16; ++ci) { const int col0 = 128 * (tid & 1) + 8 * ci, i = col0 >> 4, q0 = col0 & 15; float v[8];
; #pragma unroll
;             for (int e = 0; e < 8; ++e) { float t = 0.f; if (i <= j) { t = Kk[((j - i) * 16 + p) * 16 + q0 + e]; if (i == j && q0 + e == p) t += dp; } v[e] = t; }
;             v4u o; o.x = cvt_pk_bf16(v[0], v[1]); o.y = cvt_pk_bf16(v[2], v[3]); o.z = cvt_pk_bf16(v[4], v[5]); o.w = cvt_pk_bf16(v[6], v[7]);
;             *(v4u*)(TC + (size_t)row * A2LD + col0) = o; }
;         for (int ci = 0; ci < 8; ++ci) { const int n0 = 32 * (tid & 1) + 4 * ci; float v[8];
; #pragma unroll
;             for (int e = 0; e < 4; ++e) { const f32x2v c = Cc[p * 64 + n0 + e], l = P[(j + 1) * 64 + n0 + e]; v[2 * e] = c.x * l.x - c.y * l.y; v[2 * e + 1] = -(c.x * l.y + c.y * l.x); }
;             v4u o; o.x = cvt_pk_bf16(v[0], v[1]); o.y = cvt_pk_bf16(v[2], v[3]); o.z = cvt_pk_bf16(v[4], v[5]); o.w = cvt_pk_bf16(v[6], v[7]);
;             *(v4u*)(TC + (size_t)row * A2LD + 256 + 2 * n0) = o; }
.LBB0_328:
	s_or_b64 exec, exec, s[4:5]
	s_waitcnt vmcnt(15)
	v_cvt_pk_bf16_f32 v10, v7, v6
	v_lshlrev_b32_e32 v6, 5, v22
	v_and_b32_e32 v23, 32, v6
	v_lshlrev_b32_e32 v6, 9, v8
	v_lshlrev_b32_e32 v8, 3, v23
	v_lshlrev_b32_e32 v7, 9, v9
	v_add3_u32 v26, 0, v6, v8
	v_cvt_pk_bf16_f32 v11, v13, v12
	v_cvt_pk_bf16_f32 v12, v15, v14
	v_cvt_pk_bf16_f32 v13, v17, v16
	v_add3_u32 v27, 0, v7, v8
	ds_read_b128 v[6:9], v26 offset:16896
	ds_read_b128 v[14:17], v27 offset:512
	global_store_dwordx4 v[4:5], v[10:13], off offset:240 sc1
	ds_read_b128 v[10:13], v26 offset:16912
	ds_read_b128 v[18:21], v27 offset:528
	s_lshl_b64 s[4:5], s[2:3], 17
	s_movk_i32 s3, 0x1800
	s_waitcnt lgkmcnt(2)
	v_pk_mul_f32 v[4:5], v[6:7], v[14:15]
	v_and_b32_e32 v30, 4, v22
	v_sub_f32_e32 v24, v4, v5
	v_pk_mul_f32 v[4:5], v[6:7], v[14:15] op_sel:[0,1] op_sel_hi:[1,0]
	v_cmp_eq_u32_e32 vcc, 0, v30
	v_add_f32_e32 v4, v4, v5
	v_xor_b32_e32 v6, 0x80000000, v4
	v_pk_mul_f32 v[4:5], v[8:9], v[16:17]
	v_cvt_pk_bf16_f32 v6, v24, v6
	s_add_u32 s4, s94, s4
	v_sub_f32_e32 v7, v4, v5
	v_pk_mul_f32 v[4:5], v[8:9], v[16:17] op_sel:[0,1] op_sel_hi:[1,0]
	s_addc_u32 s5, s95, s5
	v_add_f32_e32 v4, v4, v5
	v_xor_b32_e32 v8, 0x80000000, v4
	s_waitcnt lgkmcnt(0)
	v_pk_mul_f32 v[4:5], v[10:11], v[18:19]
	v_cvt_pk_bf16_f32 v7, v7, v8
	s_mov_b32 s8, 0
	v_sub_f32_e32 v9, v4, v5
	v_pk_mul_f32 v[4:5], v[10:11], v[18:19] op_sel:[0,1] op_sel_hi:[1,0]
	s_mov_b32 s9, s8
	v_add_f32_e32 v4, v4, v5
	v_xor_b32_e32 v10, 0x80000000, v4
	v_pk_mul_f32 v[4:5], v[12:13], v[20:21]
	v_cvt_pk_bf16_f32 v8, v9, v10
	s_mov_b32 s10, s8
	v_sub_f32_e32 v11, v4, v5
	v_pk_mul_f32 v[4:5], v[12:13], v[20:21] op_sel:[0,1] op_sel_hi:[1,0]
	s_mov_b32 s11, s8
	v_add_f32_e32 v4, v4, v5
	v_xor_b32_e32 v4, 0x80000000, v4
	v_cvt_pk_bf16_f32 v9, v11, v4
	ds_read_b128 v[10:13], v26 offset:16928
	ds_read_b128 v[14:17], v27 offset:544
	v_lshlrev_b32_e32 v4, 2, v23
	v_mov_b32_e32 v5, 0
	v_lshl_add_u64 v[18:19], v[2:3], 0, v[4:5]
	global_store_dwordx4 v[18:19], v[6:9], off offset:512 sc1
	ds_read_b128 v[6:9], v26 offset:16944
	ds_read_b128 v[18:21], v27 offset:560
	s_waitcnt lgkmcnt(2)
	v_pk_mul_f32 v[24:25], v[10:11], v[14:15]
	v_pk_mul_f32 v[10:11], v[10:11], v[14:15] op_sel:[0,1] op_sel_hi:[1,0]
	v_sub_f32_e32 v23, v24, v25
	v_add_f32_e32 v10, v10, v11
	v_xor_b32_e32 v14, 0x80000000, v10
	v_pk_mul_f32 v[10:11], v[12:13], v[16:17]
	s_movk_i32 s16, 0x400
	v_sub_f32_e32 v15, v10, v11
	v_pk_mul_f32 v[10:11], v[12:13], v[16:17] op_sel:[0,1] op_sel_hi:[1,0]
	s_nop 0
	v_add_f32_e32 v10, v10, v11
	v_xor_b32_e32 v12, 0x80000000, v10
	s_waitcnt lgkmcnt(0)
	v_pk_mul_f32 v[10:11], v[6:7], v[18:19]
	v_pk_mul_f32 v[6:7], v[6:7], v[18:19] op_sel:[0,1] op_sel_hi:[1,0]
	v_sub_f32_e32 v10, v10, v11
	v_add_f32_e32 v6, v6, v7
	v_xor_b32_e32 v11, 0x80000000, v6
	v_pk_mul_f32 v[6:7], v[8:9], v[20:21]
	v_or_b32_e32 v18, 16, v4
	v_sub_f32_e32 v13, v6, v7
	v_pk_mul_f32 v[6:7], v[8:9], v[20:21] op_sel:[0,1] op_sel_hi:[1,0]
	v_mov_b32_e32 v19, v5
	v_add_f32_e32 v6, v6, v7
	v_xor_b32_e32 v9, 0x80000000, v6
	v_cvt_pk_bf16_f32 v6, v23, v14
	v_cvt_pk_bf16_f32 v7, v15, v12
	v_cvt_pk_bf16_f32 v8, v10, v11
	v_cvt_pk_bf16_f32 v9, v13, v9
	ds_read_b128 v[10:13], v26 offset:16960
	ds_read_b128 v[14:17], v27 offset:576
	v_lshl_add_u64 v[18:19], v[2:3], 0, v[18:19]
	global_store_dwordx4 v[18:19], v[6:9], off offset:512 sc1
	ds_read_b128 v[6:9], v26 offset:16976
	ds_read_b128 v[18:21], v27 offset:592
	s_waitcnt lgkmcnt(2)
	v_pk_mul_f32 v[24:25], v[10:11], v[14:15]
	v_pk_mul_f32 v[10:11], v[10:11], v[14:15] op_sel:[0,1] op_sel_hi:[1,0]
	v_sub_f32_e32 v23, v24, v25
	v_add_f32_e32 v10, v10, v11
	v_xor_b32_e32 v14, 0x80000000, v10
	v_pk_mul_f32 v[10:11], v[12:13], v[16:17]
	s_nop 0
	v_sub_f32_e32 v15, v10, v11
	v_pk_mul_f32 v[10:11], v[12:13], v[16:17] op_sel:[0,1] op_sel_hi:[1,0]
	s_nop 0
	v_add_f32_e32 v10, v10, v11
	v_xor_b32_e32 v12, 0x80000000, v10
	s_waitcnt lgkmcnt(0)
	v_pk_mul_f32 v[10:11], v[6:7], v[18:19]
	v_pk_mul_f32 v[6:7], v[6:7], v[18:19] op_sel:[0,1] op_sel_hi:[1,0]
	v_sub_f32_e32 v10, v10, v11
	v_add_f32_e32 v6, v6, v7
	v_xor_b32_e32 v11, 0x80000000, v6
	v_pk_mul_f32 v[6:7], v[8:9], v[20:21]
	v_or_b32_e32 v18, 32, v4
	v_sub_f32_e32 v13, v6, v7
	v_pk_mul_f32 v[6:7], v[8:9], v[20:21] op_sel:[0,1] op_sel_hi:[1,0]
	v_mov_b32_e32 v19, v5
	v_add_f32_e32 v6, v6, v7
	v_xor_b32_e32 v9, 0x80000000, v6
	v_cvt_pk_bf16_f32 v6, v23, v14
	v_cvt_pk_bf16_f32 v7, v15, v12
	v_cvt_pk_bf16_f32 v8, v10, v11
	v_cvt_pk_bf16_f32 v9, v13, v9
	ds_read_b128 v[10:13], v26 offset:16992
	ds_read_b128 v[14:17], v27 offset:608
	v_lshl_add_u64 v[18:19], v[2:3], 0, v[18:19]
	global_store_dwordx4 v[18:19], v[6:9], off offset:512 sc1
	ds_read_b128 v[6:9], v26 offset:17008
	ds_read_b128 v[18:21], v27 offset:624
	s_waitcnt lgkmcnt(2)
	v_pk_mul_f32 v[24:25], v[10:11], v[14:15]
	v_pk_mul_f32 v[10:11], v[10:11], v[14:15] op_sel:[0,1] op_sel_hi:[1,0]
	v_sub_f32_e32 v23, v24, v25
	v_add_f32_e32 v10, v10, v11
	v_xor_b32_e32 v14, 0x80000000, v10
	v_pk_mul_f32 v[10:11], v[12:13], v[16:17]
	s_nop 0
	v_sub_f32_e32 v15, v10, v11
	v_pk_mul_f32 v[10:11], v[12:13], v[16:17] op_sel:[0,1] op_sel_hi:[1,0]
	s_nop 0
	v_add_f32_e32 v10, v10, v11
	v_xor_b32_e32 v12, 0x80000000, v10
	s_waitcnt lgkmcnt(0)
; __device__ __forceinline__ unsigned cvt_pk_bf16(float lo, float hi) { unsigned r; asm volatile("v_cvt_pk_bf16_f32 %0, %1, %2" : "=v"(r) : "v"(lo), "v"(hi)); return r; }
; __device__ __forceinline__ void ssm_precompute(const Args& a, int g, LAS unsigned char* lds, int tid) {
;     ...
;         for (int ci = 0; ci < 8; ++ci) { const int n0 = 32 * (tid & 1) + 4 * ci; float v[8];
; #pragma unroll
;             for (int e = 0; e < 4; ++e) { const f32x2v c = Cc[p * 64 + n0 + e], l = P[(j + 1) * 64 + n0 + e]; v[2 * e] = c.x * l.x - c.y * l.y; v[2 * e + 1] = -(c.x * l.y + c.y * l.x); }
;             v4u o; o.x = cvt_pk_bf16(v[0], v[1]); o.y = cvt_pk_bf16(v[2], v[3]); o.z = cvt_pk_bf16(v[4], v[5]); o.w = cvt_pk_bf16(v[6], v[7]);
;             *(v4u*)(TC + (size_t)row * A2LD + 256 + 2 * n0) = o; }
	v_pk_mul_f32 v[10:11], v[6:7], v[18:19]
	v_pk_mul_f32 v[6:7], v[6:7], v[18:19] op_sel:[0,1] op_sel_hi:[1,0]
	v_sub_f32_e32 v10, v10, v11
	v_add_f32_e32 v6, v6, v7
	v_xor_b32_e32 v11, 0x80000000, v6
	v_pk_mul_f32 v[6:7], v[8:9], v[20:21]
	v_or_b32_e32 v18, 48, v4
	v_sub_f32_e32 v13, v6, v7
	v_pk_mul_f32 v[6:7], v[8:9], v[20:21] op_sel:[0,1] op_sel_hi:[1,0]
	v_mov_b32_e32 v19, v5
	v_add_f32_e32 v6, v6, v7
	v_xor_b32_e32 v9, 0x80000000, v6
	v_cvt_pk_bf16_f32 v6, v23, v14
	v_cvt_pk_bf16_f32 v7, v15, v12
	v_cvt_pk_bf16_f32 v8, v10, v11
	v_cvt_pk_bf16_f32 v9, v13, v9
	ds_read_b128 v[10:13], v26 offset:17024
	ds_read_b128 v[14:17], v27 offset:640
	v_lshl_add_u64 v[18:19], v[2:3], 0, v[18:19]
	global_store_dwordx4 v[18:19], v[6:9], off offset:512 sc1
	ds_read_b128 v[6:9], v26 offset:17040
	ds_read_b128 v[18:21], v27 offset:656
	s_waitcnt lgkmcnt(2)
	v_pk_mul_f32 v[24:25], v[10:11], v[14:15]
	v_pk_mul_f32 v[10:11], v[10:11], v[14:15] op_sel:[0,1] op_sel_hi:[1,0]
	v_sub_f32_e32 v23, v24, v25
	v_add_f32_e32 v10, v10, v11
	v_xor_b32_e32 v14, 0x80000000, v10
	v_pk_mul_f32 v[10:11], v[12:13], v[16:17]
	s_nop 0
	v_sub_f32_e32 v15, v10, v11
	v_pk_mul_f32 v[10:11], v[12:13], v[16:17] op_sel:[0,1] op_sel_hi:[1,0]
	s_nop 0
	v_add_f32_e32 v10, v10, v11
	v_xor_b32_e32 v12, 0x80000000, v10
	s_waitcnt lgkmcnt(0)
	v_pk_mul_f32 v[10:11], v[6:7], v[18:19]
	v_pk_mul_f32 v[6:7], v[6:7], v[18:19] op_sel:[0,1] op_sel_hi:[1,0]
	v_sub_f32_e32 v10, v10, v11
	v_add_f32_e32 v6, v6, v7
	v_xor_b32_e32 v11, 0x80000000, v6
	v_pk_mul_f32 v[6:7], v[8:9], v[20:21]
	v_or_b32_e32 v18, 64, v4
	v_sub_f32_e32 v13, v6, v7
	v_pk_mul_f32 v[6:7], v[8:9], v[20:21] op_sel:[0,1] op_sel_hi:[1,0]
	v_mov_b32_e32 v19, v5
	v_add_f32_e32 v6, v6, v7
	v_xor_b32_e32 v9, 0x80000000, v6
	v_cvt_pk_bf16_f32 v6, v23, v14
	v_cvt_pk_bf16_f32 v7, v15, v12
	v_cvt_pk_bf16_f32 v8, v10, v11
	v_cvt_pk_bf16_f32 v9, v13, v9
	ds_read_b128 v[10:13], v26 offset:17056
	ds_read_b128 v[14:17], v27 offset:672
	v_lshl_add_u64 v[18:19], v[2:3], 0, v[18:19]
	global_store_dwordx4 v[18:19], v[6:9], off offset:512 sc1
	ds_read_b128 v[6:9], v26 offset:17072
	ds_read_b128 v[18:21], v27 offset:688
	s_waitcnt lgkmcnt(2)
	v_pk_mul_f32 v[24:25], v[10:11], v[14:15]
	v_pk_mul_f32 v[10:11], v[10:11], v[14:15] op_sel:[0,1] op_sel_hi:[1,0]
	v_sub_f32_e32 v23, v24, v25
	v_add_f32_e32 v10, v10, v11
	v_xor_b32_e32 v14, 0x80000000, v10
	v_pk_mul_f32 v[10:11], v[12:13], v[16:17]
	s_nop 0
	v_sub_f32_e32 v15, v10, v11
	v_pk_mul_f32 v[10:11], v[12:13], v[16:17] op_sel:[0,1] op_sel_hi:[1,0]
	s_nop 0
	v_add_f32_e32 v10, v10, v11
	v_xor_b32_e32 v12, 0x80000000, v10
	s_waitcnt lgkmcnt(0)
	v_pk_mul_f32 v[10:11], v[6:7], v[18:19]
	v_pk_mul_f32 v[6:7], v[6:7], v[18:19] op_sel:[0,1] op_sel_hi:[1,0]
	v_sub_f32_e32 v10, v10, v11
	v_add_f32_e32 v6, v6, v7
	v_xor_b32_e32 v11, 0x80000000, v6
	v_pk_mul_f32 v[6:7], v[8:9], v[20:21]
	v_or_b32_e32 v18, 0x50, v4
	v_sub_f32_e32 v13, v6, v7
	v_pk_mul_f32 v[6:7], v[8:9], v[20:21] op_sel:[0,1] op_sel_hi:[1,0]
	v_mov_b32_e32 v19, v5
	v_add_f32_e32 v6, v6, v7
	v_xor_b32_e32 v9, 0x80000000, v6
	v_cvt_pk_bf16_f32 v6, v23, v14
	v_cvt_pk_bf16_f32 v7, v15, v12
	v_cvt_pk_bf16_f32 v8, v10, v11
	v_cvt_pk_bf16_f32 v9, v13, v9
	ds_read_b128 v[10:13], v26 offset:17088
	ds_read_b128 v[14:17], v27 offset:704
	v_lshl_add_u64 v[18:19], v[2:3], 0, v[18:19]
	global_store_dwordx4 v[18:19], v[6:9], off offset:512 sc1
	ds_read_b128 v[6:9], v26 offset:17104
	ds_read_b128 v[18:21], v27 offset:720
	s_waitcnt lgkmcnt(2)
	v_pk_mul_f32 v[24:25], v[10:11], v[14:15]
	v_pk_mul_f32 v[10:11], v[10:11], v[14:15] op_sel:[0,1] op_sel_hi:[1,0]
	v_sub_f32_e32 v23, v24, v25
	v_add_f32_e32 v10, v10, v11
	v_xor_b32_e32 v14, 0x80000000, v10
	v_pk_mul_f32 v[10:11], v[12:13], v[16:17]
	s_nop 0
	v_sub_f32_e32 v15, v10, v11
	v_pk_mul_f32 v[10:11], v[12:13], v[16:17] op_sel:[0,1] op_sel_hi:[1,0]
	s_nop 0
	v_add_f32_e32 v10, v10, v11
	v_xor_b32_e32 v12, 0x80000000, v10
	s_waitcnt lgkmcnt(0)
	v_pk_mul_f32 v[10:11], v[6:7], v[18:19]
	v_pk_mul_f32 v[6:7], v[6:7], v[18:19] op_sel:[0,1] op_sel_hi:[1,0]
	v_sub_f32_e32 v10, v10, v11
	v_add_f32_e32 v6, v6, v7
	v_xor_b32_e32 v11, 0x80000000, v6
	v_pk_mul_f32 v[6:7], v[8:9], v[20:21]
	v_or_b32_e32 v18, 0x60, v4
	v_sub_f32_e32 v13, v6, v7
	v_pk_mul_f32 v[6:7], v[8:9], v[20:21] op_sel:[0,1] op_sel_hi:[1,0]
	v_mov_b32_e32 v19, v5
	v_add_f32_e32 v6, v6, v7
	v_xor_b32_e32 v9, 0x80000000, v6
	v_cvt_pk_bf16_f32 v6, v23, v14
	v_cvt_pk_bf16_f32 v7, v15, v12
	v_cvt_pk_bf16_f32 v8, v10, v11
	v_cvt_pk_bf16_f32 v9, v13, v9
	ds_read_b128 v[10:13], v26 offset:17120
	ds_read_b128 v[14:17], v27 offset:736
	v_lshl_add_u64 v[18:19], v[2:3], 0, v[18:19]
	global_store_dwordx4 v[18:19], v[6:9], off offset:512 sc1
	ds_read_b128 v[6:9], v26 offset:17136
	ds_read_b128 v[18:21], v27 offset:752
	v_or_b32_e32 v4, 0x70, v4
	s_waitcnt lgkmcnt(2)
	v_pk_mul_f32 v[24:25], v[10:11], v[14:15]
	v_pk_mul_f32 v[10:11], v[10:11], v[14:15] op_sel:[0,1] op_sel_hi:[1,0]
	v_lshl_add_u64 v[2:3], v[2:3], 0, v[4:5]
	v_add_f32_e32 v10, v10, v11
	v_xor_b32_e32 v14, 0x80000000, v10
	v_pk_mul_f32 v[10:11], v[12:13], v[16:17]
	v_sub_f32_e32 v23, v24, v25
	v_sub_f32_e32 v15, v10, v11
	v_pk_mul_f32 v[10:11], v[12:13], v[16:17] op_sel:[0,1] op_sel_hi:[1,0]
	s_nop 0
	v_add_f32_e32 v10, v10, v11
	v_xor_b32_e32 v12, 0x80000000, v10
	s_waitcnt lgkmcnt(0)
; __device__ __forceinline__ unsigned cvt_pk_bf16(float lo, float hi) { unsigned r; asm volatile("v_cvt_pk_bf16_f32 %0, %1, %2" : "=v"(r) : "v"(lo), "v"(hi)); return r; }
; __device__ __forceinline__ void ssm_precompute(const Args& a, int g, LAS unsigned char* lds, int tid) {
;     ...
;         for (int ci = 0; ci < 8; ++ci) { const int n0 = 32 * (tid & 1) + 4 * ci; float v[8];
; #pragma unroll
;             for (int e = 0; e < 4; ++e) { const f32x2v c = Cc[p * 64 + n0 + e], l = P[(j + 1) * 64 + n0 + e]; v[2 * e] = c.x * l.x - c.y * l.y; v[2 * e + 1] = -(c.x * l.y + c.y * l.x); }
;             v4u o; o.x = cvt_pk_bf16(v[0], v[1]); o.y = cvt_pk_bf16(v[2], v[3]); o.z = cvt_pk_bf16(v[4], v[5]); o.w = cvt_pk_bf16(v[6], v[7]);
;             *(v4u*)(TC + (size_t)row * A2LD + 256 + 2 * n0) = o; }
;     }
;     {
;         const int row = tid >> 2, n = row >> 1, ri = row & 1;
;         for (int ci = 0; ci < 8; ++ci) { const int col0 = 64 * (tid & 3) + 8 * ci, i = col0 >> 4, q0 = col0 & 15; float v[8];
; #pragma unroll
;             for (int e = 0; e < 8; ++e) { const f32x2v l = P[(15 - i) * 64 + n], b = Bb[n * 16 + q0 + e]; v[e] = ri ? (l.x * b.y + l.y * b.x) : (l.x * b.x - l.y * b.y); }
;             v4u o; o.x = cvt_pk_bf16(v[0], v[1]); o.y = cvt_pk_bf16(v[2], v[3]); o.z = cvt_pk_bf16(v[4], v[5]); o.w = cvt_pk_bf16(v[6], v[7]);
;             *(v4u*)(BZ + (size_t)row * 256 + col0) = o;
;             *(v4u*)(BZ + (size_t)(128 + row) * 256 + col0) = (v4u){0u, 0u, 0u, 0u}; }
	v_pk_mul_f32 v[10:11], v[6:7], v[18:19]
	v_pk_mul_f32 v[6:7], v[6:7], v[18:19] op_sel:[0,1] op_sel_hi:[1,0]
	v_sub_f32_e32 v10, v10, v11
	v_add_f32_e32 v6, v6, v7
	v_xor_b32_e32 v11, 0x80000000, v6
	v_pk_mul_f32 v[6:7], v[8:9], v[20:21]
	s_nop 0
	v_sub_f32_e32 v13, v6, v7
	v_pk_mul_f32 v[6:7], v[8:9], v[20:21] op_sel:[0,1] op_sel_hi:[1,0]
	s_nop 0
	v_add_f32_e32 v6, v6, v7
	v_xor_b32_e32 v9, 0x80000000, v6
	v_cvt_pk_bf16_f32 v6, v23, v14
	v_cvt_pk_bf16_f32 v7, v15, v12
	v_cvt_pk_bf16_f32 v8, v10, v11
	v_cvt_pk_bf16_f32 v9, v13, v9
	global_store_dwordx4 v[2:3], v[6:9], off offset:512 sc1
	v_lshlrev_b32_e32 v3, 6, v22
	v_and_b32_e32 v4, 0xc0, v3
	v_and_b32_e32 v3, -8, v22
	v_add_u32_e32 v23, 0, v3
	v_lshlrev_b32_e32 v3, 4, v22
	v_lshlrev_b32_e32 v33, 5, v4
	v_and_b32_e32 v3, 0xffffff80, v3
	v_xad_u32 v7, v33, s3, v23
	v_add_u32_e32 v6, 0, v3
	ds_read_b64 v[20:21], v7 offset:1536
	ds_read_b128 v[8:11], v6 offset:8704
	ds_read_b128 v[12:15], v6 offset:8720
	ds_read_b128 v[16:19], v6 offset:8736
	ds_read_b128 v[24:27], v6 offset:8752
	v_ashrrev_i32_e32 v2, 2, v22
	v_ashrrev_i32_e32 v3, 31, v2
	v_lshlrev_b64 v[2:3], 9, v[2:3]
	s_waitcnt lgkmcnt(3)
	v_pk_mul_f32 v[28:29], v[20:21], v[8:9] op_sel:[0,1] op_sel_hi:[1,0]
	v_pk_mul_f32 v[8:9], v[20:21], v[8:9]
	v_add_f32_e32 v28, v28, v29
	v_sub_f32_e32 v8, v8, v9
	v_cndmask_b32_e32 v28, v28, v8, vcc
	v_pk_mul_f32 v[8:9], v[20:21], v[10:11] op_sel:[0,1] op_sel_hi:[1,0]
	v_lshl_add_u64 v[2:3], s[4:5], 0, v[2:3]
	v_add_f32_e32 v29, v8, v9
	v_pk_mul_f32 v[8:9], v[20:21], v[10:11]
	v_lshlrev_b32_e32 v4, 1, v4
	v_sub_f32_e32 v8, v8, v9
	v_cndmask_b32_e32 v10, v29, v8, vcc
	s_waitcnt lgkmcnt(2)
	v_pk_mul_f32 v[8:9], v[20:21], v[12:13] op_sel:[0,1] op_sel_hi:[1,0]
	s_mov_b32 s3, 0x6400000
	v_add_f32_e32 v11, v8, v9
	v_pk_mul_f32 v[8:9], v[20:21], v[12:13]
	s_mov_b64 s[4:5], 0x6400000
	v_sub_f32_e32 v8, v8, v9
	v_cndmask_b32_e32 v11, v11, v8, vcc
	v_pk_mul_f32 v[8:9], v[20:21], v[14:15] op_sel:[0,1] op_sel_hi:[1,0]
	s_nop 0
	v_add_f32_e32 v12, v8, v9
	v_pk_mul_f32 v[8:9], v[20:21], v[14:15]
	s_nop 0
	v_sub_f32_e32 v8, v8, v9
	v_cndmask_b32_e32 v12, v12, v8, vcc
	s_waitcnt lgkmcnt(1)
	v_pk_mul_f32 v[8:9], v[20:21], v[16:17] op_sel:[0,1] op_sel_hi:[1,0]
	s_nop 0
	v_add_f32_e32 v13, v8, v9
	v_pk_mul_f32 v[8:9], v[20:21], v[16:17]
	s_nop 0
	v_sub_f32_e32 v8, v8, v9
	v_cndmask_b32_e32 v13, v13, v8, vcc
	v_pk_mul_f32 v[8:9], v[20:21], v[18:19] op_sel:[0,1] op_sel_hi:[1,0]
	s_nop 0
	v_add_f32_e32 v14, v8, v9
	v_pk_mul_f32 v[8:9], v[20:21], v[18:19]
	s_nop 0
	v_sub_f32_e32 v8, v8, v9
	v_cndmask_b32_e32 v14, v14, v8, vcc
	s_waitcnt lgkmcnt(0)
	v_pk_mul_f32 v[8:9], v[20:21], v[24:25] op_sel:[0,1] op_sel_hi:[1,0]
	s_nop 0
	v_add_f32_e32 v15, v8, v9
	v_pk_mul_f32 v[8:9], v[20:21], v[24:25]
	s_nop 0
	v_sub_f32_e32 v8, v8, v9
	v_cndmask_b32_e32 v15, v15, v8, vcc
	v_pk_mul_f32 v[8:9], v[20:21], v[26:27] op_sel:[0,1] op_sel_hi:[1,0]
	s_nop 0
	v_add_f32_e32 v16, v8, v9
	v_pk_mul_f32 v[8:9], v[20:21], v[26:27]
	s_nop 0
	v_sub_f32_e32 v8, v8, v9
	v_cndmask_b32_e32 v16, v16, v8, vcc
	v_cvt_pk_bf16_f32 v8, v28, v10
	v_cvt_pk_bf16_f32 v9, v11, v12
	v_cvt_pk_bf16_f32 v10, v13, v14
	v_lshl_add_u64 v[12:13], v[2:3], 0, v[4:5]
	v_add_co_u32_e64 v4, s[6:7], s3, v12
	s_mov_b32 s3, 0x6410000
	s_nop 0
	v_addc_co_u32_e64 v5, s[6:7], 0, v13, s[6:7]
	v_cvt_pk_bf16_f32 v11, v15, v16
	v_lshl_add_u64 v[2:3], v[12:13], 0, s[4:5]
	global_store_dwordx4 v[4:5], v[8:11], off sc1
	s_mov_b64 s[4:5], 0x6410000
	v_add_co_u32_e64 v16, s[6:7], s3, v12
	v_lshl_add_u64 v[4:5], v[12:13], 0, s[4:5]
	s_nop 0
	v_addc_co_u32_e64 v17, s[6:7], 0, v13, s[6:7]
	ds_read_b64 v[20:21], v7 offset:1536
	ds_read_b128 v[12:15], v6 offset:8768
	v_mov_b64_e32 v[8:9], s[8:9]
	v_mov_b64_e32 v[10:11], s[10:11]
	global_store_dwordx4 v[16:17], v[8:11], off sc1
	ds_read_b128 v[16:19], v6 offset:8784
	ds_read_b128 v[24:27], v6 offset:8800
	ds_read_b128 v[28:31], v6 offset:8816
	s_waitcnt lgkmcnt(3)
	v_pk_mul_f32 v[34:35], v[20:21], v[12:13] op_sel:[0,1] op_sel_hi:[1,0]
	v_pk_mul_f32 v[12:13], v[20:21], v[12:13]
	v_add_f32_e32 v34, v34, v35
	v_sub_f32_e32 v12, v12, v13
	v_cndmask_b32_e32 v34, v34, v12, vcc
	v_pk_mul_f32 v[12:13], v[20:21], v[14:15] op_sel:[0,1] op_sel_hi:[1,0]
	s_movk_i32 s3, 0x1a00
	v_add_f32_e32 v35, v12, v13
	v_pk_mul_f32 v[12:13], v[20:21], v[14:15]
	s_movk_i32 s4, 0x1c00
	v_sub_f32_e32 v12, v12, v13
	v_cndmask_b32_e32 v14, v35, v12, vcc
	s_waitcnt lgkmcnt(2)
	v_pk_mul_f32 v[12:13], v[20:21], v[16:17] op_sel:[0,1] op_sel_hi:[1,0]
	s_nop 0
	v_add_f32_e32 v15, v12, v13
	v_pk_mul_f32 v[12:13], v[20:21], v[16:17]
	s_nop 0
	v_sub_f32_e32 v12, v12, v13
	v_cndmask_b32_e32 v15, v15, v12, vcc
	v_pk_mul_f32 v[12:13], v[20:21], v[18:19] op_sel:[0,1] op_sel_hi:[1,0]
	s_nop 0
	v_add_f32_e32 v16, v12, v13
	v_pk_mul_f32 v[12:13], v[20:21], v[18:19]
	s_nop 0
	v_sub_f32_e32 v12, v12, v13
	v_cndmask_b32_e32 v16, v16, v12, vcc
	s_waitcnt lgkmcnt(1)
	v_pk_mul_f32 v[12:13], v[20:21], v[24:25] op_sel:[0,1] op_sel_hi:[1,0]
	s_nop 0
	v_add_f32_e32 v17, v12, v13
	v_pk_mul_f32 v[12:13], v[20:21], v[24:25]
	s_nop 0
	v_sub_f32_e32 v12, v12, v13
	v_cndmask_b32_e32 v17, v17, v12, vcc
	v_pk_mul_f32 v[12:13], v[20:21], v[26:27] op_sel:[0,1] op_sel_hi:[1,0]
	s_nop 0
	v_add_f32_e32 v18, v12, v13
	v_pk_mul_f32 v[12:13], v[20:21], v[26:27]
	s_nop 0
	v_sub_f32_e32 v12, v12, v13
	v_cndmask_b32_e32 v18, v18, v12, vcc
	s_waitcnt lgkmcnt(0)
; __device__ __forceinline__ unsigned cvt_pk_bf16(float lo, float hi) { unsigned r; asm volatile("v_cvt_pk_bf16_f32 %0, %1, %2" : "=v"(r) : "v"(lo), "v"(hi)); return r; }
; __device__ __forceinline__ void ssm_precompute(const Args& a, int g, LAS unsigned char* lds, int tid) {
;     ...
;         const int row = tid >> 2, n = row >> 1, ri = row & 1;
;         for (int ci = 0; ci < 8; ++ci) { const int col0 = 64 * (tid & 3) + 8 * ci, i = col0 >> 4, q0 = col0 & 15; float v[8];
; #pragma unroll
;             for (int e = 0; e < 8; ++e) { const f32x2v l = P[(15 - i) * 64 + n], b = Bb[n * 16 + q0 + e]; v[e] = ri ? (l.x * b.y + l.y * b.x) : (l.x * b.x - l.y * b.y); }
;             v4u o; o.x = cvt_pk_bf16(v[0], v[1]); o.y = cvt_pk_bf16(v[2], v[3]); o.z = cvt_pk_bf16(v[4], v[5]); o.w = cvt_pk_bf16(v[6], v[7]);
;             *(v4u*)(BZ + (size_t)row * 256 + col0) = o;
;             *(v4u*)(BZ + (size_t)(128 + row) * 256 + col0) = (v4u){0u, 0u, 0u, 0u}; }
	v_pk_mul_f32 v[12:13], v[20:21], v[28:29] op_sel:[0,1] op_sel_hi:[1,0]
	s_nop 0
	v_add_f32_e32 v19, v12, v13
	v_pk_mul_f32 v[12:13], v[20:21], v[28:29]
	s_nop 0
	v_sub_f32_e32 v12, v12, v13
	v_cndmask_b32_e32 v19, v19, v12, vcc
	v_pk_mul_f32 v[12:13], v[20:21], v[30:31] op_sel:[0,1] op_sel_hi:[1,0]
	s_nop 0
	v_add_f32_e32 v24, v12, v13
	v_pk_mul_f32 v[12:13], v[20:21], v[30:31]
	s_nop 0
	v_sub_f32_e32 v12, v12, v13
	v_cndmask_b32_e32 v20, v24, v12, vcc
	v_cvt_pk_bf16_f32 v12, v34, v14
	v_cvt_pk_bf16_f32 v13, v15, v16
	v_cvt_pk_bf16_f32 v14, v17, v18
	v_cvt_pk_bf16_f32 v15, v19, v20
	global_store_dwordx4 v[2:3], v[12:15], off offset:16 sc1
	global_store_dwordx4 v[4:5], v[8:11], off offset:16 sc1
	s_nop 0
	v_or_b32_e32 v12, 0x200, v33
	v_xad_u32 v12, v12, s3, v23
	ds_read_b64 v[20:21], v12 offset:1024
	ds_read_b128 v[12:15], v6 offset:8704
	ds_read_b128 v[16:19], v6 offset:8720
	ds_read_b128 v[24:27], v6 offset:8736
	ds_read_b128 v[28:31], v6 offset:8752
	s_movk_i32 s3, 0x200
	s_waitcnt lgkmcnt(3)
	v_pk_mul_f32 v[34:35], v[20:21], v[12:13] op_sel:[0,1] op_sel_hi:[1,0]
	v_pk_mul_f32 v[12:13], v[20:21], v[12:13]
	v_add_f32_e32 v34, v34, v35
	v_sub_f32_e32 v12, v12, v13
	v_cndmask_b32_e32 v34, v34, v12, vcc
	v_pk_mul_f32 v[12:13], v[20:21], v[14:15] op_sel:[0,1] op_sel_hi:[1,0]
	s_nop 0
	v_add_f32_e32 v35, v12, v13
	v_pk_mul_f32 v[12:13], v[20:21], v[14:15]
	s_nop 0
	v_sub_f32_e32 v12, v12, v13
	v_cndmask_b32_e32 v14, v35, v12, vcc
	s_waitcnt lgkmcnt(2)
	v_pk_mul_f32 v[12:13], v[20:21], v[16:17] op_sel:[0,1] op_sel_hi:[1,0]
	s_nop 0
	v_add_f32_e32 v15, v12, v13
	v_pk_mul_f32 v[12:13], v[20:21], v[16:17]
	s_nop 0
	v_sub_f32_e32 v12, v12, v13
	v_cndmask_b32_e32 v15, v15, v12, vcc
	v_pk_mul_f32 v[12:13], v[20:21], v[18:19] op_sel:[0,1] op_sel_hi:[1,0]
	s_nop 0
	v_add_f32_e32 v16, v12, v13
	v_pk_mul_f32 v[12:13], v[20:21], v[18:19]
	s_nop 0
	v_sub_f32_e32 v12, v12, v13
	v_cndmask_b32_e32 v16, v16, v12, vcc
	s_waitcnt lgkmcnt(1)
	v_pk_mul_f32 v[12:13], v[20:21], v[24:25] op_sel:[0,1] op_sel_hi:[1,0]
	s_nop 0
	v_add_f32_e32 v17, v12, v13
	v_pk_mul_f32 v[12:13], v[20:21], v[24:25]
	s_nop 0
	v_sub_f32_e32 v12, v12, v13
	v_cndmask_b32_e32 v17, v17, v12, vcc
	v_pk_mul_f32 v[12:13], v[20:21], v[26:27] op_sel:[0,1] op_sel_hi:[1,0]
	s_nop 0
	v_add_f32_e32 v18, v12, v13
	v_pk_mul_f32 v[12:13], v[20:21], v[26:27]
	s_nop 0
	v_sub_f32_e32 v12, v12, v13
	v_cndmask_b32_e32 v18, v18, v12, vcc
	s_waitcnt lgkmcnt(0)
	v_pk_mul_f32 v[12:13], v[20:21], v[28:29] op_sel:[0,1] op_sel_hi:[1,0]
	s_nop 0
	v_add_f32_e32 v19, v12, v13
	v_pk_mul_f32 v[12:13], v[20:21], v[28:29]
	s_nop 0
	v_sub_f32_e32 v12, v12, v13
	v_cndmask_b32_e32 v19, v19, v12, vcc
	v_pk_mul_f32 v[12:13], v[20:21], v[30:31] op_sel:[0,1] op_sel_hi:[1,0]
	s_nop 0
	v_add_f32_e32 v24, v12, v13
	v_pk_mul_f32 v[12:13], v[20:21], v[30:31]
	s_nop 0
	v_sub_f32_e32 v12, v12, v13
	v_cndmask_b32_e32 v20, v24, v12, vcc
	v_cvt_pk_bf16_f32 v12, v34, v14
	v_cvt_pk_bf16_f32 v13, v15, v16
	v_cvt_pk_bf16_f32 v14, v17, v18
	v_cvt_pk_bf16_f32 v15, v19, v20
	global_store_dwordx4 v[2:3], v[12:15], off offset:32 sc1
	ds_read_b64 v[20:21], v7 offset:1024
	ds_read_b128 v[12:15], v6 offset:8768
	global_store_dwordx4 v[4:5], v[8:11], off offset:32 sc1
	ds_read_b128 v[16:19], v6 offset:8784
	ds_read_b128 v[24:27], v6 offset:8800
	ds_read_b128 v[28:31], v6 offset:8816
	s_waitcnt lgkmcnt(3)
	v_pk_mul_f32 v[34:35], v[20:21], v[12:13] op_sel:[0,1] op_sel_hi:[1,0]
	v_pk_mul_f32 v[12:13], v[20:21], v[12:13]
	v_add_f32_e32 v34, v34, v35
	v_sub_f32_e32 v12, v12, v13
	v_cndmask_b32_e32 v34, v34, v12, vcc
	v_pk_mul_f32 v[12:13], v[20:21], v[14:15] op_sel:[0,1] op_sel_hi:[1,0]
	s_nop 0
	v_add_f32_e32 v35, v12, v13
	v_pk_mul_f32 v[12:13], v[20:21], v[14:15]
	s_nop 0
	v_sub_f32_e32 v12, v12, v13
	v_cndmask_b32_e32 v14, v35, v12, vcc
	s_waitcnt lgkmcnt(2)
	v_pk_mul_f32 v[12:13], v[20:21], v[16:17] op_sel:[0,1] op_sel_hi:[1,0]
	s_nop 0
	v_add_f32_e32 v15, v12, v13
	v_pk_mul_f32 v[12:13], v[20:21], v[16:17]
	s_nop 0
	v_sub_f32_e32 v12, v12, v13
	v_cndmask_b32_e32 v15, v15, v12, vcc
	v_pk_mul_f32 v[12:13], v[20:21], v[18:19] op_sel:[0,1] op_sel_hi:[1,0]
	s_nop 0
	v_add_f32_e32 v16, v12, v13
	v_pk_mul_f32 v[12:13], v[20:21], v[18:19]
	s_nop 0
	v_sub_f32_e32 v12, v12, v13
	v_cndmask_b32_e32 v16, v16, v12, vcc
	s_waitcnt lgkmcnt(1)
	v_pk_mul_f32 v[12:13], v[20:21], v[24:25] op_sel:[0,1] op_sel_hi:[1,0]
	s_nop 0
	v_add_f32_e32 v17, v12, v13
	v_pk_mul_f32 v[12:13], v[20:21], v[24:25]
	s_nop 0
	v_sub_f32_e32 v12, v12, v13
	v_cndmask_b32_e32 v17, v17, v12, vcc
	v_pk_mul_f32 v[12:13], v[20:21], v[26:27] op_sel:[0,1] op_sel_hi:[1,0]
	s_nop 0
	v_add_f32_e32 v18, v12, v13
	v_pk_mul_f32 v[12:13], v[20:21], v[26:27]
	s_nop 0
	v_sub_f32_e32 v12, v12, v13
	v_cndmask_b32_e32 v18, v18, v12, vcc
	s_waitcnt lgkmcnt(0)
	v_pk_mul_f32 v[12:13], v[20:21], v[28:29] op_sel:[0,1] op_sel_hi:[1,0]
	s_nop 0
	v_add_f32_e32 v19, v12, v13
	v_pk_mul_f32 v[12:13], v[20:21], v[28:29]
	s_nop 0
	v_sub_f32_e32 v12, v12, v13
	v_cndmask_b32_e32 v19, v19, v12, vcc
	v_pk_mul_f32 v[12:13], v[20:21], v[30:31] op_sel:[0,1] op_sel_hi:[1,0]
	s_nop 0
	v_add_f32_e32 v24, v12, v13
	v_pk_mul_f32 v[12:13], v[20:21], v[30:31]
	s_nop 0
	v_sub_f32_e32 v12, v12, v13
	v_cndmask_b32_e32 v20, v24, v12, vcc
	v_cvt_pk_bf16_f32 v12, v34, v14
	v_cvt_pk_bf16_f32 v13, v15, v16
	v_cvt_pk_bf16_f32 v14, v17, v18
	v_cvt_pk_bf16_f32 v15, v19, v20
	global_store_dwordx4 v[2:3], v[12:15], off offset:48 sc1
	global_store_dwordx4 v[4:5], v[8:11], off offset:48 sc1
	s_nop 0
	v_or_b32_e32 v12, 0x400, v33
	v_xad_u32 v12, v12, s4, v23
	ds_read_b64 v[20:21], v12 offset:512
	ds_read_b128 v[12:15], v6 offset:8704
	ds_read_b128 v[16:19], v6 offset:8720
	ds_read_b128 v[24:27], v6 offset:8736
	ds_read_b128 v[28:31], v6 offset:8752
	s_movk_i32 s4, 0x1e00
	s_waitcnt lgkmcnt(3)
; __device__ __forceinline__ unsigned cvt_pk_bf16(float lo, float hi) { unsigned r; asm volatile("v_cvt_pk_bf16_f32 %0, %1, %2" : "=v"(r) : "v"(lo), "v"(hi)); return r; }
; __device__ __forceinline__ void ssm_precompute(const Args& a, int g, LAS unsigned char* lds, int tid) {
;     ...
;         const int row = tid >> 2, n = row >> 1, ri = row & 1;
;         for (int ci = 0; ci < 8; ++ci) { const int col0 = 64 * (tid & 3) + 8 * ci, i = col0 >> 4, q0 = col0 & 15; float v[8];
; #pragma unroll
;             for (int e = 0; e < 8; ++e) { const f32x2v l = P[(15 - i) * 64 + n], b = Bb[n * 16 + q0 + e]; v[e] = ri ? (l.x * b.y + l.y * b.x) : (l.x * b.x - l.y * b.y); }
;             v4u o; o.x = cvt_pk_bf16(v[0], v[1]); o.y = cvt_pk_bf16(v[2], v[3]); o.z = cvt_pk_bf16(v[4], v[5]); o.w = cvt_pk_bf16(v[6], v[7]);
;             *(v4u*)(BZ + (size_t)row * 256 + col0) = o;
;             *(v4u*)(BZ + (size_t)(128 + row) * 256 + col0) = (v4u){0u, 0u, 0u, 0u}; }
	v_pk_mul_f32 v[34:35], v[20:21], v[12:13] op_sel:[0,1] op_sel_hi:[1,0]
	v_pk_mul_f32 v[12:13], v[20:21], v[12:13]
	v_add_f32_e32 v34, v34, v35
	v_sub_f32_e32 v12, v12, v13
	v_cndmask_b32_e32 v34, v34, v12, vcc
	v_pk_mul_f32 v[12:13], v[20:21], v[14:15] op_sel:[0,1] op_sel_hi:[1,0]
	s_nop 0
	v_add_f32_e32 v35, v12, v13
	v_pk_mul_f32 v[12:13], v[20:21], v[14:15]
	s_nop 0
	v_sub_f32_e32 v12, v12, v13
	v_cndmask_b32_e32 v14, v35, v12, vcc
	s_waitcnt lgkmcnt(2)
	v_pk_mul_f32 v[12:13], v[20:21], v[16:17] op_sel:[0,1] op_sel_hi:[1,0]
	s_nop 0
	v_add_f32_e32 v15, v12, v13
	v_pk_mul_f32 v[12:13], v[20:21], v[16:17]
	s_nop 0
	v_sub_f32_e32 v12, v12, v13
	v_cndmask_b32_e32 v15, v15, v12, vcc
	v_pk_mul_f32 v[12:13], v[20:21], v[18:19] op_sel:[0,1] op_sel_hi:[1,0]
	s_nop 0
	v_add_f32_e32 v16, v12, v13
	v_pk_mul_f32 v[12:13], v[20:21], v[18:19]
	s_nop 0
	v_sub_f32_e32 v12, v12, v13
	v_cndmask_b32_e32 v16, v16, v12, vcc
	s_waitcnt lgkmcnt(1)
	v_pk_mul_f32 v[12:13], v[20:21], v[24:25] op_sel:[0,1] op_sel_hi:[1,0]
	s_nop 0
	v_add_f32_e32 v17, v12, v13
	v_pk_mul_f32 v[12:13], v[20:21], v[24:25]
	s_nop 0
	v_sub_f32_e32 v12, v12, v13
	v_cndmask_b32_e32 v17, v17, v12, vcc
	v_pk_mul_f32 v[12:13], v[20:21], v[26:27] op_sel:[0,1] op_sel_hi:[1,0]
	s_nop 0
	v_add_f32_e32 v18, v12, v13
	v_pk_mul_f32 v[12:13], v[20:21], v[26:27]
	s_nop 0
	v_sub_f32_e32 v12, v12, v13
	v_cndmask_b32_e32 v18, v18, v12, vcc
	s_waitcnt lgkmcnt(0)
	v_pk_mul_f32 v[12:13], v[20:21], v[28:29] op_sel:[0,1] op_sel_hi:[1,0]
	s_nop 0
	v_add_f32_e32 v19, v12, v13
	v_pk_mul_f32 v[12:13], v[20:21], v[28:29]
	s_nop 0
	v_sub_f32_e32 v12, v12, v13
	v_cndmask_b32_e32 v19, v19, v12, vcc
	v_pk_mul_f32 v[12:13], v[20:21], v[30:31] op_sel:[0,1] op_sel_hi:[1,0]
	s_nop 0
	v_add_f32_e32 v24, v12, v13
	v_pk_mul_f32 v[12:13], v[20:21], v[30:31]
	s_nop 0
	v_sub_f32_e32 v12, v12, v13
	v_cndmask_b32_e32 v20, v24, v12, vcc
	v_cvt_pk_bf16_f32 v12, v34, v14
	v_cvt_pk_bf16_f32 v13, v15, v16
	v_cvt_pk_bf16_f32 v14, v17, v18
	v_cvt_pk_bf16_f32 v15, v19, v20
	global_store_dwordx4 v[2:3], v[12:15], off offset:64 sc1
	ds_read_b64 v[20:21], v7 offset:512
	ds_read_b128 v[12:15], v6 offset:8768
	global_store_dwordx4 v[4:5], v[8:11], off offset:64 sc1
	ds_read_b128 v[16:19], v6 offset:8784
	ds_read_b128 v[24:27], v6 offset:8800
	ds_read_b128 v[28:31], v6 offset:8816
	s_waitcnt lgkmcnt(3)
	v_pk_mul_f32 v[34:35], v[20:21], v[12:13] op_sel:[0,1] op_sel_hi:[1,0]
	v_pk_mul_f32 v[12:13], v[20:21], v[12:13]
	v_add_f32_e32 v34, v34, v35
	v_sub_f32_e32 v12, v12, v13
	v_cndmask_b32_e32 v34, v34, v12, vcc
	v_pk_mul_f32 v[12:13], v[20:21], v[14:15] op_sel:[0,1] op_sel_hi:[1,0]
	s_nop 0
	v_add_f32_e32 v35, v12, v13
	v_pk_mul_f32 v[12:13], v[20:21], v[14:15]
	s_nop 0
	v_sub_f32_e32 v12, v12, v13
	v_cndmask_b32_e32 v14, v35, v12, vcc
	s_waitcnt lgkmcnt(2)
	v_pk_mul_f32 v[12:13], v[20:21], v[16:17] op_sel:[0,1] op_sel_hi:[1,0]
	s_nop 0
	v_add_f32_e32 v15, v12, v13
	v_pk_mul_f32 v[12:13], v[20:21], v[16:17]
	s_nop 0
	v_sub_f32_e32 v12, v12, v13
	v_cndmask_b32_e32 v15, v15, v12, vcc
	v_pk_mul_f32 v[12:13], v[20:21], v[18:19] op_sel:[0,1] op_sel_hi:[1,0]
	s_nop 0
	v_add_f32_e32 v16, v12, v13
	v_pk_mul_f32 v[12:13], v[20:21], v[18:19]
	s_nop 0
	v_sub_f32_e32 v12, v12, v13
	v_cndmask_b32_e32 v16, v16, v12, vcc
	s_waitcnt lgkmcnt(1)
	v_pk_mul_f32 v[12:13], v[20:21], v[24:25] op_sel:[0,1] op_sel_hi:[1,0]
	s_nop 0
	v_add_f32_e32 v17, v12, v13
	v_pk_mul_f32 v[12:13], v[20:21], v[24:25]
	s_nop 0
	v_sub_f32_e32 v12, v12, v13
	v_cndmask_b32_e32 v17, v17, v12, vcc
	v_pk_mul_f32 v[12:13], v[20:21], v[26:27] op_sel:[0,1] op_sel_hi:[1,0]
	s_nop 0
	v_add_f32_e32 v18, v12, v13
	v_pk_mul_f32 v[12:13], v[20:21], v[26:27]
	s_nop 0
	v_sub_f32_e32 v12, v12, v13
	v_cndmask_b32_e32 v18, v18, v12, vcc
	s_waitcnt lgkmcnt(0)
	v_pk_mul_f32 v[12:13], v[20:21], v[28:29] op_sel:[0,1] op_sel_hi:[1,0]
	s_nop 0
	v_add_f32_e32 v19, v12, v13
	v_pk_mul_f32 v[12:13], v[20:21], v[28:29]
	s_nop 0
	v_sub_f32_e32 v12, v12, v13
	v_cndmask_b32_e32 v19, v19, v12, vcc
	v_pk_mul_f32 v[12:13], v[20:21], v[30:31] op_sel:[0,1] op_sel_hi:[1,0]
	s_nop 0
	v_add_f32_e32 v24, v12, v13
	v_pk_mul_f32 v[12:13], v[20:21], v[30:31]
	s_nop 0
	v_sub_f32_e32 v12, v12, v13
	v_cndmask_b32_e32 v20, v24, v12, vcc
	v_cvt_pk_bf16_f32 v12, v34, v14
	v_cvt_pk_bf16_f32 v13, v15, v16
	v_cvt_pk_bf16_f32 v14, v17, v18
	v_cvt_pk_bf16_f32 v15, v19, v20
	global_store_dwordx4 v[2:3], v[12:15], off offset:80 sc1
	s_nop 1
	v_or_b32_e32 v12, 0x600, v33
	v_xad_u32 v12, v12, s4, v23
	ds_read_b64 v[20:21], v12
	ds_read_b128 v[12:15], v6 offset:8704
	global_store_dwordx4 v[4:5], v[8:11], off offset:80 sc1
	ds_read_b128 v[16:19], v6 offset:8720
	ds_read_b128 v[24:27], v6 offset:8736
	ds_read_b128 v[28:31], v6 offset:8752
	s_waitcnt lgkmcnt(3)
; __device__ __forceinline__ unsigned cvt_pk_bf16(float lo, float hi) { unsigned r; asm volatile("v_cvt_pk_bf16_f32 %0, %1, %2" : "=v"(r) : "v"(lo), "v"(hi)); return r; }
; __device__ __forceinline__ void ssm_precompute(const Args& a, int g, LAS unsigned char* lds, int tid) {
;     ...
;         const int row = tid >> 2, n = row >> 1, ri = row & 1;
;         for (int ci = 0; ci < 8; ++ci) { const int col0 = 64 * (tid & 3) + 8 * ci, i = col0 >> 4, q0 = col0 & 15; float v[8];
; #pragma unroll
;             for (int e = 0; e < 8; ++e) { const f32x2v l = P[(15 - i) * 64 + n], b = Bb[n * 16 + q0 + e]; v[e] = ri ? (l.x * b.y + l.y * b.x) : (l.x * b.x - l.y * b.y); }
;             v4u o; o.x = cvt_pk_bf16(v[0], v[1]); o.y = cvt_pk_bf16(v[2], v[3]); o.z = cvt_pk_bf16(v[4], v[5]); o.w = cvt_pk_bf16(v[6], v[7]);
;             *(v4u*)(BZ + (size_t)row * 256 + col0) = o;
;             *(v4u*)(BZ + (size_t)(128 + row) * 256 + col0) = (v4u){0u, 0u, 0u, 0u}; }
;     }
;     if (tid < 64) { const f32x2v l = P[16 * 64 + tid]; ((float*)(a.ws + WS_LAM))[(g * 64 + tid) * 2] = l.x; ((float*)(a.ws + WS_LAM))[(g * 64 + tid) * 2 + 1] = l.y; }
	v_pk_mul_f32 v[34:35], v[20:21], v[12:13] op_sel:[0,1] op_sel_hi:[1,0]
	v_pk_mul_f32 v[12:13], v[20:21], v[12:13]
	v_add_f32_e32 v23, v34, v35
	v_sub_f32_e32 v12, v12, v13
	v_cndmask_b32_e32 v23, v23, v12, vcc
	v_pk_mul_f32 v[12:13], v[20:21], v[14:15] op_sel:[0,1] op_sel_hi:[1,0]
	s_nop 0
	v_add_f32_e32 v33, v12, v13
	v_pk_mul_f32 v[12:13], v[20:21], v[14:15]
	s_nop 0
	v_sub_f32_e32 v12, v12, v13
	v_cndmask_b32_e32 v14, v33, v12, vcc
	s_waitcnt lgkmcnt(2)
	v_pk_mul_f32 v[12:13], v[20:21], v[16:17] op_sel:[0,1] op_sel_hi:[1,0]
	s_nop 0
	v_add_f32_e32 v15, v12, v13
	v_pk_mul_f32 v[12:13], v[20:21], v[16:17]
	s_nop 0
	v_sub_f32_e32 v12, v12, v13
	v_cndmask_b32_e32 v15, v15, v12, vcc
	v_pk_mul_f32 v[12:13], v[20:21], v[18:19] op_sel:[0,1] op_sel_hi:[1,0]
	s_nop 0
	v_add_f32_e32 v16, v12, v13
	v_pk_mul_f32 v[12:13], v[20:21], v[18:19]
	s_nop 0
	v_sub_f32_e32 v12, v12, v13
	v_cndmask_b32_e32 v16, v16, v12, vcc
	s_waitcnt lgkmcnt(1)
	v_pk_mul_f32 v[12:13], v[20:21], v[24:25] op_sel:[0,1] op_sel_hi:[1,0]
	s_nop 0
	v_add_f32_e32 v17, v12, v13
	v_pk_mul_f32 v[12:13], v[20:21], v[24:25]
	s_nop 0
	v_sub_f32_e32 v12, v12, v13
	v_cndmask_b32_e32 v17, v17, v12, vcc
	v_pk_mul_f32 v[12:13], v[20:21], v[26:27] op_sel:[0,1] op_sel_hi:[1,0]
	s_nop 0
	v_add_f32_e32 v18, v12, v13
	v_pk_mul_f32 v[12:13], v[20:21], v[26:27]
	s_nop 0
	v_sub_f32_e32 v12, v12, v13
	v_cndmask_b32_e32 v18, v18, v12, vcc
	s_waitcnt lgkmcnt(0)
	v_pk_mul_f32 v[12:13], v[20:21], v[28:29] op_sel:[0,1] op_sel_hi:[1,0]
	s_nop 0
	v_add_f32_e32 v19, v12, v13
	v_pk_mul_f32 v[12:13], v[20:21], v[28:29]
	s_nop 0
	v_sub_f32_e32 v12, v12, v13
	v_cndmask_b32_e32 v19, v19, v12, vcc
	v_pk_mul_f32 v[12:13], v[20:21], v[30:31] op_sel:[0,1] op_sel_hi:[1,0]
	s_nop 0
	v_add_f32_e32 v24, v12, v13
	v_pk_mul_f32 v[12:13], v[20:21], v[30:31]
	s_nop 0
	v_sub_f32_e32 v12, v12, v13
	v_cndmask_b32_e32 v20, v24, v12, vcc
	v_cvt_pk_bf16_f32 v12, v23, v14
	v_cvt_pk_bf16_f32 v13, v15, v16
	v_cvt_pk_bf16_f32 v14, v17, v18
	v_cvt_pk_bf16_f32 v15, v19, v20
	global_store_dwordx4 v[2:3], v[12:15], off offset:96 sc1
	ds_read_b64 v[20:21], v7
	ds_read_b128 v[12:15], v6 offset:8768
	global_store_dwordx4 v[4:5], v[8:11], off offset:96 sc1
	ds_read_b128 v[16:19], v6 offset:8784
	ds_read_b128 v[24:27], v6 offset:8800
	ds_read_b128 v[28:31], v6 offset:8816
	s_waitcnt lgkmcnt(3)
	v_pk_mul_f32 v[6:7], v[20:21], v[12:13] op_sel:[0,1] op_sel_hi:[1,0]
	s_nop 0
	v_add_f32_e32 v23, v6, v7
	v_pk_mul_f32 v[6:7], v[20:21], v[12:13]
	s_nop 0
	v_sub_f32_e32 v6, v6, v7
	v_cndmask_b32_e32 v12, v23, v6, vcc
	v_pk_mul_f32 v[6:7], v[20:21], v[14:15] op_sel:[0,1] op_sel_hi:[1,0]
	s_nop 0
	v_add_f32_e32 v13, v6, v7
	v_pk_mul_f32 v[6:7], v[20:21], v[14:15]
	s_nop 0
	v_sub_f32_e32 v6, v6, v7
	v_cndmask_b32_e32 v13, v13, v6, vcc
	s_waitcnt lgkmcnt(2)
	v_pk_mul_f32 v[6:7], v[20:21], v[16:17] op_sel:[0,1] op_sel_hi:[1,0]
	v_cvt_pk_bf16_f32 v12, v12, v13
	s_nop 0
	v_add_f32_e32 v14, v6, v7
	v_pk_mul_f32 v[6:7], v[20:21], v[16:17]
	s_nop 0
	v_sub_f32_e32 v6, v6, v7
	v_cndmask_b32_e32 v14, v14, v6, vcc
	v_pk_mul_f32 v[6:7], v[20:21], v[18:19] op_sel:[0,1] op_sel_hi:[1,0]
	s_nop 0
	v_add_f32_e32 v15, v6, v7
	v_pk_mul_f32 v[6:7], v[20:21], v[18:19]
	s_nop 0
	v_sub_f32_e32 v6, v6, v7
	v_cndmask_b32_e32 v15, v15, v6, vcc
	s_waitcnt lgkmcnt(1)
	v_pk_mul_f32 v[6:7], v[20:21], v[24:25] op_sel:[0,1] op_sel_hi:[1,0]
	v_cvt_pk_bf16_f32 v13, v14, v15
	s_nop 0
	v_add_f32_e32 v16, v6, v7
	v_pk_mul_f32 v[6:7], v[20:21], v[24:25]
	s_nop 0
	v_sub_f32_e32 v6, v6, v7
	v_cndmask_b32_e32 v16, v16, v6, vcc
	v_pk_mul_f32 v[6:7], v[20:21], v[26:27] op_sel:[0,1] op_sel_hi:[1,0]
	s_nop 0
	v_add_f32_e32 v17, v6, v7
	v_pk_mul_f32 v[6:7], v[20:21], v[26:27]
	s_nop 0
	v_sub_f32_e32 v6, v6, v7
	v_cndmask_b32_e32 v17, v17, v6, vcc
	s_waitcnt lgkmcnt(0)
	v_pk_mul_f32 v[6:7], v[20:21], v[28:29] op_sel:[0,1] op_sel_hi:[1,0]
	v_cvt_pk_bf16_f32 v14, v16, v17
	s_nop 0
	v_add_f32_e32 v18, v6, v7
	v_pk_mul_f32 v[6:7], v[20:21], v[28:29]
	s_nop 0
	v_sub_f32_e32 v6, v6, v7
	v_cndmask_b32_e32 v18, v18, v6, vcc
	v_pk_mul_f32 v[6:7], v[20:21], v[30:31] op_sel:[0,1] op_sel_hi:[1,0]
	s_nop 0
	v_add_f32_e32 v19, v6, v7
	v_pk_mul_f32 v[6:7], v[20:21], v[30:31]
	s_nop 0
	v_sub_f32_e32 v6, v6, v7
	v_cndmask_b32_e32 v6, v19, v6, vcc
	v_cvt_pk_bf16_f32 v15, v18, v6
	v_cmp_gt_i32_e32 vcc, 64, v22
	global_store_dwordx4 v[2:3], v[12:15], off offset:112 sc1
	global_store_dwordx4 v[4:5], v[8:11], off offset:112 sc1
	s_and_saveexec_b64 s[4:5], vcc
	s_cbranch_execz .LBB0_330
	s_lshl_b32 s6, s2, 7
	ds_read_b64 v[2:3], v1 offset:8192
	v_lshl_add_u32 v4, v22, 1, s6
	v_ashrrev_i32_e32 v5, 31, v4
	v_lshl_add_u64 v[4:5], v[4:5], 2, s[94:95]
	v_add_co_u32_e32 v4, vcc, 0x6c00000, v4
	s_nop 1
	v_addc_co_u32_e32 v5, vcc, 0, v5, vcc
	s_waitcnt lgkmcnt(0)
	global_store_dwordx2 v[4:5], v[2:3], off sc1

; __device__ __forceinline__ unsigned cvt_pk_bf16(float lo, float hi) { unsigned r; asm volatile("v_cvt_pk_bf16_f32 %0, %1, %2" : "=v"(r) : "v"(lo), "v"(hi)); return r; }
; __global__ void __launch_bounds__(NWAVES * 64, 2) hymba_fwd(Args a) {
;     ...
;             for (int q = 0; q < 2; ++q) { const int mm = m + q * NW2; if (mm >= mEnd) continue;
;                 const float ms = wave_sum(s[q]) * (1.0f / DM) + RMS_EPS; const float r = 1.0f / sqrtf(ms);
;                 if (lane == 0) ((float*)(ws + WS_RX))[mm] = sqrtf(ms);
;                 v4u* o = (v4u*)(R1 + (size_t)mm * DM);
; #pragma unroll
;                 for (int j = 0; j < 4; ++j) { v4u w; w.x = cvt_pk_bf16(v[q][2 * j].x * r, v[q][2 * j].y * r); w.y = cvt_pk_bf16(v[q][2 * j].z * r, v[q][2 * j].w * r);
;                     w.z = cvt_pk_bf16(v[q][2 * j + 1].x * r, v[q][2 * j + 1].y * r); w.w = cvt_pk_bf16(v[q][2 * j + 1].z * r, v[q][2 * j + 1].w * r); o[64 * j + lane] = w; } }
.LBB0_333:
	s_or_b64 exec, exec, s[6:7]
	v_div_scale_f32 v35, s[6:7], v34, v34, 1.0
	v_rcp_f32_e32 v36, v35
	v_div_scale_f32 v37, vcc, 1.0, v34, 1.0
	s_lshl_b64 s[6:7], s[10:11], 12
	v_fma_f32 v38, -v35, v36, 1.0
	v_fmac_f32_e32 v36, v38, v36
	v_mul_f32_e32 v38, v37, v36
	v_fma_f32 v39, -v35, v38, v37
	v_fmac_f32_e32 v38, v39, v36
	v_fma_f32 v35, -v35, v38, v37
	v_div_fmas_f32 v35, v35, v36, v38
	v_div_fixup_f32 v34, v35, v34, 1.0
	v_mul_f32_e32 v30, v34, v30
	v_mul_f32_e32 v31, v34, v31
	v_cvt_pk_bf16_f32 v30, v30, v31
	v_mul_f32_e32 v31, v34, v32
	v_mul_f32_e32 v32, v34, v33
	v_mul_f32_e32 v26, v34, v26
	v_mul_f32_e32 v27, v34, v27
	v_cvt_pk_bf16_f32 v31, v31, v32
	v_cvt_pk_bf16_f32 v32, v26, v27
	v_mul_f32_e32 v26, v34, v28
	v_mul_f32_e32 v27, v34, v29
	v_cvt_pk_bf16_f32 v33, v26, v27
	v_lshl_add_u64 v[26:27], v[68:69], 0, s[6:7]
	v_mul_f32_e32 v22, v34, v22
	v_mul_f32_e32 v23, v34, v23
	global_store_dwordx4 v[26:27], v[30:33], off sc1
	v_cvt_pk_bf16_f32 v22, v22, v23
	v_mul_f32_e32 v23, v34, v24
	v_mul_f32_e32 v24, v34, v25
	v_mul_f32_e32 v18, v34, v18
	v_mul_f32_e32 v19, v34, v19
	v_mul_f32_e32 v14, v34, v14
	v_mul_f32_e32 v15, v34, v15
	v_cvt_pk_bf16_f32 v23, v23, v24
	v_cvt_pk_bf16_f32 v24, v18, v19
	v_mul_f32_e32 v18, v34, v20
	v_mul_f32_e32 v19, v34, v21
	v_cvt_pk_bf16_f32 v25, v18, v19
	global_store_dwordx4 v[26:27], v[22:25], off offset:1024 sc1
	v_cvt_pk_bf16_f32 v14, v14, v15
	v_mul_f32_e32 v15, v34, v16
	v_mul_f32_e32 v16, v34, v17
	v_mul_f32_e32 v10, v34, v10
	v_mul_f32_e32 v11, v34, v11
	v_mul_f32_e32 v6, v34, v6
	v_mul_f32_e32 v7, v34, v7
	v_cvt_pk_bf16_f32 v15, v15, v16
	v_cvt_pk_bf16_f32 v16, v10, v11
	v_mul_f32_e32 v10, v34, v12
	v_mul_f32_e32 v11, v34, v13
	v_cvt_pk_bf16_f32 v17, v10, v11
	global_store_dwordx4 v[26:27], v[14:17], off offset:2048 sc1
	v_cvt_pk_bf16_f32 v6, v6, v7
	v_mul_f32_e32 v7, v34, v8
	v_mul_f32_e32 v8, v34, v9
	v_mul_f32_e32 v2, v34, v2
	v_mul_f32_e32 v3, v34, v3
	v_cvt_pk_bf16_f32 v7, v7, v8
	v_cvt_pk_bf16_f32 v8, v2, v3
	v_mul_f32_e32 v2, v34, v4
	v_mul_f32_e32 v3, v34, v5
	v_cvt_pk_bf16_f32 v9, v2, v3
	global_store_dwordx4 v[26:27], v[6:9], off offset:3072 sc1

; __global__ void __launch_bounds__(NWAVES * 64, 2) hymba_fwd(Args a) {
;     ...
;         for (int m = isS ? bx * NWAVES + wave : 1024 + (bx - NG) * NWAVES + wave; m < mEnd; m += 2 * NW2) {
;             f32x4 v[2][8]; float s[2];
; #pragma unroll
;             for (int q = 0; q < 2; ++q) { const int mq = (m + q * NW2 < mEnd) ? m + q * NW2 : m; const f32x4* xr = (const f32x4*)(a.x + (size_t)mq * DM);
; #pragma unroll
;                 for (int j = 0; j < 4; ++j) { v[q][2 * j] = xr[128 * j + 2 * lane]; v[q][2 * j + 1] = xr[128 * j + 2 * lane + 1]; } }
; #pragma unroll
;             for (int q = 0; q < 2; ++q) { float t = 0.f;
; #pragma unroll
;                 for (int j = 0; j < 8; ++j) t += (v[q][j].x * v[q][j].x + v[q][j].y * v[q][j].y) + (v[q][j].z * v[q][j].z + v[q][j].w * v[q][j].w);
;                 s[q] = t; }
; #pragma unroll
;             for (int q = 0; q < 2; ++q) { const int mm = m + q * NW2; if (mm >= mEnd) continue;
;                 const float ms = wave_sum(s[q]) * (1.0f / DM) + RMS_EPS; const float r = 1.0f / sqrtf(ms);
;                 if (lane == 0) ((float*)(ws + WS_RX))[mm] = sqrtf(ms);
.LBB0_335:
	s_ashr_i32 s9, s8, 31
	s_lshl_b64 s[6:7], s[8:9], 13
	s_add_u32 s6, s56, s6
	s_addc_u32 s7, s57, s7
	global_load_dwordx4 v[62:65], v66, s[6:7]
	global_load_dwordx4 v[58:61], v66, s[6:7] offset:16
	global_load_dwordx4 v[54:57], v66, s[6:7] offset:2048
	global_load_dwordx4 v[50:53], v66, s[6:7] offset:2064
	global_load_dwordx4 v[46:49], v76, s[6:7]
	global_load_dwordx4 v[42:45], v76, s[6:7] offset:16
	global_load_dwordx4 v[38:41], v77, s[6:7]
	global_load_dwordx4 v[34:37], v77, s[6:7] offset:16
	s_add_i32 s10, s3, s8
	s_cmp_lt_i32 s10, s16
	s_cselect_b64 s[14:15], -1, 0
	s_and_b64 s[6:7], s[14:15], exec
	s_cselect_b32 s6, s10, s8
	s_ashr_i32 s7, s6, 31
	s_lshl_b64 s[6:7], s[6:7], 13
	s_add_u32 s6, s56, s6
	s_addc_u32 s7, s57, s7
	global_load_dwordx4 v[26:29], v66, s[6:7] offset:16
	global_load_dwordx4 v[30:33], v66, s[6:7]
	global_load_dwordx4 v[18:21], v66, s[6:7] offset:2064
	global_load_dwordx4 v[22:25], v66, s[6:7] offset:2048
	global_load_dwordx4 v[10:13], v76, s[6:7] offset:16
	global_load_dwordx4 v[14:17], v76, s[6:7]
	global_load_dwordx4 v[2:5], v77, s[6:7] offset:16
	global_load_dwordx4 v[6:9], v77, s[6:7]
	s_waitcnt vmcnt(15)
	v_mul_f32_e32 v80, v63, v63
	v_mul_f32_e32 v81, v65, v65
	s_waitcnt vmcnt(14)
	v_mul_f32_e32 v82, v59, v59
	v_mul_f32_e32 v83, v61, v61
	s_waitcnt vmcnt(13)
	v_mul_f32_e32 v84, v55, v55
	v_mul_f32_e32 v85, v57, v57
	v_fmac_f32_e32 v80, v62, v62
	v_fmac_f32_e32 v81, v64, v64
	v_fmac_f32_e32 v82, v58, v58
	v_fmac_f32_e32 v83, v60, v60
	s_waitcnt vmcnt(12)
	v_mul_f32_e32 v86, v51, v51
	v_mul_f32_e32 v87, v53, v53
	v_fmac_f32_e32 v84, v54, v54
	v_fmac_f32_e32 v85, v56, v56
	v_add_f32_e32 v80, v80, v81
	v_add_f32_e32 v81, v82, v83
	s_waitcnt vmcnt(11)
	v_mul_f32_e32 v88, v47, v47
	v_mul_f32_e32 v89, v49, v49
	v_fmac_f32_e32 v86, v50, v50
	v_fmac_f32_e32 v87, v52, v52
	v_add_f32_e32 v82, v84, v85
	v_add_f32_e32 v80, v80, v81
	s_waitcnt vmcnt(10)
	v_mul_f32_e32 v90, v43, v43
	v_mul_f32_e32 v91, v45, v45
	v_fmac_f32_e32 v88, v46, v46
	v_fmac_f32_e32 v89, v48, v48
	v_add_f32_e32 v83, v86, v87
	v_add_f32_e32 v80, v80, v82
	s_waitcnt vmcnt(9)
	v_mul_f32_e32 v92, v39, v39
	v_mul_f32_e32 v93, v41, v41
	v_fmac_f32_e32 v90, v42, v42
	v_fmac_f32_e32 v91, v44, v44
	v_add_f32_e32 v84, v88, v89
	v_add_f32_e32 v80, v80, v83
	s_waitcnt vmcnt(8)
	v_mul_f32_e32 v94, v35, v35
	v_mul_f32_e32 v95, v37, v37
	v_fmac_f32_e32 v92, v38, v38
	v_fmac_f32_e32 v93, v40, v40
	v_add_f32_e32 v85, v90, v91
	v_add_f32_e32 v80, v80, v84
	v_fmac_f32_e32 v94, v34, v34
	v_fmac_f32_e32 v95, v36, v36
	v_add_f32_e32 v86, v92, v93
	v_add_f32_e32 v80, v80, v85
	v_add_f32_e32 v87, v94, v95
	v_add_f32_e32 v80, v80, v86
	v_add_f32_e32 v80, v80, v87
	ds_bpermute_b32 v81, v70, v80
	s_waitcnt lgkmcnt(0)
	v_add_f32_e32 v80, v80, v81
	ds_bpermute_b32 v81, v71, v80
	s_waitcnt lgkmcnt(0)
	v_add_f32_e32 v80, v80, v81
	ds_bpermute_b32 v81, v72, v80
	s_waitcnt lgkmcnt(0)
	v_add_f32_e32 v80, v80, v81
	ds_bpermute_b32 v81, v73, v80
	s_waitcnt lgkmcnt(0)
	v_add_f32_e32 v80, v80, v81
	ds_bpermute_b32 v81, v74, v80
	s_waitcnt lgkmcnt(0)
	v_add_f32_e32 v80, v80, v81
	ds_bpermute_b32 v81, v75, v80
	s_waitcnt lgkmcnt(0)
	v_add_f32_e32 v80, v80, v81
	v_fmamk_f32 v80, v80, 0x3a000000, v78
	v_mul_f32_e32 v81, 0x4f800000, v80
	v_cmp_gt_f32_e32 vcc, s18, v80
	s_nop 1
	v_cndmask_b32_e32 v80, v80, v81, vcc
	v_sqrt_f32_e32 v81, v80
	s_nop 0
	v_add_u32_e32 v82, -1, v81
	v_add_u32_e32 v83, 1, v81
	v_fma_f32 v84, -v82, v81, v80
	v_fma_f32 v85, -v83, v81, v80
	v_cmp_ge_f32_e64 s[6:7], 0, v84
	s_nop 1
	v_cndmask_b32_e64 v81, v81, v82, s[6:7]
	v_cmp_lt_f32_e64 s[6:7], 0, v85
	s_nop 1
	v_cndmask_b32_e64 v81, v81, v83, s[6:7]
	v_mul_f32_e32 v82, 0x37800000, v81
	v_cndmask_b32_e32 v81, v81, v82, vcc
	v_cmp_class_f32_e32 vcc, v80, v79
	s_nop 1
	v_cndmask_b32_e32 v80, v81, v80, vcc
	s_and_saveexec_b64 s[6:7], s[0:1]
	s_cbranch_execz .LBB0_337
	s_lshl_b64 s[20:21], s[8:9], 2
	s_add_u32 s20, s4, s20
	s_addc_u32 s21, s5, s21
	global_store_dword v67, v80, s[20:21] sc1
; __device__ __forceinline__ unsigned cvt_pk_bf16(float lo, float hi) { unsigned r; asm volatile("v_cvt_pk_bf16_f32 %0, %1, %2" : "=v"(r) : "v"(lo), "v"(hi)); return r; }
; __global__ void __launch_bounds__(NWAVES * 64, 2) hymba_fwd(Args a) {
;     ...
;             for (int q = 0; q < 2; ++q) { float t = 0.f;
; #pragma unroll
;                 for (int j = 0; j < 8; ++j) t += (v[q][j].x * v[q][j].x + v[q][j].y * v[q][j].y) + (v[q][j].z * v[q][j].z + v[q][j].w * v[q][j].w);
;                 s[q] = t; }
; #pragma unroll
;             for (int q = 0; q < 2; ++q) { const int mm = m + q * NW2; if (mm >= mEnd) continue;
;                 const float ms = wave_sum(s[q]) * (1.0f / DM) + RMS_EPS; const float r = 1.0f / sqrtf(ms);
;                 if (lane == 0) ((float*)(ws + WS_RX))[mm] = sqrtf(ms);
;                 v4u* o = (v4u*)(R1 + (size_t)mm * DM);
; #pragma unroll
;                 for (int j = 0; j < 4; ++j) { v4u w; w.x = cvt_pk_bf16(v[q][2 * j].x * r, v[q][2 * j].y * r); w.y = cvt_pk_bf16(v[q][2 * j].z * r, v[q][2 * j].w * r);
;                     w.z = cvt_pk_bf16(v[q][2 * j + 1].x * r, v[q][2 * j + 1].y * r); w.w = cvt_pk_bf16(v[q][2 * j + 1].z * r, v[q][2 * j + 1].w * r); o[64 * j + lane] = w; } }
.LBB0_337:
	s_or_b64 exec, exec, s[6:7]
	v_div_scale_f32 v81, s[6:7], v80, v80, 1.0
	v_rcp_f32_e32 v82, v81
	v_div_scale_f32 v83, vcc, 1.0, v80, 1.0
	s_lshl_b64 s[6:7], s[8:9], 12
	v_fma_f32 v84, -v81, v82, 1.0
	v_fmac_f32_e32 v82, v84, v82
	v_mul_f32_e32 v84, v83, v82
	v_fma_f32 v85, -v81, v84, v83
	v_fmac_f32_e32 v84, v85, v82
	v_fma_f32 v81, -v81, v84, v83
	v_div_fmas_f32 v81, v81, v82, v84
	v_div_fixup_f32 v80, v81, v80, 1.0
	v_mul_f32_e32 v62, v80, v62
	v_mul_f32_e32 v63, v80, v63
	v_cvt_pk_bf16_f32 v62, v62, v63
	v_mul_f32_e32 v63, v80, v64
	v_mul_f32_e32 v64, v80, v65
	v_mul_f32_e32 v58, v80, v58
	v_mul_f32_e32 v59, v80, v59
	v_cvt_pk_bf16_f32 v63, v63, v64
	v_cvt_pk_bf16_f32 v64, v58, v59
	v_mul_f32_e32 v58, v80, v60
	v_mul_f32_e32 v59, v80, v61
	v_cvt_pk_bf16_f32 v65, v58, v59
	v_lshl_add_u64 v[58:59], v[68:69], 0, s[6:7]
	v_mul_f32_e32 v54, v80, v54
	v_mul_f32_e32 v55, v80, v55
	global_store_dwordx4 v[58:59], v[62:65], off sc1
	v_cvt_pk_bf16_f32 v54, v54, v55
	v_mul_f32_e32 v55, v80, v56
	v_mul_f32_e32 v56, v80, v57
	v_mul_f32_e32 v50, v80, v50
	v_mul_f32_e32 v51, v80, v51
	v_mul_f32_e32 v46, v80, v46
	v_mul_f32_e32 v47, v80, v47
	v_cvt_pk_bf16_f32 v55, v55, v56
	v_cvt_pk_bf16_f32 v56, v50, v51
	v_mul_f32_e32 v50, v80, v52
	v_mul_f32_e32 v51, v80, v53
	v_cvt_pk_bf16_f32 v57, v50, v51
	global_store_dwordx4 v[58:59], v[54:57], off offset:1024 sc1
	v_cvt_pk_bf16_f32 v46, v46, v47
	v_mul_f32_e32 v47, v80, v48
	v_mul_f32_e32 v48, v80, v49
	v_mul_f32_e32 v42, v80, v42
	v_mul_f32_e32 v43, v80, v43
	v_mul_f32_e32 v38, v80, v38
	v_mul_f32_e32 v39, v80, v39
	v_cvt_pk_bf16_f32 v47, v47, v48
	v_cvt_pk_bf16_f32 v48, v42, v43
	v_mul_f32_e32 v42, v80, v44
	v_mul_f32_e32 v43, v80, v45
	v_cvt_pk_bf16_f32 v49, v42, v43
	global_store_dwordx4 v[58:59], v[46:49], off offset:2048 sc1
	v_cvt_pk_bf16_f32 v38, v38, v39
	v_mul_f32_e32 v39, v80, v40
	v_mul_f32_e32 v40, v80, v41
	v_mul_f32_e32 v34, v80, v34
	v_mul_f32_e32 v35, v80, v35
	s_andn2_b64 vcc, exec, s[14:15]
	v_cvt_pk_bf16_f32 v39, v39, v40
	v_cvt_pk_bf16_f32 v40, v34, v35
	v_mul_f32_e32 v34, v80, v36
	v_mul_f32_e32 v35, v80, v37
	v_cvt_pk_bf16_f32 v41, v34, v35
	global_store_dwordx4 v[58:59], v[38:41], off offset:3072 sc1
	s_cbranch_vccnz .LBB0_334
	s_waitcnt vmcnt(10)
	v_mul_f32_e32 v34, v31, v31
	v_mul_f32_e32 v35, v33, v33
	v_fmac_f32_e32 v34, v30, v30
	v_fmac_f32_e32 v35, v32, v32
	v_add_f32_e32 v34, v34, v35
	v_mul_f32_e32 v35, v27, v27
	v_mul_f32_e32 v36, v29, v29
	v_fmac_f32_e32 v35, v26, v26
	v_fmac_f32_e32 v36, v28, v28
	v_add_f32_e32 v35, v35, v36
	v_add_f32_e32 v34, v34, v35
	s_waitcnt vmcnt(8)
	v_mul_f32_e32 v35, v23, v23
	v_mul_f32_e32 v36, v25, v25
	v_fmac_f32_e32 v35, v22, v22
	v_fmac_f32_e32 v36, v24, v24
	v_add_f32_e32 v35, v35, v36
	v_add_f32_e32 v34, v34, v35
	v_mul_f32_e32 v35, v19, v19
	v_mul_f32_e32 v36, v21, v21
	v_fmac_f32_e32 v35, v18, v18
	v_fmac_f32_e32 v36, v20, v20
	v_add_f32_e32 v35, v35, v36
	v_add_f32_e32 v34, v34, v35
	s_waitcnt vmcnt(6)
	v_mul_f32_e32 v35, v15, v15
	v_mul_f32_e32 v36, v17, v17
	v_fmac_f32_e32 v35, v14, v14
	v_fmac_f32_e32 v36, v16, v16
	v_add_f32_e32 v35, v35, v36
	v_add_f32_e32 v34, v34, v35
	v_mul_f32_e32 v35, v11, v11
	v_mul_f32_e32 v36, v13, v13
	v_fmac_f32_e32 v35, v10, v10
	v_fmac_f32_e32 v36, v12, v12
	v_add_f32_e32 v35, v35, v36
	v_add_f32_e32 v34, v34, v35
	s_waitcnt vmcnt(4)
	v_mul_f32_e32 v35, v7, v7
	v_mul_f32_e32 v36, v9, v9
	v_fmac_f32_e32 v35, v6, v6
	v_fmac_f32_e32 v36, v8, v8
	v_add_f32_e32 v35, v35, v36
	v_add_f32_e32 v34, v34, v35
	v_mul_f32_e32 v35, v3, v3
	v_mul_f32_e32 v36, v5, v5
	v_fmac_f32_e32 v35, v2, v2
	v_fmac_f32_e32 v36, v4, v4
	v_add_f32_e32 v35, v35, v36
	v_add_f32_e32 v34, v34, v35
	ds_bpermute_b32 v35, v70, v34
	s_ashr_i32 s11, s10, 31
	s_waitcnt lgkmcnt(0)
	v_add_f32_e32 v34, v34, v35
	ds_bpermute_b32 v35, v71, v34
	s_waitcnt lgkmcnt(0)
	v_add_f32_e32 v34, v34, v35
	ds_bpermute_b32 v35, v72, v34
	s_waitcnt lgkmcnt(0)
	v_add_f32_e32 v34, v34, v35
	ds_bpermute_b32 v35, v73, v34
	s_waitcnt lgkmcnt(0)
	v_add_f32_e32 v34, v34, v35
	ds_bpermute_b32 v35, v74, v34
	s_waitcnt lgkmcnt(0)
	v_add_f32_e32 v34, v34, v35
	ds_bpermute_b32 v35, v75, v34
	s_waitcnt lgkmcnt(0)
	v_add_f32_e32 v34, v34, v35
	v_fmamk_f32 v34, v34, 0x3a000000, v78
	v_mul_f32_e32 v35, 0x4f800000, v34
	v_cmp_gt_f32_e32 vcc, s18, v34
	s_nop 1
	v_cndmask_b32_e32 v34, v34, v35, vcc
	v_sqrt_f32_e32 v35, v34
	s_nop 0
	v_add_u32_e32 v36, -1, v35
	v_fma_f32 v37, -v36, v35, v34
	v_cmp_ge_f32_e64 s[6:7], 0, v37
	v_add_u32_e32 v37, 1, v35
	s_nop 0
	v_cndmask_b32_e64 v36, v35, v36, s[6:7]
	v_fma_f32 v35, -v37, v35, v34
	v_cmp_lt_f32_e64 s[6:7], 0, v35
	s_nop 1
	v_cndmask_b32_e64 v35, v36, v37, s[6:7]
	v_mul_f32_e32 v36, 0x37800000, v35
	v_cndmask_b32_e32 v35, v35, v36, vcc
	v_cmp_class_f32_e32 vcc, v34, v79
	s_nop 1
	v_cndmask_b32_e32 v34, v35, v34, vcc
	s_and_saveexec_b64 s[6:7], s[0:1]
	s_cbranch_execz .LBB0_333
	s_lshl_b64 s[14:15], s[10:11], 2
	s_add_u32 s14, s4, s14
	s_addc_u32 s15, s5, s15
	global_store_dword v67, v34, s[14:15] sc1
	s_branch .LBB0_333

; __device__ __forceinline__ unsigned cvt_pk_bf16(float lo, float hi) { unsigned r; asm volatile("v_cvt_pk_bf16_f32 %0, %1, %2" : "=v"(r) : "v"(lo), "v"(hi)); return r; }
;     __device__ __forceinline__ void operator()(const f32x4 (&acc)[2][2][4][2], const Unit& u, int wr, int wc, int fr, int fq) const {
;     ...
;         } else {
; #pragma unroll
;             for (int ai = 0; ai < 2; ++ai)
; #pragma unroll
;                 for (int m = 0; m < 4; ++m) { const int row = row0 + ai * HALF + m * 16;
; #pragma unroll
;                     for (int bj = 0; bj < 2; ++bj) { const f32x4 v0 = acc[ai][bj][m][0], v1 = acc[ai][bj][m][1];
;                         const int gcol = (u.pn - 5) * 256 + bj * HALF + cw, g = gcol >> 4, q0 = gcol & 15;
;                         u32x4 w; w.x = cvt_pk_bf16(v0[0], v0[1]); w.y = cvt_pk_bf16(v0[2], v0[3]); w.z = cvt_pk_bf16(v1[0], v1[1]); w.w = cvt_pk_bf16(v1[2], v1[3]);
;                         *(u32x4*)(A2 + (size_t)g * (1024 * 384) + (size_t)(row >> 4) * 384 + (row & 15) * 16 + q0) = w; } }
;         }
.LBB0_409:
	v_lshl_add_u32 v149, s4, 8, v160
	v_lshrrev_b32_e32 v151, 4, v149
	v_mov_b64_e32 v[176:177], s[58:59]
	s_ashr_i32 s15, s5, 4
	v_mad_u64_u32 v[152:153], s[22:23], v151, s47, v[176:177]
	v_mad_i64_i32 v[172:173], s[22:23], s15, v169, v[152:153]
	v_lshl_add_u64 v[172:173], v[172:173], 0, v[138:139]
	v_mov_b32_e32 v149, v139
	v_cvt_pk_bf16_f32 v154, v126, v127
	v_cvt_pk_bf16_f32 v155, v128, v129
	v_lshl_add_u64 v[172:173], v[172:173], 0, v[148:149]
	v_or_b32_e32 v151, 8, v151
	v_cvt_pk_bf16_f32 v156, v122, v123
	v_cvt_pk_bf16_f32 v157, v124, v125
	global_store_dwordx4 v[172:173], v[154:157], off sc1
	s_or_b32 s17, s15, 1
	v_cvt_pk_bf16_f32 v172, v118, v119
	v_cvt_pk_bf16_f32 v173, v120, v121
	v_cvt_pk_bf16_f32 v174, v114, v115
	v_cvt_pk_bf16_f32 v175, v116, v117
	s_nop 0
	v_mad_u64_u32 v[154:155], s[22:23], v151, s47, v[176:177]
	v_mad_i64_i32 v[156:157], s[22:23], s15, v169, v[154:155]
	v_lshl_add_u64 v[156:157], v[156:157], 0, v[138:139]
	v_lshl_add_u64 v[156:157], v[156:157], 0, v[148:149]
	global_store_dwordx4 v[156:157], v[172:175], off sc1
	v_mad_i64_i32 v[156:157], s[22:23], s17, v169, v[152:153]
	v_lshl_add_u64 v[156:157], v[156:157], 0, v[138:139]
	v_lshl_add_u64 v[156:157], v[156:157], 0, v[148:149]
	v_cvt_pk_bf16_f32 v172, v110, v111
	v_cvt_pk_bf16_f32 v173, v112, v113
	v_cvt_pk_bf16_f32 v174, v106, v107
	v_cvt_pk_bf16_f32 v175, v108, v109
	global_store_dwordx4 v[156:157], v[172:175], off sc1
	v_mad_i64_i32 v[156:157], s[22:23], s17, v169, v[154:155]
	v_lshl_add_u64 v[156:157], v[156:157], 0, v[138:139]
	v_lshl_add_u64 v[156:157], v[156:157], 0, v[148:149]
	s_or_b32 s17, s15, 2
	v_cvt_pk_bf16_f32 v172, v102, v103
	v_cvt_pk_bf16_f32 v173, v104, v105
	v_cvt_pk_bf16_f32 v174, v98, v99
	v_cvt_pk_bf16_f32 v175, v100, v101
	global_store_dwordx4 v[156:157], v[172:175], off sc1
	v_mad_i64_i32 v[156:157], s[22:23], s17, v169, v[152:153]
	v_lshl_add_u64 v[156:157], v[156:157], 0, v[138:139]
	v_lshl_add_u64 v[156:157], v[156:157], 0, v[148:149]
	v_cvt_pk_bf16_f32 v172, v94, v95
	v_cvt_pk_bf16_f32 v173, v96, v97
	v_cvt_pk_bf16_f32 v174, v90, v91
	v_cvt_pk_bf16_f32 v175, v92, v93
	global_store_dwordx4 v[156:157], v[172:175], off sc1
	v_mad_i64_i32 v[156:157], s[22:23], s17, v169, v[154:155]
	v_lshl_add_u64 v[156:157], v[156:157], 0, v[138:139]
	v_lshl_add_u64 v[156:157], v[156:157], 0, v[148:149]
	s_or_b32 s15, s15, 3
	v_cvt_pk_bf16_f32 v172, v86, v87
	v_cvt_pk_bf16_f32 v173, v88, v89
	v_cvt_pk_bf16_f32 v174, v82, v83
	v_cvt_pk_bf16_f32 v175, v84, v85
	global_store_dwordx4 v[156:157], v[172:175], off sc1
	v_mad_i64_i32 v[156:157], s[22:23], s15, v169, v[152:153]
	v_lshl_add_u64 v[156:157], v[156:157], 0, v[138:139]
	v_lshl_add_u64 v[156:157], v[156:157], 0, v[148:149]
	v_cvt_pk_bf16_f32 v172, v78, v79
	v_cvt_pk_bf16_f32 v173, v80, v81
	v_cvt_pk_bf16_f32 v174, v74, v75
	v_cvt_pk_bf16_f32 v175, v76, v77
	global_store_dwordx4 v[156:157], v[172:175], off sc1
	v_mad_i64_i32 v[156:157], s[22:23], s15, v169, v[154:155]
	v_lshl_add_u64 v[156:157], v[156:157], 0, v[138:139]
	s_add_i32 s15, s5, 0x80
	v_lshl_add_u64 v[156:157], v[156:157], 0, v[148:149]
	s_ashr_i32 s15, s15, 4
	v_cvt_pk_bf16_f32 v172, v70, v71
	v_cvt_pk_bf16_f32 v173, v72, v73
	v_cvt_pk_bf16_f32 v174, v66, v67
	v_cvt_pk_bf16_f32 v175, v68, v69
	global_store_dwordx4 v[156:157], v[172:175], off sc1
	v_mad_i64_i32 v[156:157], s[22:23], s15, v169, v[152:153]
	v_lshl_add_u64 v[156:157], v[156:157], 0, v[138:139]
	v_lshl_add_u64 v[156:157], v[156:157], 0, v[148:149]
	v_cvt_pk_bf16_f32 v172, v62, v63
	v_cvt_pk_bf16_f32 v173, v64, v65
	v_cvt_pk_bf16_f32 v174, v58, v59
	v_cvt_pk_bf16_f32 v175, v60, v61
	global_store_dwordx4 v[156:157], v[172:175], off sc1
	v_mad_i64_i32 v[156:157], s[22:23], s15, v169, v[154:155]
	v_lshl_add_u64 v[156:157], v[156:157], 0, v[138:139]
	s_add_i32 s15, s5, 0x90
	v_lshl_add_u64 v[156:157], v[156:157], 0, v[148:149]
	s_ashr_i32 s15, s15, 4
	v_cvt_pk_bf16_f32 v172, v54, v55
	v_cvt_pk_bf16_f32 v173, v56, v57
	v_cvt_pk_bf16_f32 v174, v50, v51
	v_cvt_pk_bf16_f32 v175, v52, v53
	global_store_dwordx4 v[156:157], v[172:175], off sc1
	v_mad_i64_i32 v[156:157], s[22:23], s15, v169, v[152:153]
	v_lshl_add_u64 v[156:157], v[156:157], 0, v[138:139]
	v_lshl_add_u64 v[156:157], v[156:157], 0, v[148:149]
	v_cvt_pk_bf16_f32 v172, v46, v47
	v_cvt_pk_bf16_f32 v173, v48, v49
	v_cvt_pk_bf16_f32 v174, v42, v43
	v_cvt_pk_bf16_f32 v175, v44, v45
	global_store_dwordx4 v[156:157], v[172:175], off sc1
	v_mad_i64_i32 v[156:157], s[22:23], s15, v169, v[154:155]
	v_lshl_add_u64 v[156:157], v[156:157], 0, v[138:139]
	s_add_i32 s15, s5, 0xa0
	v_lshl_add_u64 v[156:157], v[156:157], 0, v[148:149]
	s_ashr_i32 s15, s15, 4
	v_cvt_pk_bf16_f32 v172, v38, v39
	v_cvt_pk_bf16_f32 v173, v40, v41
	v_cvt_pk_bf16_f32 v174, v34, v35
	v_cvt_pk_bf16_f32 v175, v36, v37
	global_store_dwordx4 v[156:157], v[172:175], off sc1
	v_mad_i64_i32 v[156:157], s[22:23], s15, v169, v[152:153]
	v_lshl_add_u64 v[156:157], v[156:157], 0, v[138:139]
	v_lshl_add_u64 v[156:157], v[156:157], 0, v[148:149]
	v_cvt_pk_bf16_f32 v172, v30, v31
	v_cvt_pk_bf16_f32 v173, v32, v33
	v_cvt_pk_bf16_f32 v174, v26, v27
	v_cvt_pk_bf16_f32 v175, v28, v29
	global_store_dwordx4 v[156:157], v[172:175], off sc1
	v_mad_i64_i32 v[156:157], s[22:23], s15, v169, v[154:155]
	s_add_i32 s15, s5, 0xb0
	s_ashr_i32 s15, s15, 4
	v_mad_i64_i32 v[152:153], s[22:23], s15, v169, v[152:153]
	v_lshl_add_u64 v[156:157], v[156:157], 0, v[138:139]
	v_lshl_add_u64 v[152:153], v[152:153], 0, v[138:139]
	v_cvt_pk_bf16_f32 v172, v22, v23
	v_cvt_pk_bf16_f32 v173, v24, v25
	v_cvt_pk_bf16_f32 v174, v18, v19
	v_cvt_pk_bf16_f32 v175, v20, v21
	v_lshl_add_u64 v[156:157], v[156:157], 0, v[148:149]
	v_lshl_add_u64 v[152:153], v[152:153], 0, v[148:149]
	global_store_dwordx4 v[156:157], v[172:175], off sc1
	s_nop 1
	v_cvt_pk_bf16_f32 v172, v14, v15
	v_cvt_pk_bf16_f32 v173, v16, v17
	v_cvt_pk_bf16_f32 v174, v10, v11
	v_cvt_pk_bf16_f32 v175, v12, v13
	global_store_dwordx4 v[152:153], v[172:175], off sc1
	v_mad_i64_i32 v[152:153], s[22:23], s15, v169, v[154:155]
	v_lshl_add_u64 v[152:153], v[152:153], 0, v[138:139]
	v_lshl_add_u64 v[152:153], v[152:153], 0, v[148:149]
	v_cvt_pk_bf16_f32 v172, v6, v7
	v_cvt_pk_bf16_f32 v173, v8, v9
	v_cvt_pk_bf16_f32 v174, v2, v3
	v_cvt_pk_bf16_f32 v175, v4, v5
	global_store_dwordx4 v[152:153], v[172:175], off sc1
	s_cbranch_execnz .LBB0_408
; __device__ __forceinline__ unsigned cvt_pk_bf16(float lo, float hi) { unsigned r; asm volatile("v_cvt_pk_bf16_f32 %0, %1, %2" : "=v"(r) : "v"(lo), "v"(hi)); return r; }
;     __device__ __forceinline__ void operator()(const f32x4 (&acc)[2][2][4][2], const Unit& u, int wr, int wc, int fr, int fq) const {
;     ...
;         if (u.pn < 5) {
;             const bool isq = u.pn < 4; const float sc = isq ? ATT_C2 : 1.0f;
;             const int i0 = (cw & 63) >> 1;
;             float invf[4];
; #pragma unroll
;             for (int t = 0; t < 4; ++t) invf[t] = __builtin_amdgcn_exp2f(-(float)(i0 + t) * (13.287712379549449f / 32.0f));
;             bf16_t* base = isq ? (Q + u.pn * 256) : Kp; const int ld = isq ? 1024 : 256;
; #pragma unroll
;             for (int ai = 0; ai < 2; ++ai)
; #pragma unroll
;                 for (int m = 0; m < 4; ++m) { const int row = row0 + ai * HALF + m * 16; const float p = (float)posl[wr * 64 + fr + ai * HALF + m * 16];
;                     float cs[4], sn[4];
; #pragma unroll
;                     for (int t = 0; t < 4; ++t) { const float ang = p * invf[t]; const float fr_ = __builtin_amdgcn_fractf(ang * 0.15915494309189535f); sn[t] = __builtin_amdgcn_sinf(fr_) * sc; cs[t] = __builtin_amdgcn_cosf(fr_) * sc; }
; #pragma unroll
;                     for (int bj = 0; bj < 2; ++bj) { const f32x4 v0 = acc[ai][bj][m][0], v1 = acc[ai][bj][m][1];
;                         u32x4 w;
;                         w.x = cvt_pk_bf16(v0[0] * cs[0] - v0[1] * sn[0], v0[1] * cs[0] + v0[0] * sn[0]);
;                         w.y = cvt_pk_bf16(v0[2] * cs[1] - v0[3] * sn[1], v0[3] * cs[1] + v0[2] * sn[1]);
;                         w.z = cvt_pk_bf16(v1[0] * cs[2] - v1[1] * sn[2], v1[1] * cs[2] + v1[0] * sn[2]);
;                         w.w = cvt_pk_bf16(v1[2] * cs[3] - v1[3] * sn[3], v1[3] * cs[3] + v1[2] * sn[3]);
;                         *(u32x4*)(base + (size_t)row * ld + bj * HALF + cw) = w; } }
.LBB0_410:
	s_lshl_b32 s22, s4, 8
	ds_read_b32 v149, v165
	s_ashr_i32 s23, s22, 31
	s_lshl_b64 s[22:23], s[22:23], 1
	s_add_u32 s15, s84, s22
	s_addc_u32 s17, s85, s23
	s_cmp_eq_u32 s4, 4
	s_waitcnt lgkmcnt(0)
	v_cvt_f32_i32_e32 v149, v149
	v_or_b32_e32 v154, s5, v158
	s_cselect_b64 s[4:5], -1, 0
	v_cndmask_b32_e64 v152, v170, 1.0, s[4:5]
	s_and_b64 s[4:5], s[4:5], exec
	s_cselect_b32 s5, s41, s17
	s_cselect_b32 s4, s40, s15
	v_mov_b32_e32 v151, v139
	v_lshl_add_u64 v[156:157], s[4:5], 0, v[150:151]
	v_mul_f32_e32 v151, v161, v149
	v_mul_f32_e32 v151, 0.15915494, v151
	v_fract_f32_e32 v151, v151
	v_sin_f32_e32 v173, v151
	v_cos_f32_e32 v172, v151
	v_mul_f32_e32 v151, v162, v149
	v_mul_f32_e32 v151, 0.15915494, v151
	v_fract_f32_e32 v151, v151
	v_sin_f32_e32 v175, v151
	v_cos_f32_e32 v174, v151
	v_mul_f32_e32 v151, v163, v149
	v_mul_f32_e32 v151, 0.15915494, v151
	v_fract_f32_e32 v151, v151
	v_sin_f32_e32 v177, v151
	v_cos_f32_e32 v176, v151
	v_mul_f32_e32 v149, v164, v149
	v_mul_f32_e32 v149, 0.15915494, v149
	v_pk_mul_f32 v[172:173], v[152:153], v[172:173] op_sel_hi:[0,1]
	v_fract_f32_e32 v149, v149
	v_pk_mul_f32 v[182:183], v[126:127], v[172:173]
	v_pk_mul_f32 v[174:175], v[152:153], v[174:175] op_sel_hi:[0,1]
	v_sin_f32_e32 v179, v149
	v_cos_f32_e32 v178, v149
	v_sub_f32_e32 v149, v182, v183
	v_pk_mul_f32 v[126:127], v[126:127], v[172:173] op_sel:[1,0] op_sel_hi:[0,1]
	v_pk_mul_f32 v[182:183], v[128:129], v[174:175]
	v_pk_mul_f32 v[128:129], v[128:129], v[174:175] op_sel:[1,0] op_sel_hi:[0,1]
	v_add_f32_e32 v126, v126, v127
	v_sub_f32_e32 v127, v182, v183
	v_add_f32_e32 v128, v128, v129
	v_pk_mul_f32 v[176:177], v[152:153], v[176:177] op_sel_hi:[0,1]
	v_cvt_pk_bf16_f32 v126, v149, v126
	v_cvt_pk_bf16_f32 v127, v127, v128
	v_pk_mul_f32 v[128:129], v[122:123], v[176:177]
	v_pk_mul_f32 v[122:123], v[122:123], v[176:177] op_sel:[1,0] op_sel_hi:[0,1]
	v_sub_f32_e32 v128, v128, v129
	v_add_f32_e32 v122, v122, v123
	v_cvt_pk_bf16_f32 v128, v128, v122
	v_pk_mul_f32 v[122:123], v[152:153], v[178:179] op_sel_hi:[0,1]
	v_pk_mul_f32 v[178:179], v[124:125], v[122:123]
	v_pk_mul_f32 v[124:125], v[124:125], v[122:123] op_sel:[1,0] op_sel_hi:[0,1]
	v_ashrrev_i32_e32 v155, 31, v154
	s_cselect_b32 s4, 8, 10
	v_sub_f32_e32 v129, v178, v179
	v_add_f32_e32 v124, v124, v125
	v_lshlrev_b64 v[180:181], s4, v[154:155]
	v_cvt_pk_bf16_f32 v129, v129, v124
	v_pk_mul_f32 v[124:125], v[118:119], v[172:173]
	v_pk_mul_f32 v[118:119], v[118:119], v[172:173] op_sel:[1,0] op_sel_hi:[0,1]
	v_lshl_add_u64 v[180:181], v[180:181], 1, v[156:157]
	v_sub_f32_e32 v124, v124, v125
	v_add_f32_e32 v118, v118, v119
	global_store_dwordx4 v[180:181], v[126:129], off sc1
	v_cvt_pk_bf16_f32 v118, v124, v118
	v_pk_mul_f32 v[124:125], v[120:121], v[174:175]
	v_pk_mul_f32 v[120:121], v[120:121], v[174:175] op_sel:[1,0] op_sel_hi:[0,1]
	v_sub_f32_e32 v119, v124, v125
	v_add_f32_e32 v120, v120, v121
	v_cvt_pk_bf16_f32 v119, v119, v120
	v_pk_mul_f32 v[120:121], v[114:115], v[176:177]
	v_pk_mul_f32 v[114:115], v[114:115], v[176:177] op_sel:[1,0] op_sel_hi:[0,1]
	v_sub_f32_e32 v120, v120, v121
	v_add_f32_e32 v114, v114, v115
	v_cvt_pk_bf16_f32 v120, v120, v114
	v_pk_mul_f32 v[114:115], v[116:117], v[122:123]
	s_nop 0
	v_sub_f32_e32 v121, v114, v115
	v_pk_mul_f32 v[114:115], v[116:117], v[122:123] op_sel:[1,0] op_sel_hi:[0,1]
	v_add_f32_e32 v114, v114, v115
	v_cvt_pk_bf16_f32 v121, v121, v114
	ds_read_b32 v114, v165 offset:64
	global_store_dwordx4 v[180:181], v[118:121], off offset:256 sc1
	s_waitcnt lgkmcnt(0)
	v_cvt_f32_i32_e32 v122, v114
	v_mul_f32_e32 v114, v161, v122
	v_mul_f32_e32 v114, 0.15915494, v114
	v_fract_f32_e32 v114, v114
	v_mul_f32_e32 v116, v162, v122
	v_sin_f32_e32 v115, v114
	v_cos_f32_e32 v114, v114
	v_mul_f32_e32 v116, 0.15915494, v116
	v_fract_f32_e32 v116, v116
	v_mul_f32_e32 v118, v163, v122
	v_sin_f32_e32 v117, v116
	v_cos_f32_e32 v116, v116
	v_mul_f32_e32 v118, 0.15915494, v118
	v_fract_f32_e32 v118, v118
	v_sin_f32_e32 v119, v118
	v_cos_f32_e32 v118, v118
	v_mul_f32_e32 v120, v164, v122
	v_pk_mul_f32 v[114:115], v[152:153], v[114:115] op_sel_hi:[0,1]
	v_mul_f32_e32 v120, 0.15915494, v120
	v_pk_mul_f32 v[124:125], v[110:111], v[114:115]
	v_pk_mul_f32 v[110:111], v[110:111], v[114:115] op_sel:[1,0] op_sel_hi:[0,1]
	v_fract_f32_e32 v120, v120
	v_sub_f32_e32 v124, v124, v125
	v_add_f32_e32 v110, v110, v111
	v_pk_mul_f32 v[116:117], v[152:153], v[116:117] op_sel_hi:[0,1]
	v_sin_f32_e32 v121, v120
	v_cos_f32_e32 v120, v120
	v_cvt_pk_bf16_f32 v110, v124, v110
	v_pk_mul_f32 v[124:125], v[112:113], v[116:117]
	v_pk_mul_f32 v[112:113], v[112:113], v[116:117] op_sel:[1,0] op_sel_hi:[0,1]
	v_sub_f32_e32 v111, v124, v125
	v_add_f32_e32 v112, v112, v113
	v_pk_mul_f32 v[118:119], v[152:153], v[118:119] op_sel_hi:[0,1]
	v_cvt_pk_bf16_f32 v111, v111, v112
	v_pk_mul_f32 v[112:113], v[106:107], v[118:119]
	v_pk_mul_f32 v[106:107], v[106:107], v[118:119] op_sel:[1,0] op_sel_hi:[0,1]
	v_sub_f32_e32 v112, v112, v113
	v_add_f32_e32 v106, v106, v107
	v_cvt_pk_bf16_f32 v112, v112, v106
	v_pk_mul_f32 v[106:107], v[152:153], v[120:121] op_sel_hi:[0,1]
	v_or_b32_e32 v122, 16, v154
	v_pk_mul_f32 v[120:121], v[108:109], v[106:107]
	v_pk_mul_f32 v[108:109], v[108:109], v[106:107] op_sel:[1,0] op_sel_hi:[0,1]
	v_ashrrev_i32_e32 v123, 31, v122
	v_sub_f32_e32 v113, v120, v121
	v_add_f32_e32 v108, v108, v109
	v_lshlrev_b64 v[122:123], s4, v[122:123]
	v_cvt_pk_bf16_f32 v113, v113, v108
	v_pk_mul_f32 v[108:109], v[102:103], v[114:115]
	v_pk_mul_f32 v[102:103], v[102:103], v[114:115] op_sel:[1,0] op_sel_hi:[0,1]
	v_lshl_add_u64 v[122:123], v[122:123], 1, v[156:157]
	v_sub_f32_e32 v108, v108, v109
	v_add_f32_e32 v102, v102, v103
	global_store_dwordx4 v[122:123], v[110:113], off sc1
	v_cvt_pk_bf16_f32 v102, v108, v102
	v_pk_mul_f32 v[108:109], v[104:105], v[116:117]
	v_pk_mul_f32 v[104:105], v[104:105], v[116:117] op_sel:[1,0] op_sel_hi:[0,1]
	v_sub_f32_e32 v103, v108, v109
	v_add_f32_e32 v104, v104, v105
	v_cvt_pk_bf16_f32 v103, v103, v104
	v_pk_mul_f32 v[104:105], v[98:99], v[118:119]
	v_pk_mul_f32 v[98:99], v[98:99], v[118:119] op_sel:[1,0] op_sel_hi:[0,1]
	v_sub_f32_e32 v104, v104, v105
	v_add_f32_e32 v98, v98, v99
	v_cvt_pk_bf16_f32 v104, v104, v98
	v_pk_mul_f32 v[98:99], v[100:101], v[106:107]
	s_nop 0
	v_sub_f32_e32 v105, v98, v99
	v_pk_mul_f32 v[98:99], v[100:101], v[106:107] op_sel:[1,0] op_sel_hi:[0,1]
	v_add_f32_e32 v98, v98, v99
	v_cvt_pk_bf16_f32 v105, v105, v98
	ds_read_b32 v98, v165 offset:128
	global_store_dwordx4 v[122:123], v[102:105], off offset:256 sc1
	s_waitcnt lgkmcnt(0)
; __device__ __forceinline__ unsigned cvt_pk_bf16(float lo, float hi) { unsigned r; asm volatile("v_cvt_pk_bf16_f32 %0, %1, %2" : "=v"(r) : "v"(lo), "v"(hi)); return r; }
;     __device__ __forceinline__ void operator()(const f32x4 (&acc)[2][2][4][2], const Unit& u, int wr, int wc, int fr, int fq) const {
;     ...
;             for (int ai = 0; ai < 2; ++ai)
; #pragma unroll
;                 for (int m = 0; m < 4; ++m) { const int row = row0 + ai * HALF + m * 16; const float p = (float)posl[wr * 64 + fr + ai * HALF + m * 16];
;                     float cs[4], sn[4];
; #pragma unroll
;                     for (int t = 0; t < 4; ++t) { const float ang = p * invf[t]; const float fr_ = __builtin_amdgcn_fractf(ang * 0.15915494309189535f); sn[t] = __builtin_amdgcn_sinf(fr_) * sc; cs[t] = __builtin_amdgcn_cosf(fr_) * sc; }
; #pragma unroll
;                     for (int bj = 0; bj < 2; ++bj) { const f32x4 v0 = acc[ai][bj][m][0], v1 = acc[ai][bj][m][1];
;                         u32x4 w;
;                         w.x = cvt_pk_bf16(v0[0] * cs[0] - v0[1] * sn[0], v0[1] * cs[0] + v0[0] * sn[0]);
;                         w.y = cvt_pk_bf16(v0[2] * cs[1] - v0[3] * sn[1], v0[3] * cs[1] + v0[2] * sn[1]);
;                         w.z = cvt_pk_bf16(v1[0] * cs[2] - v1[1] * sn[2], v1[1] * cs[2] + v1[0] * sn[2]);
;                         w.w = cvt_pk_bf16(v1[2] * cs[3] - v1[3] * sn[3], v1[3] * cs[3] + v1[2] * sn[3]);
;                         *(u32x4*)(base + (size_t)row * ld + bj * HALF + cw) = w; } }
	v_cvt_f32_i32_e32 v106, v98
	v_mul_f32_e32 v98, v161, v106
	v_mul_f32_e32 v98, 0.15915494, v98
	v_fract_f32_e32 v98, v98
	v_mul_f32_e32 v100, v162, v106
	v_sin_f32_e32 v99, v98
	v_cos_f32_e32 v98, v98
	v_mul_f32_e32 v100, 0.15915494, v100
	v_fract_f32_e32 v100, v100
	v_mul_f32_e32 v102, v163, v106
	v_sin_f32_e32 v101, v100
	v_cos_f32_e32 v100, v100
	v_mul_f32_e32 v102, 0.15915494, v102
	v_fract_f32_e32 v102, v102
	v_sin_f32_e32 v103, v102
	v_cos_f32_e32 v102, v102
	v_mul_f32_e32 v104, v164, v106
	v_pk_mul_f32 v[98:99], v[152:153], v[98:99] op_sel_hi:[0,1]
	v_mul_f32_e32 v104, 0.15915494, v104
	v_pk_mul_f32 v[108:109], v[94:95], v[98:99]
	v_pk_mul_f32 v[94:95], v[94:95], v[98:99] op_sel:[1,0] op_sel_hi:[0,1]
	v_fract_f32_e32 v104, v104
	v_sub_f32_e32 v108, v108, v109
	v_add_f32_e32 v94, v94, v95
	v_pk_mul_f32 v[100:101], v[152:153], v[100:101] op_sel_hi:[0,1]
	v_sin_f32_e32 v105, v104
	v_cos_f32_e32 v104, v104
	v_cvt_pk_bf16_f32 v94, v108, v94
	v_pk_mul_f32 v[108:109], v[96:97], v[100:101]
	v_pk_mul_f32 v[96:97], v[96:97], v[100:101] op_sel:[1,0] op_sel_hi:[0,1]
	v_sub_f32_e32 v95, v108, v109
	v_add_f32_e32 v96, v96, v97
	v_pk_mul_f32 v[102:103], v[152:153], v[102:103] op_sel_hi:[0,1]
	v_cvt_pk_bf16_f32 v95, v95, v96
	v_pk_mul_f32 v[96:97], v[90:91], v[102:103]
	v_pk_mul_f32 v[90:91], v[90:91], v[102:103] op_sel:[1,0] op_sel_hi:[0,1]
	v_sub_f32_e32 v96, v96, v97
	v_add_f32_e32 v90, v90, v91
	v_cvt_pk_bf16_f32 v96, v96, v90
	v_pk_mul_f32 v[90:91], v[152:153], v[104:105] op_sel_hi:[0,1]
	v_or_b32_e32 v106, 32, v154
	v_pk_mul_f32 v[104:105], v[92:93], v[90:91]
	v_pk_mul_f32 v[92:93], v[92:93], v[90:91] op_sel:[1,0] op_sel_hi:[0,1]
	v_ashrrev_i32_e32 v107, 31, v106
	v_sub_f32_e32 v97, v104, v105
	v_add_f32_e32 v92, v92, v93
	v_lshlrev_b64 v[106:107], s4, v[106:107]
	v_cvt_pk_bf16_f32 v97, v97, v92
	v_pk_mul_f32 v[92:93], v[86:87], v[98:99]
	v_pk_mul_f32 v[86:87], v[86:87], v[98:99] op_sel:[1,0] op_sel_hi:[0,1]
	v_lshl_add_u64 v[106:107], v[106:107], 1, v[156:157]
	v_sub_f32_e32 v92, v92, v93
	v_add_f32_e32 v86, v86, v87
	global_store_dwordx4 v[106:107], v[94:97], off sc1
	v_cvt_pk_bf16_f32 v86, v92, v86
	v_pk_mul_f32 v[92:93], v[88:89], v[100:101]
	v_pk_mul_f32 v[88:89], v[88:89], v[100:101] op_sel:[1,0] op_sel_hi:[0,1]
	v_sub_f32_e32 v87, v92, v93
	v_add_f32_e32 v88, v88, v89
	v_cvt_pk_bf16_f32 v87, v87, v88
	v_pk_mul_f32 v[88:89], v[82:83], v[102:103]
	v_pk_mul_f32 v[82:83], v[82:83], v[102:103] op_sel:[1,0] op_sel_hi:[0,1]
	v_sub_f32_e32 v88, v88, v89
	v_add_f32_e32 v82, v82, v83
	v_cvt_pk_bf16_f32 v88, v88, v82
	v_pk_mul_f32 v[82:83], v[84:85], v[90:91]
	s_nop 0
	v_sub_f32_e32 v89, v82, v83
	v_pk_mul_f32 v[82:83], v[84:85], v[90:91] op_sel:[1,0] op_sel_hi:[0,1]
	v_add_f32_e32 v82, v82, v83
	v_cvt_pk_bf16_f32 v89, v89, v82
	ds_read_b32 v82, v165 offset:192
	global_store_dwordx4 v[106:107], v[86:89], off offset:256 sc1
	s_waitcnt lgkmcnt(0)
	v_cvt_f32_i32_e32 v90, v82
	v_mul_f32_e32 v82, v161, v90
	v_mul_f32_e32 v82, 0.15915494, v82
	v_fract_f32_e32 v82, v82
	v_mul_f32_e32 v84, v162, v90
	v_sin_f32_e32 v83, v82
	v_cos_f32_e32 v82, v82
	v_mul_f32_e32 v84, 0.15915494, v84
	v_fract_f32_e32 v84, v84
	v_mul_f32_e32 v86, v163, v90
	v_sin_f32_e32 v85, v84
	v_cos_f32_e32 v84, v84
	v_mul_f32_e32 v86, 0.15915494, v86
	v_fract_f32_e32 v86, v86
	v_sin_f32_e32 v87, v86
	v_cos_f32_e32 v86, v86
	v_mul_f32_e32 v88, v164, v90
	v_pk_mul_f32 v[82:83], v[152:153], v[82:83] op_sel_hi:[0,1]
	v_mul_f32_e32 v88, 0.15915494, v88
	v_pk_mul_f32 v[92:93], v[78:79], v[82:83]
	v_pk_mul_f32 v[78:79], v[78:79], v[82:83] op_sel:[1,0] op_sel_hi:[0,1]
	v_fract_f32_e32 v88, v88
	v_sub_f32_e32 v92, v92, v93
	v_add_f32_e32 v78, v78, v79
	v_pk_mul_f32 v[84:85], v[152:153], v[84:85] op_sel_hi:[0,1]
	v_sin_f32_e32 v89, v88
	v_cos_f32_e32 v88, v88
	v_cvt_pk_bf16_f32 v78, v92, v78
	v_pk_mul_f32 v[92:93], v[80:81], v[84:85]
	v_pk_mul_f32 v[80:81], v[80:81], v[84:85] op_sel:[1,0] op_sel_hi:[0,1]
	v_sub_f32_e32 v79, v92, v93
	v_add_f32_e32 v80, v80, v81
	v_pk_mul_f32 v[86:87], v[152:153], v[86:87] op_sel_hi:[0,1]
	v_cvt_pk_bf16_f32 v79, v79, v80
	v_pk_mul_f32 v[80:81], v[74:75], v[86:87]
	v_pk_mul_f32 v[74:75], v[74:75], v[86:87] op_sel:[1,0] op_sel_hi:[0,1]
	v_sub_f32_e32 v80, v80, v81
	v_add_f32_e32 v74, v74, v75
	v_cvt_pk_bf16_f32 v80, v80, v74
	v_pk_mul_f32 v[74:75], v[152:153], v[88:89] op_sel_hi:[0,1]
	v_or_b32_e32 v90, 48, v154
	v_pk_mul_f32 v[88:89], v[76:77], v[74:75]
	v_pk_mul_f32 v[76:77], v[76:77], v[74:75] op_sel:[1,0] op_sel_hi:[0,1]
	v_ashrrev_i32_e32 v91, 31, v90
	v_sub_f32_e32 v81, v88, v89
	v_add_f32_e32 v76, v76, v77
	v_lshlrev_b64 v[90:91], s4, v[90:91]
	v_cvt_pk_bf16_f32 v81, v81, v76
	v_pk_mul_f32 v[76:77], v[70:71], v[82:83]
	v_pk_mul_f32 v[70:71], v[70:71], v[82:83] op_sel:[1,0] op_sel_hi:[0,1]
	v_lshl_add_u64 v[90:91], v[90:91], 1, v[156:157]
	v_sub_f32_e32 v76, v76, v77
	v_add_f32_e32 v70, v70, v71
	global_store_dwordx4 v[90:91], v[78:81], off sc1
	v_cvt_pk_bf16_f32 v70, v76, v70
	v_pk_mul_f32 v[76:77], v[72:73], v[84:85]
	v_pk_mul_f32 v[72:73], v[72:73], v[84:85] op_sel:[1,0] op_sel_hi:[0,1]
	v_sub_f32_e32 v71, v76, v77
	v_add_f32_e32 v72, v72, v73
	v_cvt_pk_bf16_f32 v71, v71, v72
	v_pk_mul_f32 v[72:73], v[66:67], v[86:87]
	v_pk_mul_f32 v[66:67], v[66:67], v[86:87] op_sel:[1,0] op_sel_hi:[0,1]
	v_sub_f32_e32 v72, v72, v73
	v_add_f32_e32 v66, v66, v67
	v_cvt_pk_bf16_f32 v72, v72, v66
	v_pk_mul_f32 v[66:67], v[68:69], v[74:75]
	s_nop 0
	v_sub_f32_e32 v73, v66, v67
	v_pk_mul_f32 v[66:67], v[68:69], v[74:75] op_sel:[1,0] op_sel_hi:[0,1]
	v_add_f32_e32 v66, v66, v67
	v_cvt_pk_bf16_f32 v73, v73, v66
	ds_read_b32 v66, v165 offset:512
	global_store_dwordx4 v[90:91], v[70:73], off offset:256 sc1
	s_waitcnt lgkmcnt(0)
; __device__ __forceinline__ unsigned cvt_pk_bf16(float lo, float hi) { unsigned r; asm volatile("v_cvt_pk_bf16_f32 %0, %1, %2" : "=v"(r) : "v"(lo), "v"(hi)); return r; }
;     __device__ __forceinline__ void operator()(const f32x4 (&acc)[2][2][4][2], const Unit& u, int wr, int wc, int fr, int fq) const {
;     ...
;                 for (int m = 0; m < 4; ++m) { const int row = row0 + ai * HALF + m * 16; const float p = (float)posl[wr * 64 + fr + ai * HALF + m * 16];
;                     float cs[4], sn[4];
; #pragma unroll
;                     for (int t = 0; t < 4; ++t) { const float ang = p * invf[t]; const float fr_ = __builtin_amdgcn_fractf(ang * 0.15915494309189535f); sn[t] = __builtin_amdgcn_sinf(fr_) * sc; cs[t] = __builtin_amdgcn_cosf(fr_) * sc; }
; #pragma unroll
;                     for (int bj = 0; bj < 2; ++bj) { const f32x4 v0 = acc[ai][bj][m][0], v1 = acc[ai][bj][m][1];
;                         u32x4 w;
;                         w.x = cvt_pk_bf16(v0[0] * cs[0] - v0[1] * sn[0], v0[1] * cs[0] + v0[0] * sn[0]);
;                         w.y = cvt_pk_bf16(v0[2] * cs[1] - v0[3] * sn[1], v0[3] * cs[1] + v0[2] * sn[1]);
;                         w.z = cvt_pk_bf16(v1[0] * cs[2] - v1[1] * sn[2], v1[1] * cs[2] + v1[0] * sn[2]);
;                         w.w = cvt_pk_bf16(v1[2] * cs[3] - v1[3] * sn[3], v1[3] * cs[3] + v1[2] * sn[3]);
;                         *(u32x4*)(base + (size_t)row * ld + bj * HALF + cw) = w; } }
	v_cvt_f32_i32_e32 v67, v66
	v_add_u32_e32 v66, 0x80, v154
	v_mul_f32_e32 v68, v161, v67
	v_mul_f32_e32 v68, 0.15915494, v68
	v_fract_f32_e32 v68, v68
	v_mul_f32_e32 v70, v162, v67
	v_sin_f32_e32 v69, v68
	v_cos_f32_e32 v68, v68
	v_mul_f32_e32 v70, 0.15915494, v70
	v_fract_f32_e32 v70, v70
	v_mul_f32_e32 v72, v163, v67
	v_sin_f32_e32 v71, v70
	v_cos_f32_e32 v70, v70
	v_mul_f32_e32 v72, 0.15915494, v72
	v_fract_f32_e32 v72, v72
	v_sin_f32_e32 v73, v72
	v_cos_f32_e32 v72, v72
	v_mul_f32_e32 v67, v164, v67
	v_pk_mul_f32 v[68:69], v[152:153], v[68:69] op_sel_hi:[0,1]
	v_mul_f32_e32 v67, 0.15915494, v67
	v_pk_mul_f32 v[76:77], v[62:63], v[68:69]
	v_pk_mul_f32 v[62:63], v[62:63], v[68:69] op_sel:[1,0] op_sel_hi:[0,1]
	v_fract_f32_e32 v67, v67
	v_sub_f32_e32 v76, v76, v77
	v_add_f32_e32 v62, v62, v63
	v_pk_mul_f32 v[70:71], v[152:153], v[70:71] op_sel_hi:[0,1]
	v_sin_f32_e32 v75, v67
	v_cos_f32_e32 v74, v67
	v_cvt_pk_bf16_f32 v62, v76, v62
	v_pk_mul_f32 v[76:77], v[64:65], v[70:71]
	v_pk_mul_f32 v[64:65], v[64:65], v[70:71] op_sel:[1,0] op_sel_hi:[0,1]
	v_sub_f32_e32 v63, v76, v77
	v_add_f32_e32 v64, v64, v65
	v_pk_mul_f32 v[72:73], v[152:153], v[72:73] op_sel_hi:[0,1]
	v_cvt_pk_bf16_f32 v63, v63, v64
	v_pk_mul_f32 v[64:65], v[58:59], v[72:73]
	v_pk_mul_f32 v[58:59], v[58:59], v[72:73] op_sel:[1,0] op_sel_hi:[0,1]
	v_sub_f32_e32 v64, v64, v65
	v_add_f32_e32 v58, v58, v59
	v_cvt_pk_bf16_f32 v64, v64, v58
	v_pk_mul_f32 v[58:59], v[152:153], v[74:75] op_sel_hi:[0,1]
	v_pk_mul_f32 v[74:75], v[60:61], v[58:59]
	v_pk_mul_f32 v[60:61], v[60:61], v[58:59] op_sel:[1,0] op_sel_hi:[0,1]
	v_ashrrev_i32_e32 v67, 31, v66
	v_sub_f32_e32 v65, v74, v75
	v_add_f32_e32 v60, v60, v61
	v_lshlrev_b64 v[66:67], s4, v[66:67]
	v_cvt_pk_bf16_f32 v65, v65, v60
	v_pk_mul_f32 v[60:61], v[54:55], v[68:69]
	v_pk_mul_f32 v[54:55], v[54:55], v[68:69] op_sel:[1,0] op_sel_hi:[0,1]
	v_lshl_add_u64 v[66:67], v[66:67], 1, v[156:157]
	v_sub_f32_e32 v60, v60, v61
	v_add_f32_e32 v54, v54, v55
	global_store_dwordx4 v[66:67], v[62:65], off sc1
	v_cvt_pk_bf16_f32 v54, v60, v54
	v_pk_mul_f32 v[60:61], v[56:57], v[70:71]
	v_pk_mul_f32 v[56:57], v[56:57], v[70:71] op_sel:[1,0] op_sel_hi:[0,1]
	v_sub_f32_e32 v55, v60, v61
	v_add_f32_e32 v56, v56, v57
	v_cvt_pk_bf16_f32 v55, v55, v56
	v_pk_mul_f32 v[56:57], v[50:51], v[72:73]
	v_pk_mul_f32 v[50:51], v[50:51], v[72:73] op_sel:[1,0] op_sel_hi:[0,1]
	v_sub_f32_e32 v56, v56, v57
	v_add_f32_e32 v50, v50, v51
	v_cvt_pk_bf16_f32 v56, v56, v50
	v_pk_mul_f32 v[50:51], v[52:53], v[58:59]
	s_nop 0
	v_sub_f32_e32 v57, v50, v51
	v_pk_mul_f32 v[50:51], v[52:53], v[58:59] op_sel:[1,0] op_sel_hi:[0,1]
	v_add_f32_e32 v50, v50, v51
	v_cvt_pk_bf16_f32 v57, v57, v50
	ds_read_b32 v50, v165 offset:576
	global_store_dwordx4 v[66:67], v[54:57], off offset:256 sc1
	s_waitcnt lgkmcnt(0)
	v_cvt_f32_i32_e32 v58, v50
	v_mul_f32_e32 v50, v161, v58
	v_mul_f32_e32 v50, 0.15915494, v50
	v_fract_f32_e32 v50, v50
	v_mul_f32_e32 v52, v162, v58
	v_sin_f32_e32 v51, v50
	v_cos_f32_e32 v50, v50
	v_mul_f32_e32 v52, 0.15915494, v52
	v_fract_f32_e32 v52, v52
	v_mul_f32_e32 v54, v163, v58
	v_sin_f32_e32 v53, v52
	v_cos_f32_e32 v52, v52
	v_mul_f32_e32 v54, 0.15915494, v54
	v_fract_f32_e32 v54, v54
	v_sin_f32_e32 v55, v54
	v_cos_f32_e32 v54, v54
	v_mul_f32_e32 v56, v164, v58
	v_pk_mul_f32 v[50:51], v[152:153], v[50:51] op_sel_hi:[0,1]
	v_mul_f32_e32 v56, 0.15915494, v56
	v_pk_mul_f32 v[60:61], v[46:47], v[50:51]
	v_pk_mul_f32 v[46:47], v[46:47], v[50:51] op_sel:[1,0] op_sel_hi:[0,1]
	v_fract_f32_e32 v56, v56
	v_sub_f32_e32 v60, v60, v61
	v_add_f32_e32 v46, v46, v47
	v_pk_mul_f32 v[52:53], v[152:153], v[52:53] op_sel_hi:[0,1]
	v_sin_f32_e32 v57, v56
	v_cos_f32_e32 v56, v56
	v_cvt_pk_bf16_f32 v46, v60, v46
	v_pk_mul_f32 v[60:61], v[48:49], v[52:53]
	v_pk_mul_f32 v[48:49], v[48:49], v[52:53] op_sel:[1,0] op_sel_hi:[0,1]
	v_sub_f32_e32 v47, v60, v61
	v_add_f32_e32 v48, v48, v49
	v_pk_mul_f32 v[54:55], v[152:153], v[54:55] op_sel_hi:[0,1]
	v_cvt_pk_bf16_f32 v47, v47, v48
	v_pk_mul_f32 v[48:49], v[42:43], v[54:55]
	v_pk_mul_f32 v[42:43], v[42:43], v[54:55] op_sel:[1,0] op_sel_hi:[0,1]
	v_sub_f32_e32 v48, v48, v49
	v_add_f32_e32 v42, v42, v43
	v_cvt_pk_bf16_f32 v48, v48, v42
	v_pk_mul_f32 v[42:43], v[152:153], v[56:57] op_sel_hi:[0,1]
	v_add_u32_e32 v58, 0x90, v154
	v_pk_mul_f32 v[56:57], v[44:45], v[42:43]
	v_pk_mul_f32 v[44:45], v[44:45], v[42:43] op_sel:[1,0] op_sel_hi:[0,1]
	v_ashrrev_i32_e32 v59, 31, v58
	v_sub_f32_e32 v49, v56, v57
	v_add_f32_e32 v44, v44, v45
	v_lshlrev_b64 v[58:59], s4, v[58:59]
	v_cvt_pk_bf16_f32 v49, v49, v44
	v_pk_mul_f32 v[44:45], v[38:39], v[50:51]
	v_pk_mul_f32 v[38:39], v[38:39], v[50:51] op_sel:[1,0] op_sel_hi:[0,1]
	v_lshl_add_u64 v[58:59], v[58:59], 1, v[156:157]
	v_sub_f32_e32 v44, v44, v45
	v_add_f32_e32 v38, v38, v39
	global_store_dwordx4 v[58:59], v[46:49], off sc1
	v_cvt_pk_bf16_f32 v38, v44, v38
	v_pk_mul_f32 v[44:45], v[40:41], v[52:53]
	v_pk_mul_f32 v[40:41], v[40:41], v[52:53] op_sel:[1,0] op_sel_hi:[0,1]
	v_sub_f32_e32 v39, v44, v45
	v_add_f32_e32 v40, v40, v41
	v_cvt_pk_bf16_f32 v39, v39, v40
	v_pk_mul_f32 v[40:41], v[34:35], v[54:55]
	v_pk_mul_f32 v[34:35], v[34:35], v[54:55] op_sel:[1,0] op_sel_hi:[0,1]
	v_sub_f32_e32 v40, v40, v41
	v_add_f32_e32 v34, v34, v35
	v_cvt_pk_bf16_f32 v40, v40, v34
	v_pk_mul_f32 v[34:35], v[36:37], v[42:43]
	s_nop 0
	v_sub_f32_e32 v41, v34, v35
	v_pk_mul_f32 v[34:35], v[36:37], v[42:43] op_sel:[1,0] op_sel_hi:[0,1]
	v_add_f32_e32 v34, v34, v35
	v_cvt_pk_bf16_f32 v41, v41, v34
	ds_read_b32 v34, v165 offset:640
	global_store_dwordx4 v[58:59], v[38:41], off offset:256 sc1
	s_waitcnt lgkmcnt(0)
; __device__ __forceinline__ unsigned cvt_pk_bf16(float lo, float hi) { unsigned r; asm volatile("v_cvt_pk_bf16_f32 %0, %1, %2" : "=v"(r) : "v"(lo), "v"(hi)); return r; }
;     __device__ __forceinline__ void operator()(const f32x4 (&acc)[2][2][4][2], const Unit& u, int wr, int wc, int fr, int fq) const {
;     ...
;                 for (int m = 0; m < 4; ++m) { const int row = row0 + ai * HALF + m * 16; const float p = (float)posl[wr * 64 + fr + ai * HALF + m * 16];
;                     float cs[4], sn[4];
; #pragma unroll
;                     for (int t = 0; t < 4; ++t) { const float ang = p * invf[t]; const float fr_ = __builtin_amdgcn_fractf(ang * 0.15915494309189535f); sn[t] = __builtin_amdgcn_sinf(fr_) * sc; cs[t] = __builtin_amdgcn_cosf(fr_) * sc; }
; #pragma unroll
;                     for (int bj = 0; bj < 2; ++bj) { const f32x4 v0 = acc[ai][bj][m][0], v1 = acc[ai][bj][m][1];
;                         u32x4 w;
;                         w.x = cvt_pk_bf16(v0[0] * cs[0] - v0[1] * sn[0], v0[1] * cs[0] + v0[0] * sn[0]);
;                         w.y = cvt_pk_bf16(v0[2] * cs[1] - v0[3] * sn[1], v0[3] * cs[1] + v0[2] * sn[1]);
;                         w.z = cvt_pk_bf16(v1[0] * cs[2] - v1[1] * sn[2], v1[1] * cs[2] + v1[0] * sn[2]);
;                         w.w = cvt_pk_bf16(v1[2] * cs[3] - v1[3] * sn[3], v1[3] * cs[3] + v1[2] * sn[3]);
;                         *(u32x4*)(base + (size_t)row * ld + bj * HALF + cw) = w; } }
	v_cvt_f32_i32_e32 v42, v34
	v_mul_f32_e32 v34, v161, v42
	v_mul_f32_e32 v34, 0.15915494, v34
	v_fract_f32_e32 v34, v34
	v_mul_f32_e32 v36, v162, v42
	v_sin_f32_e32 v35, v34
	v_cos_f32_e32 v34, v34
	v_mul_f32_e32 v36, 0.15915494, v36
	v_fract_f32_e32 v36, v36
	v_mul_f32_e32 v38, v163, v42
	v_sin_f32_e32 v37, v36
	v_cos_f32_e32 v36, v36
	v_mul_f32_e32 v38, 0.15915494, v38
	v_fract_f32_e32 v38, v38
	v_sin_f32_e32 v39, v38
	v_cos_f32_e32 v38, v38
	v_mul_f32_e32 v40, v164, v42
	v_pk_mul_f32 v[34:35], v[152:153], v[34:35] op_sel_hi:[0,1]
	v_mul_f32_e32 v40, 0.15915494, v40
	v_pk_mul_f32 v[44:45], v[30:31], v[34:35]
	v_pk_mul_f32 v[30:31], v[30:31], v[34:35] op_sel:[1,0] op_sel_hi:[0,1]
	v_fract_f32_e32 v40, v40
	v_sub_f32_e32 v44, v44, v45
	v_add_f32_e32 v30, v30, v31
	v_pk_mul_f32 v[36:37], v[152:153], v[36:37] op_sel_hi:[0,1]
	v_sin_f32_e32 v41, v40
	v_cos_f32_e32 v40, v40
	v_cvt_pk_bf16_f32 v30, v44, v30
	v_pk_mul_f32 v[44:45], v[32:33], v[36:37]
	v_pk_mul_f32 v[32:33], v[32:33], v[36:37] op_sel:[1,0] op_sel_hi:[0,1]
	v_sub_f32_e32 v31, v44, v45
	v_add_f32_e32 v32, v32, v33
	v_pk_mul_f32 v[38:39], v[152:153], v[38:39] op_sel_hi:[0,1]
	v_cvt_pk_bf16_f32 v31, v31, v32
	v_pk_mul_f32 v[32:33], v[26:27], v[38:39]
	v_pk_mul_f32 v[26:27], v[26:27], v[38:39] op_sel:[1,0] op_sel_hi:[0,1]
	v_sub_f32_e32 v32, v32, v33
	v_add_f32_e32 v26, v26, v27
	v_cvt_pk_bf16_f32 v32, v32, v26
	v_pk_mul_f32 v[26:27], v[152:153], v[40:41] op_sel_hi:[0,1]
	v_add_u32_e32 v42, 0xa0, v154
	v_pk_mul_f32 v[40:41], v[28:29], v[26:27]
	v_pk_mul_f32 v[28:29], v[28:29], v[26:27] op_sel:[1,0] op_sel_hi:[0,1]
	v_ashrrev_i32_e32 v43, 31, v42
	v_sub_f32_e32 v33, v40, v41
	v_add_f32_e32 v28, v28, v29
	v_lshlrev_b64 v[42:43], s4, v[42:43]
	v_cvt_pk_bf16_f32 v33, v33, v28
	v_pk_mul_f32 v[28:29], v[22:23], v[34:35]
	v_pk_mul_f32 v[22:23], v[22:23], v[34:35] op_sel:[1,0] op_sel_hi:[0,1]
	v_lshl_add_u64 v[42:43], v[42:43], 1, v[156:157]
	v_sub_f32_e32 v28, v28, v29
	v_add_f32_e32 v22, v22, v23
	global_store_dwordx4 v[42:43], v[30:33], off sc1
	v_cvt_pk_bf16_f32 v22, v28, v22
	v_pk_mul_f32 v[28:29], v[24:25], v[36:37]
	v_pk_mul_f32 v[24:25], v[24:25], v[36:37] op_sel:[1,0] op_sel_hi:[0,1]
	v_sub_f32_e32 v23, v28, v29
	v_add_f32_e32 v24, v24, v25
	v_cvt_pk_bf16_f32 v23, v23, v24
	v_pk_mul_f32 v[24:25], v[18:19], v[38:39]
	v_pk_mul_f32 v[18:19], v[18:19], v[38:39] op_sel:[1,0] op_sel_hi:[0,1]
	v_sub_f32_e32 v24, v24, v25
	v_add_f32_e32 v18, v18, v19
	v_cvt_pk_bf16_f32 v24, v24, v18
	v_pk_mul_f32 v[18:19], v[20:21], v[26:27]
	s_nop 0
	v_sub_f32_e32 v25, v18, v19
	v_pk_mul_f32 v[18:19], v[20:21], v[26:27] op_sel:[1,0] op_sel_hi:[0,1]
	v_add_f32_e32 v18, v18, v19
	v_cvt_pk_bf16_f32 v25, v25, v18
	ds_read_b32 v18, v165 offset:704
	global_store_dwordx4 v[42:43], v[22:25], off offset:256 sc1
	s_waitcnt lgkmcnt(0)
	v_cvt_f32_i32_e32 v26, v18
	v_mul_f32_e32 v18, v161, v26
	v_mul_f32_e32 v18, 0.15915494, v18
	v_fract_f32_e32 v18, v18
	v_mul_f32_e32 v20, v162, v26
	v_sin_f32_e32 v19, v18
	v_cos_f32_e32 v18, v18
	v_mul_f32_e32 v20, 0.15915494, v20
	v_fract_f32_e32 v20, v20
	v_mul_f32_e32 v22, v163, v26
	v_sin_f32_e32 v21, v20
	v_cos_f32_e32 v20, v20
	v_mul_f32_e32 v22, 0.15915494, v22
	v_fract_f32_e32 v22, v22
	v_sin_f32_e32 v23, v22
	v_cos_f32_e32 v22, v22
	v_mul_f32_e32 v24, v164, v26
	v_pk_mul_f32 v[18:19], v[152:153], v[18:19] op_sel_hi:[0,1]
	v_mul_f32_e32 v24, 0.15915494, v24
	v_pk_mul_f32 v[28:29], v[14:15], v[18:19]
	v_pk_mul_f32 v[14:15], v[14:15], v[18:19] op_sel:[1,0] op_sel_hi:[0,1]
	v_fract_f32_e32 v24, v24
	v_sub_f32_e32 v28, v28, v29
	v_add_f32_e32 v14, v14, v15
	v_pk_mul_f32 v[20:21], v[152:153], v[20:21] op_sel_hi:[0,1]
	v_sin_f32_e32 v25, v24
	v_cos_f32_e32 v24, v24
	v_cvt_pk_bf16_f32 v14, v28, v14
	v_pk_mul_f32 v[28:29], v[16:17], v[20:21]
	v_pk_mul_f32 v[16:17], v[16:17], v[20:21] op_sel:[1,0] op_sel_hi:[0,1]
	v_sub_f32_e32 v15, v28, v29
	v_add_f32_e32 v16, v16, v17
	v_pk_mul_f32 v[22:23], v[152:153], v[22:23] op_sel_hi:[0,1]
	v_cvt_pk_bf16_f32 v15, v15, v16
	v_pk_mul_f32 v[16:17], v[10:11], v[22:23]
	v_pk_mul_f32 v[10:11], v[10:11], v[22:23] op_sel:[1,0] op_sel_hi:[0,1]
	v_sub_f32_e32 v16, v16, v17
	v_add_f32_e32 v10, v10, v11
	v_cvt_pk_bf16_f32 v16, v16, v10
	v_pk_mul_f32 v[10:11], v[152:153], v[24:25] op_sel_hi:[0,1]
	v_add_u32_e32 v26, 0xb0, v154
	v_pk_mul_f32 v[24:25], v[12:13], v[10:11]
	v_pk_mul_f32 v[12:13], v[12:13], v[10:11] op_sel:[1,0] op_sel_hi:[0,1]
	v_ashrrev_i32_e32 v27, 31, v26
	v_sub_f32_e32 v17, v24, v25
	v_add_f32_e32 v12, v12, v13
	v_lshlrev_b64 v[26:27], s4, v[26:27]
	v_cvt_pk_bf16_f32 v17, v17, v12
	v_pk_mul_f32 v[12:13], v[6:7], v[18:19]
	v_pk_mul_f32 v[6:7], v[6:7], v[18:19] op_sel:[1,0] op_sel_hi:[0,1]
	v_lshl_add_u64 v[26:27], v[26:27], 1, v[156:157]
	v_sub_f32_e32 v12, v12, v13
	v_add_f32_e32 v6, v6, v7
	global_store_dwordx4 v[26:27], v[14:17], off sc1
	v_cvt_pk_bf16_f32 v6, v12, v6
	v_pk_mul_f32 v[12:13], v[8:9], v[20:21]
	v_pk_mul_f32 v[8:9], v[8:9], v[20:21] op_sel:[1,0] op_sel_hi:[0,1]
	v_sub_f32_e32 v7, v12, v13
	v_add_f32_e32 v8, v8, v9
	v_cvt_pk_bf16_f32 v7, v7, v8
	v_pk_mul_f32 v[8:9], v[2:3], v[22:23]
	v_pk_mul_f32 v[2:3], v[2:3], v[22:23] op_sel:[1,0] op_sel_hi:[0,1]
	v_sub_f32_e32 v8, v8, v9
	v_add_f32_e32 v2, v2, v3
	v_cvt_pk_bf16_f32 v8, v8, v2
	v_pk_mul_f32 v[2:3], v[4:5], v[10:11]
	s_nop 0
	v_sub_f32_e32 v9, v2, v3
	v_pk_mul_f32 v[2:3], v[4:5], v[10:11] op_sel:[1,0] op_sel_hi:[0,1]
	v_add_f32_e32 v2, v2, v3
	v_cvt_pk_bf16_f32 v9, v9, v2
	global_store_dwordx4 v[26:27], v[6:9], off offset:256 sc1
	s_andn2_b64 vcc, exec, s[0:1]
	s_mov_b64 s[0:1], -1
	s_cbranch_vccnz .LBB0_399

; __device__ __forceinline__ unsigned cvt_pk_bf16(float lo, float hi) { unsigned r; asm volatile("v_cvt_pk_bf16_f32 %0, %1, %2" : "=v"(r) : "v"(lo), "v"(hi)); return r; }
;     __device__ __forceinline__ void operator()(const f32x4 (&acc)[2][2][4][2], const Unit& u, int wr, int wc, int fr, int fq) const {
;     ...
;             for (int m = 0; m < 4; ++m) { bf16_t* rowp = O + (size_t)(row0 + ai * HALF + m * 16) * ldc + col0;
; #pragma unroll
;                 for (int bj = 0; bj < 2; ++bj) { const f32x4 v0 = acc[ai][bj][m][0], v1 = acc[ai][bj][m][1];
;                     u32x4 w; w.x = cvt_pk_bf16(v0[0], v0[1]); w.y = cvt_pk_bf16(v0[2], v0[3]); w.z = cvt_pk_bf16(v1[0], v1[1]); w.w = cvt_pk_bf16(v1[2], v1[3]);
;                     *(u32x4*)(rowp + bj * HALF) = w; } }
.LBB0_434:
	v_lshl_add_u32 v150, s28, 8, v144
	v_lshl_or_b32 v142, s53, 8, v146
	v_ashrrev_i32_e32 v151, 31, v150
	v_ashrrev_i32_e32 v143, 31, v142
	v_lshlrev_b64 v[152:153], 15, v[150:151]
	v_lshl_add_u64 v[152:153], s[6:7], 0, v[152:153]
	v_lshlrev_b64 v[154:155], 1, v[142:143]
	v_lshl_add_u64 v[142:143], v[152:153], 0, v[154:155]
	v_cvt_pk_bf16_f32 v126, v126, v127
	v_cvt_pk_bf16_f32 v127, v128, v129
	v_cvt_pk_bf16_f32 v128, v122, v123
	v_cvt_pk_bf16_f32 v129, v124, v125
	global_store_dwordx4 v[142:143], v[126:129], off sc1
	v_cvt_pk_bf16_f32 v114, v114, v115
	v_cvt_pk_bf16_f32 v115, v116, v117
	v_cvt_pk_bf16_f32 v116, v106, v107
	v_or_b32_e32 v106, 16, v150
	v_ashrrev_i32_e32 v107, 31, v106
	v_lshlrev_b64 v[106:107], 15, v[106:107]
	v_lshl_add_u64 v[106:107], s[6:7], 0, v[106:107]
	v_cvt_pk_bf16_f32 v117, v108, v109
	global_store_dwordx4 v[142:143], v[114:117], off offset:256 sc1
	s_mov_b64 s[30:31], 0x400000
	s_nop 0
	v_lshl_add_u64 v[114:115], v[106:107], 0, v[154:155]
	v_cvt_pk_bf16_f32 v106, v118, v119
	v_cvt_pk_bf16_f32 v107, v120, v121
	v_cvt_pk_bf16_f32 v108, v110, v111
	v_cvt_pk_bf16_f32 v109, v112, v113
	global_store_dwordx4 v[114:115], v[106:109], off sc1
	v_cvt_pk_bf16_f32 v98, v98, v99
	v_cvt_pk_bf16_f32 v99, v100, v101
	v_cvt_pk_bf16_f32 v100, v90, v91
	v_or_b32_e32 v90, 32, v150
	v_ashrrev_i32_e32 v91, 31, v90
	v_lshlrev_b64 v[90:91], 15, v[90:91]
	v_lshl_add_u64 v[90:91], s[6:7], 0, v[90:91]
	v_cvt_pk_bf16_f32 v101, v92, v93
	global_store_dwordx4 v[114:115], v[98:101], off offset:256 sc1
	s_nop 1
	v_lshl_add_u64 v[98:99], v[90:91], 0, v[154:155]
	v_cvt_pk_bf16_f32 v90, v102, v103
	v_cvt_pk_bf16_f32 v91, v104, v105
	v_cvt_pk_bf16_f32 v92, v94, v95
	v_cvt_pk_bf16_f32 v93, v96, v97
	global_store_dwordx4 v[98:99], v[90:93], off sc1
	v_cvt_pk_bf16_f32 v82, v82, v83
	v_cvt_pk_bf16_f32 v83, v84, v85
	v_cvt_pk_bf16_f32 v84, v74, v75
	v_or_b32_e32 v74, 48, v150
	v_ashrrev_i32_e32 v75, 31, v74
	v_lshlrev_b64 v[74:75], 15, v[74:75]
	v_lshl_add_u64 v[74:75], s[6:7], 0, v[74:75]
	v_cvt_pk_bf16_f32 v85, v76, v77
	global_store_dwordx4 v[98:99], v[82:85], off offset:256 sc1
	s_nop 1
	v_lshl_add_u64 v[82:83], v[74:75], 0, v[154:155]
	v_cvt_pk_bf16_f32 v74, v86, v87
	v_cvt_pk_bf16_f32 v75, v88, v89
	v_cvt_pk_bf16_f32 v76, v78, v79
	v_cvt_pk_bf16_f32 v77, v80, v81
	global_store_dwordx4 v[82:83], v[74:77], off sc1
	v_cvt_pk_bf16_f32 v70, v70, v71
	v_cvt_pk_bf16_f32 v71, v72, v73
	v_cvt_pk_bf16_f32 v72, v66, v67
	v_cvt_pk_bf16_f32 v73, v68, v69
	global_store_dwordx4 v[82:83], v[70:73], off offset:256 sc1
	v_cvt_pk_bf16_f32 v62, v62, v63
	v_cvt_pk_bf16_f32 v63, v64, v65
	v_cvt_pk_bf16_f32 v64, v58, v59
	v_add_co_u32_e32 v58, vcc, s49, v142
	v_lshl_add_u64 v[66:67], v[142:143], 0, s[30:31]
	s_nop 0
	v_addc_co_u32_e32 v59, vcc, 0, v143, vcc
	v_cvt_pk_bf16_f32 v65, v60, v61
	global_store_dwordx4 v[58:59], v[62:65], off sc1
	v_cvt_pk_bf16_f32 v50, v50, v51
	v_cvt_pk_bf16_f32 v51, v52, v53
	v_cvt_pk_bf16_f32 v52, v42, v43
	v_cvt_pk_bf16_f32 v53, v44, v45
	global_store_dwordx4 v[66:67], v[50:53], off offset:256 sc1
	v_cvt_pk_bf16_f32 v42, v54, v55
	v_cvt_pk_bf16_f32 v43, v56, v57
	v_cvt_pk_bf16_f32 v44, v46, v47
	v_add_co_u32_e32 v46, vcc, s50, v142
	s_nop 0
	v_lshl_add_u64 v[50:51], v[142:143], 0, s[12:13]
	v_addc_co_u32_e32 v47, vcc, 0, v143, vcc
	v_cvt_pk_bf16_f32 v45, v48, v49
	global_store_dwordx4 v[46:47], v[42:45], off sc1
	v_cvt_pk_bf16_f32 v34, v34, v35
	v_cvt_pk_bf16_f32 v35, v36, v37
	v_cvt_pk_bf16_f32 v36, v26, v27
	v_cvt_pk_bf16_f32 v37, v28, v29
	global_store_dwordx4 v[50:51], v[34:37], off offset:256 sc1
	v_cvt_pk_bf16_f32 v26, v38, v39
	v_cvt_pk_bf16_f32 v27, v40, v41
	v_cvt_pk_bf16_f32 v28, v30, v31
	v_add_co_u32_e32 v30, vcc, s51, v142
	s_nop 0
	v_lshl_add_u64 v[34:35], v[142:143], 0, s[14:15]
	v_addc_co_u32_e32 v31, vcc, 0, v143, vcc
	v_cvt_pk_bf16_f32 v29, v32, v33
	global_store_dwordx4 v[30:31], v[26:29], off sc1
	v_cvt_pk_bf16_f32 v18, v18, v19
	v_cvt_pk_bf16_f32 v19, v20, v21
	v_cvt_pk_bf16_f32 v20, v10, v11
	v_cvt_pk_bf16_f32 v21, v12, v13
	global_store_dwordx4 v[34:35], v[18:21], off offset:256 sc1
	v_cvt_pk_bf16_f32 v10, v22, v23
	v_cvt_pk_bf16_f32 v11, v24, v25
	v_cvt_pk_bf16_f32 v12, v14, v15
	v_add_co_u32_e32 v14, vcc, s52, v142
	s_nop 0
	v_lshl_add_u64 v[18:19], v[142:143], 0, s[16:17]
	v_addc_co_u32_e32 v15, vcc, 0, v143, vcc
	s_andn2_b64 vcc, exec, s[18:19]
	s_mov_b64 s[18:19], -1
	v_cvt_pk_bf16_f32 v13, v16, v17
	global_store_dwordx4 v[14:15], v[10:13], off sc1
	v_cvt_pk_bf16_f32 v6, v6, v7
	v_cvt_pk_bf16_f32 v7, v8, v9
	v_cvt_pk_bf16_f32 v8, v2, v3
	v_cvt_pk_bf16_f32 v9, v4, v5
	global_store_dwordx4 v[18:19], v[6:9], off offset:256 sc1
	s_cbranch_vccnz .LBB0_423
	s_andn2_b64 vcc, exec, s[0:1]
	s_cbranch_vccnz .LBB0_422
	s_barrier
	s_branch .LBB0_422

; __device__ __forceinline__ unsigned cvt_pk_bf16(float lo, float hi) { unsigned r; asm volatile("v_cvt_pk_bf16_f32 %0, %1, %2" : "=v"(r) : "v"(lo), "v"(hi)); return r; }
; #define LAS __attribute__((address_space(3)))
; __device__ __forceinline__ int map_row_rt(int mode, int n) {
;     if (mode == MAP_WIN) return map_row<MAP_WIN>(n);
;     if (mode == MAP_GATE) return map_row<MAP_GATE>(n);
;     if (mode == MAP_UP) return map_row<MAP_UP>(n);
;     return n;
; __device__ __forceinline__ void tr_finish(const TrDesc& d, const TrRegs& t, LAS float* scr, int lane) {
;     ...
;     for (int j = 0; j < 4; ++j) { const int n = (lane >> 3) + 8 * j; const LAS float* s = scr + (8 * c) * 33 + n;
;         v4u o; o.x = cvt_pk_bf16(s[0 * 33] * t.g0.x, s[1 * 33] * t.g0.y); o.y = cvt_pk_bf16(s[2 * 33] * t.g0.z, s[3 * 33] * t.g0.w); o.z = cvt_pk_bf16(s[4 * 33] * t.g1.x, s[5 * 33] * t.g1.y); o.w = cvt_pk_bf16(s[6 * 33] * t.g1.z, s[7 * 33] * t.g1.w);
;         *(v4u*)(d.WT + (size_t)map_row_rt(d.mode, n0 + n) * d.K + k0 + 8 * c) = o; }
.LBB0_501:
	ds_read2_b32 v[102:103], v66 offset0:8 offset1:41
	s_lshl_b32 s16, s20, 6
	v_mad_i64_i32 v[12:13], s[18:19], v12, s26, 0
	s_ashr_i32 s17, s16, 31
	v_lshl_add_u64 v[12:13], v[12:13], 1, s[6:7]
	v_lshl_add_u64 v[12:13], s[16:17], 1, v[12:13]
	v_mov_b32_e32 v31, v27
	v_lshl_add_u64 v[12:13], v[12:13], 0, v[30:31]
	global_store_dwordx4 v[12:13], v[22:25], off sc1
	s_waitcnt lgkmcnt(0)
	v_mul_f32_e32 v12, v3, v103
	v_mul_f32_e32 v11, v2, v102
	v_cvt_pk_bf16_f32 v22, v11, v12
	ds_read2_b32 v[12:13], v66 offset0:74 offset1:107
	s_cmp_lt_i32 s25, 2
	s_mov_b64 s[18:19], -1
	s_waitcnt lgkmcnt(0)
	v_mul_f32_e32 v11, v4, v12
	v_mul_f32_e32 v12, v5, v13
	v_cvt_pk_bf16_f32 v23, v11, v12
	ds_read2_b32 v[12:13], v66 offset0:140 offset1:173
	s_waitcnt lgkmcnt(0)
	v_mul_f32_e32 v11, v6, v12
	v_mul_f32_e32 v12, v7, v13
	v_cvt_pk_bf16_f32 v24, v11, v12
	ds_read2_b32 v[12:13], v66 offset0:206 offset1:239
	s_waitcnt lgkmcnt(0)
	v_mul_f32_e32 v11, v8, v12
	v_mul_f32_e32 v12, v9, v13
	v_cvt_pk_bf16_f32 v25, v11, v12
	v_or_b32_e32 v11, s30, v67
	s_cbranch_scc1 .LBB0_509
	s_cmp_lt_i32 s25, 3
	s_cbranch_scc1 .LBB0_506
	s_cmp_eq_u32 s25, 3
	v_mov_b32_e32 v12, v11
	s_cbranch_scc0 .LBB0_505
	v_and_b32_e32 v12, 0x6f, v11
	v_or_b32_e32 v12, s34, v12
	v_or_b32_e32 v12, 0x80, v12

; __device__ __forceinline__ unsigned cvt_pk_bf16(float lo, float hi) { unsigned r; asm volatile("v_cvt_pk_bf16_f32 %0, %1, %2" : "=v"(r) : "v"(lo), "v"(hi)); return r; }
; #define LAS __attribute__((address_space(3)))
; __device__ __forceinline__ int map_row_rt(int mode, int n) {
;     if (mode == MAP_WIN) return map_row<MAP_WIN>(n);
;     if (mode == MAP_GATE) return map_row<MAP_GATE>(n);
;     if (mode == MAP_UP) return map_row<MAP_UP>(n);
;     return n;
; __device__ __forceinline__ void tr_finish(const TrDesc& d, const TrRegs& t, LAS float* scr, int lane) {
;     ...
;     for (int j = 0; j < 4; ++j) { const int n = (lane >> 3) + 8 * j; const LAS float* s = scr + (8 * c) * 33 + n;
;         v4u o; o.x = cvt_pk_bf16(s[0 * 33] * t.g0.x, s[1 * 33] * t.g0.y); o.y = cvt_pk_bf16(s[2 * 33] * t.g0.z, s[3 * 33] * t.g0.w); o.z = cvt_pk_bf16(s[4 * 33] * t.g1.x, s[5 * 33] * t.g1.y); o.w = cvt_pk_bf16(s[6 * 33] * t.g1.z, s[7 * 33] * t.g1.w);
;         *(v4u*)(d.WT + (size_t)map_row_rt(d.mode, n0 + n) * d.K + k0 + 8 * c) = o; }
.LBB0_521:
	ds_read2_b32 v[102:103], v66 offset0:16 offset1:49
	v_mad_i64_i32 v[12:13], s[18:19], v12, s26, 0
	v_lshl_add_u64 v[12:13], v[12:13], 1, s[6:7]
	v_lshl_add_u64 v[12:13], s[16:17], 1, v[12:13]
	v_mov_b32_e32 v31, v27
	v_lshl_add_u64 v[12:13], v[12:13], 0, v[30:31]
	global_store_dwordx4 v[12:13], v[22:25], off sc1
	s_waitcnt lgkmcnt(0)
	v_mul_f32_e32 v12, v3, v103
	v_mul_f32_e32 v11, v2, v102
	v_cvt_pk_bf16_f32 v22, v11, v12
	ds_read2_b32 v[12:13], v66 offset0:82 offset1:115
	s_cmp_lt_i32 s25, 2
	s_mov_b64 s[18:19], -1
	s_waitcnt lgkmcnt(0)
	v_mul_f32_e32 v11, v4, v12
	v_mul_f32_e32 v12, v5, v13
	v_cvt_pk_bf16_f32 v23, v11, v12
	ds_read2_b32 v[12:13], v66 offset0:148 offset1:181
	s_waitcnt lgkmcnt(0)
	v_mul_f32_e32 v11, v6, v12
	v_mul_f32_e32 v12, v7, v13
	v_cvt_pk_bf16_f32 v24, v11, v12
	ds_read2_b32 v[12:13], v66 offset0:214 offset1:247
	s_waitcnt lgkmcnt(0)
	v_mul_f32_e32 v11, v8, v12
	v_mul_f32_e32 v12, v9, v13
	v_cvt_pk_bf16_f32 v25, v11, v12
	v_or_b32_e32 v11, s30, v68
	s_cbranch_scc1 .LBB0_529
	s_cmp_lt_i32 s25, 3
	s_cbranch_scc1 .LBB0_526
	s_cmp_eq_u32 s25, 3
	v_mov_b32_e32 v12, v11
	s_cbranch_scc0 .LBB0_525
	v_and_b32_e32 v12, 0x77, v11
	v_or_b32_e32 v12, s34, v12
	v_or_b32_e32 v12, 0x80, v12

; __device__ __forceinline__ unsigned cvt_pk_bf16(float lo, float hi) { unsigned r; asm volatile("v_cvt_pk_bf16_f32 %0, %1, %2" : "=v"(r) : "v"(lo), "v"(hi)); return r; }
; #define LAS __attribute__((address_space(3)))
; __device__ __forceinline__ int map_row_rt(int mode, int n) {
;     if (mode == MAP_WIN) return map_row<MAP_WIN>(n);
;     if (mode == MAP_GATE) return map_row<MAP_GATE>(n);
;     if (mode == MAP_UP) return map_row<MAP_UP>(n);
;     return n;
; __device__ __forceinline__ void tr_finish(const TrDesc& d, const TrRegs& t, LAS float* scr, int lane) {
;     ...
;     for (int j = 0; j < 4; ++j) { const int n = (lane >> 3) + 8 * j; const LAS float* s = scr + (8 * c) * 33 + n;
;         v4u o; o.x = cvt_pk_bf16(s[0 * 33] * t.g0.x, s[1 * 33] * t.g0.y); o.y = cvt_pk_bf16(s[2 * 33] * t.g0.z, s[3 * 33] * t.g0.w); o.z = cvt_pk_bf16(s[4 * 33] * t.g1.x, s[5 * 33] * t.g1.y); o.w = cvt_pk_bf16(s[6 * 33] * t.g1.z, s[7 * 33] * t.g1.w);
;         *(v4u*)(d.WT + (size_t)map_row_rt(d.mode, n0 + n) * d.K + k0 + 8 * c) = o; }
.LBB0_541:
	ds_read2_b32 v[102:103], v66 offset0:24 offset1:57
	v_mad_i64_i32 v[12:13], s[18:19], v12, s26, 0
	v_lshl_add_u64 v[12:13], v[12:13], 1, s[6:7]
	v_lshl_add_u64 v[12:13], s[16:17], 1, v[12:13]
	v_mov_b32_e32 v31, v27
	v_lshl_add_u64 v[12:13], v[12:13], 0, v[30:31]
	global_store_dwordx4 v[12:13], v[22:25], off sc1
	s_waitcnt lgkmcnt(0)
	v_mul_f32_e32 v12, v3, v103
	v_mul_f32_e32 v11, v2, v102
	v_cvt_pk_bf16_f32 v22, v11, v12
	ds_read2_b32 v[12:13], v66 offset0:90 offset1:123
	s_cmp_lt_i32 s25, 2
	s_mov_b64 s[18:19], -1
	s_waitcnt lgkmcnt(0)
	v_mul_f32_e32 v11, v4, v12
	v_mul_f32_e32 v12, v5, v13
	v_cvt_pk_bf16_f32 v23, v11, v12
	ds_read2_b32 v[12:13], v66 offset0:156 offset1:189
	s_waitcnt lgkmcnt(0)
	v_mul_f32_e32 v11, v6, v12
	v_mul_f32_e32 v12, v7, v13
	v_cvt_pk_bf16_f32 v24, v11, v12
	ds_read2_b32 v[12:13], v66 offset0:222 offset1:255
	s_waitcnt lgkmcnt(0)
	v_mul_f32_e32 v11, v8, v12
	v_mul_f32_e32 v12, v9, v13
	v_cvt_pk_bf16_f32 v25, v11, v12
	v_or_b32_e32 v11, s30, v69
	s_cbranch_scc1 .LBB0_549
	s_cmp_lt_i32 s25, 3
	s_cbranch_scc1 .LBB0_546
	s_cmp_eq_u32 s25, 3
	v_mov_b32_e32 v12, v11
	s_cbranch_scc0 .LBB0_545
	v_and_b32_e32 v12, 0x7f, v11
	v_or_b32_e32 v12, s34, v12
	v_or_b32_e32 v12, 0x80, v12

; __device__ __forceinline__ unsigned cvt_pk_bf16(float lo, float hi) { unsigned r; asm volatile("v_cvt_pk_bf16_f32 %0, %1, %2" : "=v"(r) : "v"(lo), "v"(hi)); return r; }
; #define LAS __attribute__((address_space(3)))
; __device__ __forceinline__ void tr_finish(const TrDesc& d, const TrRegs& t, LAS float* scr, int lane) {
;     ...
;     for (int j = 0; j < 4; ++j) { const int n = (lane >> 3) + 8 * j; const LAS float* s = scr + (8 * c) * 33 + n;
;         v4u o; o.x = cvt_pk_bf16(s[0 * 33] * t.g0.x, s[1 * 33] * t.g0.y); o.y = cvt_pk_bf16(s[2 * 33] * t.g0.z, s[3 * 33] * t.g0.w); o.z = cvt_pk_bf16(s[4 * 33] * t.g1.x, s[5 * 33] * t.g1.y); o.w = cvt_pk_bf16(s[6 * 33] * t.g1.z, s[7 * 33] * t.g1.w);
;         *(v4u*)(d.WT + (size_t)map_row_rt(d.mode, n0 + n) * d.K + k0 + 8 * c) = o; }
; __global__ void __launch_bounds__(NWAVES * 64, 2) hymba_fwd(Args a) {
;     ...
;             while (it < it_hi) {
;                 const int nx = it + NCWx; const bool more = nx < it_hi;
;                 if (more) { FFN_DESC(dn, nx); tr_load(dn, lane, tn); }
;                 tr_finish(dc, tc, scr, lane);
;                 if (more) { dc = dn; tc = tn; }
;                 it = nx;
.LBB0_561:
	v_mad_i64_i32 v[12:13], s[18:19], v12, s26, 0
	v_lshl_add_u64 v[12:13], v[12:13], 1, s[6:7]
	v_lshl_add_u64 v[12:13], s[16:17], 1, v[12:13]
	v_mov_b32_e32 v31, v27
	v_lshl_add_u64 v[12:13], v[12:13], 0, v[30:31]
	global_store_dwordx4 v[12:13], v[22:25], off sc1
	s_waitcnt lgkmcnt(0)
	s_andn2_b64 vcc, exec, s[14:15]
	s_cbranch_vccnz .LBB0_463
	v_mov_b64_e32 v[6:7], v[18:19]
	v_mov_b64_e32 v[2:3], v[14:15]
	s_mov_b32 s24, s27
	s_mov_b32 s25, s28
	s_mov_b32 s0, s8
	s_mov_b32 s26, s29
	s_mov_b64 s[6:7], s[10:11]
	v_mov_b64_e32 v[8:9], v[20:21]
	v_mov_b64_e32 v[4:5], v[16:17]
	v_mov_b32_e32 v62, v101
	v_mov_b32_e32 v61, v100
	v_mov_b32_e32 v60, v99
	v_mov_b32_e32 v59, v98
	v_mov_b32_e32 v58, v97
	v_mov_b32_e32 v57, v96
	v_mov_b32_e32 v56, v95
	v_mov_b32_e32 v55, v94
	v_mov_b32_e32 v54, v93
	v_mov_b32_e32 v53, v92
	v_mov_b32_e32 v52, v91
	v_mov_b32_e32 v51, v90
	v_mov_b32_e32 v50, v89
	v_mov_b32_e32 v49, v88
	v_mov_b32_e32 v48, v87
	v_mov_b32_e32 v47, v86
	v_mov_b32_e32 v46, v85
	v_mov_b32_e32 v45, v84
	v_mov_b32_e32 v44, v83
	v_mov_b32_e32 v43, v82
	v_mov_b32_e32 v42, v81
	v_mov_b32_e32 v41, v80
	v_mov_b32_e32 v40, v79
	v_mov_b32_e32 v39, v78
	v_mov_b32_e32 v38, v77
	v_mov_b32_e32 v37, v76
	v_mov_b32_e32 v36, v75
	v_mov_b32_e32 v35, v74
	v_mov_b32_e32 v34, v73
	v_mov_b32_e32 v33, v72
	v_mov_b32_e32 v32, v71
	v_mov_b32_e32 v29, v70
	s_branch .LBB0_463

; __device__ __forceinline__ unsigned cvt_pk_bf16(float lo, float hi) { unsigned r; asm volatile("v_cvt_pk_bf16_f32 %0, %1, %2" : "=v"(r) : "v"(lo), "v"(hi)); return r; }
; __device__ __forceinline__ float gelu_tanh(float x) { const float u = 1.5957691216057308f * (x + 0.044715f * x * x * x); return x * sigmoidf_(u); }
; __device__ __forceinline__ float sigmoidf_(float x) { return __builtin_amdgcn_rcpf(1.0f + __builtin_amdgcn_exp2f(-1.4426950408889634f * x)); }
;     __device__ __forceinline__ void operator()(const f32x4 (&acc)[2][2][4][2], const Unit& u, int wr, int wc, int fr, int fq) const {
;     ...
;                 for (int bj = 0; bj < 2; ++bj) { const f32x4 v0 = acc[ai][bj][m][0], v1 = acc[ai][bj][m][1];
;                     const int j = 8 * bj + 2 * wc + (fq >> 1), p0 = 8 * (fq & 1);
;                     u32x4 w; w.x = cvt_pk_bf16(gelu_tanh(v0[0]), gelu_tanh(v0[1])); w.y = cvt_pk_bf16(gelu_tanh(v0[2]), gelu_tanh(v0[3]));
;                     w.z = cvt_pk_bf16(gelu_tanh(v1[0]), gelu_tanh(v1[1])); w.w = cvt_pk_bf16(gelu_tanh(v1[2]), gelu_tanh(v1[3]));
;                     *(u32x4*)(Zb + (size_t)g * (16384 * 16) + (size_t)(bc * 16 + j) * 16 + p0) = w; asm volatile("" ::: "memory"); } }
.LBB0_650:
	v_mul_f32_e32 v140, 0x3d372713, v128
	v_mul_f32_e32 v143, 0x3d372713, v129
	v_mul_f32_e32 v140, v128, v140
	v_mul_f32_e32 v143, v129, v143
	v_fma_f32 v140, v128, v140, v128
	v_fma_f32 v143, v129, v143, v129
	v_mul_f32_e32 v140, 0x3fcc422a, v140
	v_mul_f32_e32 v143, 0x3fcc422a, v143
	v_mul_f32_e32 v140, 0xbfb8aa3b, v140
	v_mul_f32_e32 v143, 0xbfb8aa3b, v143
	v_exp_f32_e32 v140, v140
	v_exp_f32_e32 v143, v143
	v_mul_f32_e32 v151, 0x3d372713, v130
	v_mul_f32_e32 v151, v130, v151
	v_add_f32_e32 v140, 1.0, v140
	v_add_f32_e32 v143, 1.0, v143
	v_rcp_f32_e32 v140, v140
	v_rcp_f32_e32 v143, v143
	v_fma_f32 v151, v130, v151, v130
	v_mul_f32_e32 v151, 0x3fcc422a, v151
	v_mul_f32_e32 v151, 0xbfb8aa3b, v151
	v_exp_f32_e32 v151, v151
	v_mul_f32_e32 v128, v128, v140
	v_mul_f32_e32 v129, v129, v143
	v_mul_f32_e32 v140, 0x3d372713, v131
	v_mul_f32_e32 v143, 0x3d372713, v124
	v_mul_f32_e32 v140, v131, v140
	v_mul_f32_e32 v143, v124, v143
	v_fma_f32 v140, v131, v140, v131
	v_fma_f32 v143, v124, v143, v124
	v_mul_f32_e32 v140, 0x3fcc422a, v140
	v_mul_f32_e32 v143, 0x3fcc422a, v143
	v_cvt_pk_bf16_f32 v128, v128, v129
	v_add_f32_e32 v129, 1.0, v151
	v_mul_f32_e32 v140, 0xbfb8aa3b, v140
	v_mul_f32_e32 v143, 0xbfb8aa3b, v143
	v_rcp_f32_e32 v129, v129
	v_exp_f32_e32 v140, v140
	v_exp_f32_e32 v143, v143
	s_ashr_i32 s7, s6, 31
	v_mul_f32_e32 v129, v130, v129
	v_add_f32_e32 v130, 1.0, v140
	v_add_f32_e32 v140, 1.0, v143
	v_rcp_f32_e32 v130, v130
	v_rcp_f32_e32 v140, v140
	v_mul_f32_e32 v143, 0x3d372713, v125
	v_mul_f32_e32 v143, v125, v143
	v_mul_f32_e32 v130, v131, v130
	v_mul_f32_e32 v124, v124, v140
	v_mul_f32_e32 v131, 0x3d372713, v126
	v_mul_f32_e32 v140, 0x3d372713, v127
	v_fma_f32 v143, v125, v143, v125
	v_mul_f32_e32 v131, v126, v131
	v_mul_f32_e32 v140, v127, v140
	v_mul_f32_e32 v143, 0x3fcc422a, v143
	v_fma_f32 v131, v126, v131, v126
	v_fma_f32 v140, v127, v140, v127
	v_mul_f32_e32 v143, 0xbfb8aa3b, v143
	v_mul_f32_e32 v131, 0x3fcc422a, v131
	v_mul_f32_e32 v140, 0x3fcc422a, v140
	v_exp_f32_e32 v143, v143
	v_mul_f32_e32 v131, 0xbfb8aa3b, v131
	v_mul_f32_e32 v140, 0xbfb8aa3b, v140
	v_exp_f32_e32 v131, v131
	v_exp_f32_e32 v140, v140
	v_cvt_pk_bf16_f32 v129, v129, v130
	v_add_f32_e32 v130, 1.0, v143
	v_rcp_f32_e32 v130, v130
	v_add_f32_e32 v131, 1.0, v131
	v_add_f32_e32 v140, 1.0, v140
	v_rcp_f32_e32 v131, v131
	v_rcp_f32_e32 v140, v140
	v_mul_f32_e32 v125, v125, v130
	v_cvt_pk_bf16_f32 v130, v124, v125
	v_mul_f32_e32 v124, v126, v131
	v_mul_f32_e32 v125, v127, v140
	v_mul_f32_e32 v126, 0x3d372713, v120
	v_mul_f32_e32 v127, 0x3d372713, v121
	v_mul_f32_e32 v126, v120, v126
	v_mul_f32_e32 v127, v121, v127
	v_fma_f32 v126, v120, v126, v120
	v_fma_f32 v127, v121, v127, v121
	v_mul_f32_e32 v126, 0x3fcc422a, v126
	v_mul_f32_e32 v127, 0x3fcc422a, v127
	s_lshl_b64 s[6:7], s[6:7], 19
	v_mul_f32_e32 v126, 0xbfb8aa3b, v126
	v_mul_f32_e32 v127, 0xbfb8aa3b, v127
	v_and_or_b32 v150, v145, s56, v144
	s_add_u32 s6, s80, s6
	v_exp_f32_e32 v126, v126
	v_exp_f32_e32 v127, v127
	s_addc_u32 s7, s81, s7
	v_lshlrev_b32_e32 v140, 5, v150
	v_cvt_pk_bf16_f32 v131, v124, v125
	v_lshl_add_u64 v[124:125], s[6:7], 0, v[140:141]
	v_mov_b32_e32 v143, v141
	v_lshl_add_u64 v[124:125], v[124:125], 0, v[142:143]
	global_store_dwordx4 v[124:125], v[128:131], off sc1
	v_add_f32_e32 v126, 1.0, v126
	v_add_f32_e32 v127, 1.0, v127
	v_mul_f32_e32 v128, 0x3d372713, v122
	v_rcp_f32_e32 v126, v126
	v_rcp_f32_e32 v127, v127
	v_mul_f32_e32 v128, v122, v128
	v_fma_f32 v128, v122, v128, v122
	v_mul_f32_e32 v128, 0x3fcc422a, v128
	v_mul_f32_e32 v128, 0xbfb8aa3b, v128
	v_exp_f32_e32 v128, v128
	v_mul_f32_e32 v120, v120, v126
	v_mul_f32_e32 v121, v121, v127
	v_mul_f32_e32 v126, 0x3d372713, v123
	v_mul_f32_e32 v127, 0x3d372713, v116
	v_mul_f32_e32 v126, v123, v126
	v_mul_f32_e32 v127, v116, v127
	v_fma_f32 v126, v123, v126, v123
	v_fma_f32 v127, v116, v127, v116
	v_mul_f32_e32 v126, 0x3fcc422a, v126
	v_mul_f32_e32 v127, 0x3fcc422a, v127
	v_cvt_pk_bf16_f32 v120, v120, v121
	v_add_f32_e32 v121, 1.0, v128
	v_mul_f32_e32 v126, 0xbfb8aa3b, v126
	v_mul_f32_e32 v127, 0xbfb8aa3b, v127
	v_rcp_f32_e32 v121, v121
	v_exp_f32_e32 v126, v126
	v_exp_f32_e32 v127, v127
	v_mul_f32_e32 v121, v122, v121
	v_add_f32_e32 v122, 1.0, v126
	v_add_f32_e32 v126, 1.0, v127
	v_rcp_f32_e32 v122, v122
	v_rcp_f32_e32 v126, v126
	v_mul_f32_e32 v127, 0x3d372713, v117
	v_mul_f32_e32 v127, v117, v127
	v_mul_f32_e32 v122, v123, v122
	v_mul_f32_e32 v116, v116, v126
	v_mul_f32_e32 v123, 0x3d372713, v118
	v_mul_f32_e32 v126, 0x3d372713, v119
	v_fma_f32 v127, v117, v127, v117
	v_mul_f32_e32 v123, v118, v123
	v_mul_f32_e32 v126, v119, v126
	v_mul_f32_e32 v127, 0x3fcc422a, v127
	v_fma_f32 v123, v118, v123, v118
	v_fma_f32 v126, v119, v126, v119
	v_mul_f32_e32 v127, 0xbfb8aa3b, v127
	v_mul_f32_e32 v123, 0x3fcc422a, v123
	v_mul_f32_e32 v126, 0x3fcc422a, v126
	v_exp_f32_e32 v127, v127
	v_mul_f32_e32 v123, 0xbfb8aa3b, v123
	v_mul_f32_e32 v126, 0xbfb8aa3b, v126
	v_exp_f32_e32 v123, v123
	v_exp_f32_e32 v126, v126
	v_cvt_pk_bf16_f32 v121, v121, v122
	v_add_f32_e32 v122, 1.0, v127
	v_rcp_f32_e32 v122, v122
	v_add_f32_e32 v123, 1.0, v123
	v_add_f32_e32 v126, 1.0, v126
	v_rcp_f32_e32 v123, v123
	v_rcp_f32_e32 v126, v126
	v_mul_f32_e32 v117, v117, v122
	v_cvt_pk_bf16_f32 v122, v116, v117
	v_mul_f32_e32 v116, v118, v123
	v_mul_f32_e32 v117, v119, v126
	v_cvt_pk_bf16_f32 v123, v116, v117
	v_mul_f32_e32 v116, 0x3d372713, v112
	v_mul_f32_e32 v117, 0x3d372713, v113
	v_mul_f32_e32 v116, v112, v116
	v_mul_f32_e32 v117, v113, v117
	v_fma_f32 v116, v112, v116, v112
	v_fma_f32 v117, v113, v117, v113
	v_mul_f32_e32 v116, 0x3fcc422a, v116
	v_mul_f32_e32 v117, 0x3fcc422a, v117
; __device__ __forceinline__ unsigned cvt_pk_bf16(float lo, float hi) { unsigned r; asm volatile("v_cvt_pk_bf16_f32 %0, %1, %2" : "=v"(r) : "v"(lo), "v"(hi)); return r; }
; __device__ __forceinline__ float gelu_tanh(float x) { const float u = 1.5957691216057308f * (x + 0.044715f * x * x * x); return x * sigmoidf_(u); }
; __device__ __forceinline__ float sigmoidf_(float x) { return __builtin_amdgcn_rcpf(1.0f + __builtin_amdgcn_exp2f(-1.4426950408889634f * x)); }
;     __device__ __forceinline__ void operator()(const f32x4 (&acc)[2][2][4][2], const Unit& u, int wr, int wc, int fr, int fq) const {
;     ...
;                 for (int bj = 0; bj < 2; ++bj) { const f32x4 v0 = acc[ai][bj][m][0], v1 = acc[ai][bj][m][1];
;                     const int j = 8 * bj + 2 * wc + (fq >> 1), p0 = 8 * (fq & 1);
;                     u32x4 w; w.x = cvt_pk_bf16(gelu_tanh(v0[0]), gelu_tanh(v0[1])); w.y = cvt_pk_bf16(gelu_tanh(v0[2]), gelu_tanh(v0[3]));
;                     w.z = cvt_pk_bf16(gelu_tanh(v1[0]), gelu_tanh(v1[1])); w.w = cvt_pk_bf16(gelu_tanh(v1[2]), gelu_tanh(v1[3]));
;                     *(u32x4*)(Zb + (size_t)g * (16384 * 16) + (size_t)(bc * 16 + j) * 16 + p0) = w; asm volatile("" ::: "memory"); } }
	v_mul_f32_e32 v116, 0xbfb8aa3b, v116
	v_mul_f32_e32 v117, 0xbfb8aa3b, v117
	v_exp_f32_e32 v116, v116
	v_exp_f32_e32 v117, v117
	v_mul_f32_e32 v118, 0x3d372713, v114
	v_mul_f32_e32 v118, v114, v118
	v_add_f32_e32 v116, 1.0, v116
	v_add_f32_e32 v117, 1.0, v117
	v_rcp_f32_e32 v116, v116
	v_rcp_f32_e32 v117, v117
	v_fma_f32 v118, v114, v118, v114
	v_mul_f32_e32 v118, 0x3fcc422a, v118
	v_mul_f32_e32 v118, 0xbfb8aa3b, v118
	v_exp_f32_e32 v118, v118
	v_mul_f32_e32 v112, v112, v116
	v_mul_f32_e32 v113, v113, v117
	v_mul_f32_e32 v116, 0x3d372713, v115
	v_mul_f32_e32 v117, 0x3d372713, v108
	v_mul_f32_e32 v116, v115, v116
	v_mul_f32_e32 v117, v108, v117
	v_fma_f32 v116, v115, v116, v115
	v_fma_f32 v117, v108, v117, v108
	global_store_dwordx4 v[124:125], v[120:123], off offset:256 sc1
	v_mul_f32_e32 v116, 0x3fcc422a, v116
	v_mul_f32_e32 v117, 0x3fcc422a, v117
	v_cvt_pk_bf16_f32 v112, v112, v113
	v_add_f32_e32 v113, 1.0, v118
	v_mul_f32_e32 v116, 0xbfb8aa3b, v116
	v_mul_f32_e32 v117, 0xbfb8aa3b, v117
	v_rcp_f32_e32 v113, v113
	v_exp_f32_e32 v116, v116
	v_exp_f32_e32 v117, v117
	v_mul_f32_e32 v113, v114, v113
	v_add_f32_e32 v114, 1.0, v116
	v_add_f32_e32 v116, 1.0, v117
	v_rcp_f32_e32 v114, v114
	v_rcp_f32_e32 v116, v116
	v_mul_f32_e32 v117, 0x3d372713, v109
	v_mul_f32_e32 v117, v109, v117
	v_mul_f32_e32 v114, v115, v114
	v_mul_f32_e32 v108, v108, v116
	v_mul_f32_e32 v115, 0x3d372713, v110
	v_mul_f32_e32 v116, 0x3d372713, v111
	v_fma_f32 v117, v109, v117, v109
	v_mul_f32_e32 v115, v110, v115
	v_mul_f32_e32 v116, v111, v116
	v_mul_f32_e32 v117, 0x3fcc422a, v117
	v_fma_f32 v115, v110, v115, v110
	v_fma_f32 v116, v111, v116, v111
	v_mul_f32_e32 v117, 0xbfb8aa3b, v117
	v_mul_f32_e32 v115, 0x3fcc422a, v115
	v_mul_f32_e32 v116, 0x3fcc422a, v116
	v_exp_f32_e32 v117, v117
	v_mul_f32_e32 v115, 0xbfb8aa3b, v115
	v_mul_f32_e32 v116, 0xbfb8aa3b, v116
	v_exp_f32_e32 v115, v115
	v_exp_f32_e32 v116, v116
	v_cvt_pk_bf16_f32 v113, v113, v114
	v_add_f32_e32 v114, 1.0, v117
	v_rcp_f32_e32 v114, v114
	v_add_f32_e32 v115, 1.0, v115
	v_add_f32_e32 v116, 1.0, v116
	v_rcp_f32_e32 v115, v115
	v_rcp_f32_e32 v116, v116
	v_mul_f32_e32 v109, v109, v114
	v_cvt_pk_bf16_f32 v114, v108, v109
	v_mul_f32_e32 v108, v110, v115
	v_mul_f32_e32 v109, v111, v116
	v_mul_f32_e32 v110, 0x3d372713, v104
	v_mul_f32_e32 v111, 0x3d372713, v105
	v_mul_f32_e32 v110, v104, v110
	v_mul_f32_e32 v111, v105, v111
	v_fma_f32 v110, v104, v110, v104
	v_fma_f32 v111, v105, v111, v105
	v_mul_f32_e32 v110, 0x3fcc422a, v110
	v_mul_f32_e32 v111, 0x3fcc422a, v111
	v_mul_f32_e32 v110, 0xbfb8aa3b, v110
	v_mul_f32_e32 v111, 0xbfb8aa3b, v111
	v_exp_f32_e32 v110, v110
	v_exp_f32_e32 v111, v111
	v_cvt_pk_bf16_f32 v115, v108, v109
	v_add_co_u32_e32 v108, vcc, s54, v124
	v_add_f32_e32 v110, 1.0, v110
	s_nop 0
	v_addc_co_u32_e32 v109, vcc, 0, v125, vcc
	global_store_dwordx4 v[108:109], v[112:115], off sc1
	v_add_f32_e32 v111, 1.0, v111
	v_rcp_f32_e32 v110, v110
	v_mul_f32_e32 v112, 0x3d372713, v106
	v_rcp_f32_e32 v111, v111
	v_mul_f32_e32 v112, v106, v112
	v_fma_f32 v112, v106, v112, v106
	v_mul_f32_e32 v112, 0x3fcc422a, v112
	v_mul_f32_e32 v112, 0xbfb8aa3b, v112
	v_exp_f32_e32 v112, v112
	v_mul_f32_e32 v104, v104, v110
	v_mul_f32_e32 v105, v105, v111
	v_mul_f32_e32 v110, 0x3d372713, v107
	v_mul_f32_e32 v111, 0x3d372713, v100
	v_mul_f32_e32 v110, v107, v110
	v_mul_f32_e32 v111, v100, v111
	v_fma_f32 v110, v107, v110, v107
	v_fma_f32 v111, v100, v111, v100
	v_mul_f32_e32 v110, 0x3fcc422a, v110
	v_mul_f32_e32 v111, 0x3fcc422a, v111
	v_cvt_pk_bf16_f32 v104, v104, v105
	v_add_f32_e32 v105, 1.0, v112
	v_mul_f32_e32 v110, 0xbfb8aa3b, v110
	v_mul_f32_e32 v111, 0xbfb8aa3b, v111
	v_rcp_f32_e32 v105, v105
	v_exp_f32_e32 v110, v110
	v_exp_f32_e32 v111, v111
	v_mul_f32_e32 v105, v106, v105
	v_add_f32_e32 v106, 1.0, v110
	v_add_f32_e32 v110, 1.0, v111
	v_rcp_f32_e32 v106, v106
	v_rcp_f32_e32 v110, v110
	v_mul_f32_e32 v111, 0x3d372713, v101
	v_mul_f32_e32 v111, v101, v111
	v_mul_f32_e32 v106, v107, v106
	v_mul_f32_e32 v100, v100, v110
	v_mul_f32_e32 v107, 0x3d372713, v102
	v_mul_f32_e32 v110, 0x3d372713, v103
	v_fma_f32 v111, v101, v111, v101
	v_mul_f32_e32 v107, v102, v107
	v_mul_f32_e32 v110, v103, v110
	v_mul_f32_e32 v111, 0x3fcc422a, v111
	v_fma_f32 v107, v102, v107, v102
	v_fma_f32 v110, v103, v110, v103
	v_mul_f32_e32 v111, 0xbfb8aa3b, v111
	v_mul_f32_e32 v107, 0x3fcc422a, v107
	v_mul_f32_e32 v110, 0x3fcc422a, v110
	v_exp_f32_e32 v111, v111
	v_mul_f32_e32 v107, 0xbfb8aa3b, v107
	v_mul_f32_e32 v110, 0xbfb8aa3b, v110
	v_exp_f32_e32 v107, v107
	v_exp_f32_e32 v110, v110
	v_cvt_pk_bf16_f32 v105, v105, v106
	v_add_f32_e32 v106, 1.0, v111
	v_rcp_f32_e32 v106, v106
	v_add_f32_e32 v107, 1.0, v107
	v_add_f32_e32 v110, 1.0, v110
	v_rcp_f32_e32 v107, v107
	v_rcp_f32_e32 v110, v110
	v_mul_f32_e32 v101, v101, v106
	v_cvt_pk_bf16_f32 v106, v100, v101
	v_mul_f32_e32 v100, v102, v107
	v_mul_f32_e32 v101, v103, v110
	v_cvt_pk_bf16_f32 v107, v100, v101
	v_mul_f32_e32 v100, 0x3d372713, v96
	v_mul_f32_e32 v101, 0x3d372713, v97
	v_mul_f32_e32 v100, v96, v100
	v_mul_f32_e32 v101, v97, v101
	v_fma_f32 v100, v96, v100, v96
	v_fma_f32 v101, v97, v101, v97
	v_mul_f32_e32 v100, 0x3fcc422a, v100
	v_mul_f32_e32 v101, 0x3fcc422a, v101
	v_mul_f32_e32 v100, 0xbfb8aa3b, v100
	v_mul_f32_e32 v101, 0xbfb8aa3b, v101
	v_exp_f32_e32 v100, v100
	v_exp_f32_e32 v101, v101
	v_mul_f32_e32 v102, 0x3d372713, v98
	v_mul_f32_e32 v102, v98, v102
	v_add_f32_e32 v100, 1.0, v100
	v_add_f32_e32 v101, 1.0, v101
	v_rcp_f32_e32 v100, v100
	v_rcp_f32_e32 v101, v101
	v_fma_f32 v102, v98, v102, v98
	v_mul_f32_e32 v102, 0x3fcc422a, v102
	v_mul_f32_e32 v102, 0xbfb8aa3b, v102
; __device__ __forceinline__ unsigned cvt_pk_bf16(float lo, float hi) { unsigned r; asm volatile("v_cvt_pk_bf16_f32 %0, %1, %2" : "=v"(r) : "v"(lo), "v"(hi)); return r; }
; __device__ __forceinline__ float gelu_tanh(float x) { const float u = 1.5957691216057308f * (x + 0.044715f * x * x * x); return x * sigmoidf_(u); }
; __device__ __forceinline__ float sigmoidf_(float x) { return __builtin_amdgcn_rcpf(1.0f + __builtin_amdgcn_exp2f(-1.4426950408889634f * x)); }
;     __device__ __forceinline__ void operator()(const f32x4 (&acc)[2][2][4][2], const Unit& u, int wr, int wc, int fr, int fq) const {
;     ...
;                 for (int bj = 0; bj < 2; ++bj) { const f32x4 v0 = acc[ai][bj][m][0], v1 = acc[ai][bj][m][1];
;                     const int j = 8 * bj + 2 * wc + (fq >> 1), p0 = 8 * (fq & 1);
;                     u32x4 w; w.x = cvt_pk_bf16(gelu_tanh(v0[0]), gelu_tanh(v0[1])); w.y = cvt_pk_bf16(gelu_tanh(v0[2]), gelu_tanh(v0[3]));
;                     w.z = cvt_pk_bf16(gelu_tanh(v1[0]), gelu_tanh(v1[1])); w.w = cvt_pk_bf16(gelu_tanh(v1[2]), gelu_tanh(v1[3]));
;                     *(u32x4*)(Zb + (size_t)g * (16384 * 16) + (size_t)(bc * 16 + j) * 16 + p0) = w; asm volatile("" ::: "memory"); } }
	v_exp_f32_e32 v102, v102
	v_mul_f32_e32 v96, v96, v100
	v_mul_f32_e32 v97, v97, v101
	v_mul_f32_e32 v100, 0x3d372713, v99
	v_mul_f32_e32 v101, 0x3d372713, v92
	v_mul_f32_e32 v100, v99, v100
	v_mul_f32_e32 v101, v92, v101
	v_fma_f32 v100, v99, v100, v99
	v_fma_f32 v101, v92, v101, v92
	global_store_dwordx4 v[108:109], v[104:107], off offset:256 sc1
	v_mul_f32_e32 v100, 0x3fcc422a, v100
	v_mul_f32_e32 v101, 0x3fcc422a, v101
	v_cvt_pk_bf16_f32 v96, v96, v97
	v_add_f32_e32 v97, 1.0, v102
	v_mul_f32_e32 v100, 0xbfb8aa3b, v100
	v_mul_f32_e32 v101, 0xbfb8aa3b, v101
	v_rcp_f32_e32 v97, v97
	v_exp_f32_e32 v100, v100
	v_exp_f32_e32 v101, v101
	v_mul_f32_e32 v97, v98, v97
	v_add_f32_e32 v98, 1.0, v100
	v_add_f32_e32 v100, 1.0, v101
	v_rcp_f32_e32 v98, v98
	v_rcp_f32_e32 v100, v100
	v_mul_f32_e32 v101, 0x3d372713, v93
	v_mul_f32_e32 v101, v93, v101
	v_mul_f32_e32 v98, v99, v98
	v_mul_f32_e32 v92, v92, v100
	v_mul_f32_e32 v99, 0x3d372713, v94
	v_mul_f32_e32 v100, 0x3d372713, v95
	v_fma_f32 v101, v93, v101, v93
	v_mul_f32_e32 v99, v94, v99
	v_mul_f32_e32 v100, v95, v100
	v_mul_f32_e32 v101, 0x3fcc422a, v101
	v_fma_f32 v99, v94, v99, v94
	v_fma_f32 v100, v95, v100, v95
	v_mul_f32_e32 v101, 0xbfb8aa3b, v101
	v_mul_f32_e32 v99, 0x3fcc422a, v99
	v_mul_f32_e32 v100, 0x3fcc422a, v100
	v_exp_f32_e32 v101, v101
	v_mul_f32_e32 v99, 0xbfb8aa3b, v99
	v_mul_f32_e32 v100, 0xbfb8aa3b, v100
	v_exp_f32_e32 v99, v99
	v_exp_f32_e32 v100, v100
	v_cvt_pk_bf16_f32 v97, v97, v98
	v_add_f32_e32 v98, 1.0, v101
	v_rcp_f32_e32 v98, v98
	v_add_f32_e32 v99, 1.0, v99
	v_add_f32_e32 v100, 1.0, v100
	v_rcp_f32_e32 v99, v99
	v_rcp_f32_e32 v100, v100
	v_mul_f32_e32 v93, v93, v98
	v_cvt_pk_bf16_f32 v98, v92, v93
	v_mul_f32_e32 v92, v94, v99
	v_mul_f32_e32 v93, v95, v100
	v_mul_f32_e32 v94, 0x3d372713, v88
	v_mul_f32_e32 v95, 0x3d372713, v89
	v_mul_f32_e32 v94, v88, v94
	v_mul_f32_e32 v95, v89, v95
	v_fma_f32 v94, v88, v94, v88
	v_fma_f32 v95, v89, v95, v89
	v_mul_f32_e32 v94, 0x3fcc422a, v94
	v_mul_f32_e32 v95, 0x3fcc422a, v95
	v_mul_f32_e32 v94, 0xbfb8aa3b, v94
	v_mul_f32_e32 v95, 0xbfb8aa3b, v95
	v_exp_f32_e32 v94, v94
	v_exp_f32_e32 v95, v95
	v_cvt_pk_bf16_f32 v99, v92, v93
	v_add_co_u32_e32 v92, vcc, s55, v124
	v_add_f32_e32 v94, 1.0, v94
	s_nop 0
	v_addc_co_u32_e32 v93, vcc, 0, v125, vcc
	global_store_dwordx4 v[92:93], v[96:99], off sc1
	v_add_f32_e32 v95, 1.0, v95
	v_rcp_f32_e32 v94, v94
	v_mul_f32_e32 v96, 0x3d372713, v90
	v_rcp_f32_e32 v95, v95
	v_mul_f32_e32 v96, v90, v96
	v_fma_f32 v96, v90, v96, v90
	v_mul_f32_e32 v96, 0x3fcc422a, v96
	v_mul_f32_e32 v96, 0xbfb8aa3b, v96
	v_exp_f32_e32 v96, v96
	v_mul_f32_e32 v88, v88, v94
	v_mul_f32_e32 v89, v89, v95
	v_mul_f32_e32 v94, 0x3d372713, v91
	v_mul_f32_e32 v95, 0x3d372713, v84
	v_mul_f32_e32 v94, v91, v94
	v_mul_f32_e32 v95, v84, v95
	v_fma_f32 v94, v91, v94, v91
	v_fma_f32 v95, v84, v95, v84
	v_mul_f32_e32 v94, 0x3fcc422a, v94
	v_mul_f32_e32 v95, 0x3fcc422a, v95
	v_cvt_pk_bf16_f32 v88, v88, v89
	v_add_f32_e32 v89, 1.0, v96
	v_mul_f32_e32 v94, 0xbfb8aa3b, v94
	v_mul_f32_e32 v95, 0xbfb8aa3b, v95
	v_rcp_f32_e32 v89, v89
	v_exp_f32_e32 v94, v94
	v_exp_f32_e32 v95, v95
	v_mul_f32_e32 v89, v90, v89
	v_add_f32_e32 v90, 1.0, v94
	v_add_f32_e32 v94, 1.0, v95
	v_rcp_f32_e32 v90, v90
	v_rcp_f32_e32 v94, v94
	v_mul_f32_e32 v95, 0x3d372713, v85
	v_mul_f32_e32 v95, v85, v95
	v_mul_f32_e32 v90, v91, v90
	v_mul_f32_e32 v84, v84, v94
	v_mul_f32_e32 v91, 0x3d372713, v86
	v_mul_f32_e32 v94, 0x3d372713, v87
	v_fma_f32 v95, v85, v95, v85
	v_mul_f32_e32 v91, v86, v91
	v_mul_f32_e32 v94, v87, v94
	v_mul_f32_e32 v95, 0x3fcc422a, v95
	v_fma_f32 v91, v86, v91, v86
	v_fma_f32 v94, v87, v94, v87
	v_mul_f32_e32 v95, 0xbfb8aa3b, v95
	v_mul_f32_e32 v91, 0x3fcc422a, v91
	v_mul_f32_e32 v94, 0x3fcc422a, v94
	v_exp_f32_e32 v95, v95
	v_mul_f32_e32 v91, 0xbfb8aa3b, v91
	v_mul_f32_e32 v94, 0xbfb8aa3b, v94
	v_exp_f32_e32 v91, v91
	v_exp_f32_e32 v94, v94
	v_cvt_pk_bf16_f32 v89, v89, v90
	v_add_f32_e32 v90, 1.0, v95
	v_rcp_f32_e32 v90, v90
	v_add_f32_e32 v91, 1.0, v91
	v_add_f32_e32 v94, 1.0, v94
	v_rcp_f32_e32 v91, v91
	v_rcp_f32_e32 v94, v94
	v_mul_f32_e32 v85, v85, v90
	v_cvt_pk_bf16_f32 v90, v84, v85
	v_mul_f32_e32 v84, v86, v91
	v_mul_f32_e32 v85, v87, v94
	v_cvt_pk_bf16_f32 v91, v84, v85
	v_mul_f32_e32 v84, 0x3d372713, v80
	v_mul_f32_e32 v85, 0x3d372713, v81
	v_mul_f32_e32 v84, v80, v84
	v_mul_f32_e32 v85, v81, v85
	v_fma_f32 v84, v80, v84, v80
	v_fma_f32 v85, v81, v85, v81
	v_mul_f32_e32 v84, 0x3fcc422a, v84
	v_mul_f32_e32 v85, 0x3fcc422a, v85
	v_mul_f32_e32 v84, 0xbfb8aa3b, v84
	v_mul_f32_e32 v85, 0xbfb8aa3b, v85
	v_exp_f32_e32 v84, v84
	v_exp_f32_e32 v85, v85
	v_mul_f32_e32 v86, 0x3d372713, v82
	v_mul_f32_e32 v86, v82, v86
	v_add_f32_e32 v84, 1.0, v84
	v_add_f32_e32 v85, 1.0, v85
	v_rcp_f32_e32 v84, v84
	v_rcp_f32_e32 v85, v85
	v_fma_f32 v86, v82, v86, v82
	v_mul_f32_e32 v86, 0x3fcc422a, v86
	v_mul_f32_e32 v86, 0xbfb8aa3b, v86
	v_exp_f32_e32 v86, v86
	v_mul_f32_e32 v80, v80, v84
	v_mul_f32_e32 v81, v81, v85
	v_mul_f32_e32 v84, 0x3d372713, v83
	v_mul_f32_e32 v85, 0x3d372713, v76
	v_mul_f32_e32 v84, v83, v84
	v_mul_f32_e32 v85, v76, v85
	v_fma_f32 v84, v83, v84, v83
	v_fma_f32 v85, v76, v85, v76
	global_store_dwordx4 v[92:93], v[88:91], off offset:256 sc1
	v_mul_f32_e32 v84, 0x3fcc422a, v84
	v_mul_f32_e32 v85, 0x3fcc422a, v85
	v_cvt_pk_bf16_f32 v80, v80, v81
	v_add_f32_e32 v81, 1.0, v86
	v_mul_f32_e32 v84, 0xbfb8aa3b, v84
	v_mul_f32_e32 v85, 0xbfb8aa3b, v85
	v_rcp_f32_e32 v81, v81
	v_exp_f32_e32 v84, v84
	v_exp_f32_e32 v85, v85
	v_mul_f32_e32 v81, v82, v81
	v_add_f32_e32 v82, 1.0, v84
	v_add_f32_e32 v84, 1.0, v85
	v_rcp_f32_e32 v82, v82
	v_rcp_f32_e32 v84, v84
; __device__ __forceinline__ unsigned cvt_pk_bf16(float lo, float hi) { unsigned r; asm volatile("v_cvt_pk_bf16_f32 %0, %1, %2" : "=v"(r) : "v"(lo), "v"(hi)); return r; }
; __device__ __forceinline__ float gelu_tanh(float x) { const float u = 1.5957691216057308f * (x + 0.044715f * x * x * x); return x * sigmoidf_(u); }
; __device__ __forceinline__ float sigmoidf_(float x) { return __builtin_amdgcn_rcpf(1.0f + __builtin_amdgcn_exp2f(-1.4426950408889634f * x)); }
;     __device__ __forceinline__ void operator()(const f32x4 (&acc)[2][2][4][2], const Unit& u, int wr, int wc, int fr, int fq) const {
;     ...
;                 for (int bj = 0; bj < 2; ++bj) { const f32x4 v0 = acc[ai][bj][m][0], v1 = acc[ai][bj][m][1];
;                     const int j = 8 * bj + 2 * wc + (fq >> 1), p0 = 8 * (fq & 1);
;                     u32x4 w; w.x = cvt_pk_bf16(gelu_tanh(v0[0]), gelu_tanh(v0[1])); w.y = cvt_pk_bf16(gelu_tanh(v0[2]), gelu_tanh(v0[3]));
;                     w.z = cvt_pk_bf16(gelu_tanh(v1[0]), gelu_tanh(v1[1])); w.w = cvt_pk_bf16(gelu_tanh(v1[2]), gelu_tanh(v1[3]));
;                     *(u32x4*)(Zb + (size_t)g * (16384 * 16) + (size_t)(bc * 16 + j) * 16 + p0) = w; asm volatile("" ::: "memory"); } }
	v_mul_f32_e32 v85, 0x3d372713, v77
	v_mul_f32_e32 v85, v77, v85
	v_mul_f32_e32 v82, v83, v82
	v_mul_f32_e32 v76, v76, v84
	v_mul_f32_e32 v83, 0x3d372713, v78
	v_mul_f32_e32 v84, 0x3d372713, v79
	v_fma_f32 v85, v77, v85, v77
	v_mul_f32_e32 v83, v78, v83
	v_mul_f32_e32 v84, v79, v84
	v_mul_f32_e32 v85, 0x3fcc422a, v85
	v_fma_f32 v83, v78, v83, v78
	v_fma_f32 v84, v79, v84, v79
	v_mul_f32_e32 v85, 0xbfb8aa3b, v85
	v_mul_f32_e32 v83, 0x3fcc422a, v83
	v_mul_f32_e32 v84, 0x3fcc422a, v84
	v_exp_f32_e32 v85, v85
	v_mul_f32_e32 v83, 0xbfb8aa3b, v83
	v_mul_f32_e32 v84, 0xbfb8aa3b, v84
	v_exp_f32_e32 v83, v83
	v_exp_f32_e32 v84, v84
	v_cvt_pk_bf16_f32 v81, v81, v82
	v_add_f32_e32 v82, 1.0, v85
	v_rcp_f32_e32 v82, v82
	v_add_f32_e32 v83, 1.0, v83
	v_add_f32_e32 v84, 1.0, v84
	v_rcp_f32_e32 v83, v83
	v_rcp_f32_e32 v84, v84
	v_mul_f32_e32 v77, v77, v82
	v_cvt_pk_bf16_f32 v82, v76, v77
	v_mul_f32_e32 v76, v78, v83
	v_mul_f32_e32 v77, v79, v84
	v_mul_f32_e32 v78, 0x3d372713, v72
	v_mul_f32_e32 v79, 0x3d372713, v73
	v_mul_f32_e32 v78, v72, v78
	v_mul_f32_e32 v79, v73, v79
	v_fma_f32 v78, v72, v78, v72
	v_fma_f32 v79, v73, v79, v73
	v_mul_f32_e32 v78, 0x3fcc422a, v78
	v_mul_f32_e32 v79, 0x3fcc422a, v79
	v_mul_f32_e32 v78, 0xbfb8aa3b, v78
	v_mul_f32_e32 v79, 0xbfb8aa3b, v79
	v_exp_f32_e32 v78, v78
	v_exp_f32_e32 v79, v79
	v_cvt_pk_bf16_f32 v83, v76, v77
	v_add_co_u32_e32 v76, vcc, s46, v124
	v_add_f32_e32 v78, 1.0, v78
	s_nop 0
	v_addc_co_u32_e32 v77, vcc, 0, v125, vcc
	global_store_dwordx4 v[76:77], v[80:83], off sc1
	v_add_f32_e32 v79, 1.0, v79
	v_rcp_f32_e32 v78, v78
	v_mul_f32_e32 v80, 0x3d372713, v74
	v_rcp_f32_e32 v79, v79
	v_mul_f32_e32 v80, v74, v80
	v_fma_f32 v80, v74, v80, v74
	v_mul_f32_e32 v80, 0x3fcc422a, v80
	v_mul_f32_e32 v80, 0xbfb8aa3b, v80
	v_exp_f32_e32 v80, v80
	v_mul_f32_e32 v72, v72, v78
	v_mul_f32_e32 v73, v73, v79
	v_mul_f32_e32 v78, 0x3d372713, v75
	v_mul_f32_e32 v79, 0x3d372713, v68
	v_mul_f32_e32 v78, v75, v78
	v_mul_f32_e32 v79, v68, v79
	v_fma_f32 v78, v75, v78, v75
	v_fma_f32 v79, v68, v79, v68
	v_mul_f32_e32 v78, 0x3fcc422a, v78
	v_mul_f32_e32 v79, 0x3fcc422a, v79
	v_cvt_pk_bf16_f32 v72, v72, v73
	v_add_f32_e32 v73, 1.0, v80
	v_mul_f32_e32 v78, 0xbfb8aa3b, v78
	v_mul_f32_e32 v79, 0xbfb8aa3b, v79
	v_rcp_f32_e32 v73, v73
	v_exp_f32_e32 v78, v78
	v_exp_f32_e32 v79, v79
	v_mul_f32_e32 v73, v74, v73
	v_add_f32_e32 v74, 1.0, v78
	v_add_f32_e32 v78, 1.0, v79
	v_rcp_f32_e32 v78, v78
	v_rcp_f32_e32 v74, v74
	v_mul_f32_e32 v79, 0x3d372713, v69
	v_mul_f32_e32 v79, v69, v79
	v_mul_f32_e32 v68, v68, v78
	v_mul_f32_e32 v78, 0x3d372713, v71
	v_fma_f32 v79, v69, v79, v69
	v_mul_f32_e32 v74, v75, v74
	v_mul_f32_e32 v75, 0x3d372713, v70
	v_mul_f32_e32 v78, v71, v78
	v_mul_f32_e32 v79, 0x3fcc422a, v79
	v_mul_f32_e32 v75, v70, v75
	v_fma_f32 v78, v71, v78, v71
	v_mul_f32_e32 v79, 0xbfb8aa3b, v79
	v_fma_f32 v75, v70, v75, v70
	v_mul_f32_e32 v78, 0x3fcc422a, v78
	v_exp_f32_e32 v79, v79
	v_mul_f32_e32 v75, 0x3fcc422a, v75
	v_mul_f32_e32 v78, 0xbfb8aa3b, v78
	v_mul_f32_e32 v75, 0xbfb8aa3b, v75
	v_exp_f32_e32 v78, v78
	v_exp_f32_e32 v75, v75
	v_cvt_pk_bf16_f32 v73, v73, v74
	v_add_f32_e32 v74, 1.0, v79
	v_rcp_f32_e32 v74, v74
	v_add_f32_e32 v78, 1.0, v78
	v_add_f32_e32 v75, 1.0, v75
	v_rcp_f32_e32 v78, v78
	v_rcp_f32_e32 v75, v75
	v_mul_f32_e32 v69, v69, v74
	v_cvt_pk_bf16_f32 v74, v68, v69
	v_mul_f32_e32 v69, v71, v78
	v_mul_f32_e32 v68, v70, v75
	v_cvt_pk_bf16_f32 v75, v68, v69
	v_mul_f32_e32 v69, 0x3d372713, v64
	v_mul_f32_e32 v70, 0x3d372713, v65
	v_mul_f32_e32 v69, v64, v69
	v_mul_f32_e32 v70, v65, v70
	v_fma_f32 v69, v64, v69, v64
	v_fma_f32 v70, v65, v70, v65
	v_mul_f32_e32 v69, 0x3fcc422a, v69
	v_mul_f32_e32 v70, 0x3fcc422a, v70
	v_mul_f32_e32 v69, 0xbfb8aa3b, v69
	v_mul_f32_e32 v70, 0xbfb8aa3b, v70
	v_exp_f32_e32 v69, v69
	v_exp_f32_e32 v70, v70
	v_mul_f32_e32 v71, 0x3d372713, v66
	v_mul_f32_e32 v71, v66, v71
	v_add_f32_e32 v69, 1.0, v69
	v_add_f32_e32 v70, 1.0, v70
	v_rcp_f32_e32 v69, v69
	v_rcp_f32_e32 v70, v70
	v_fma_f32 v71, v66, v71, v66
	v_mul_f32_e32 v71, 0x3fcc422a, v71
	v_mul_f32_e32 v71, 0xbfb8aa3b, v71
	v_exp_f32_e32 v71, v71
	v_mul_f32_e32 v64, v64, v69
	v_mul_f32_e32 v65, v65, v70
	v_mul_f32_e32 v69, 0x3d372713, v67
	v_mul_f32_e32 v70, 0x3d372713, v60
	v_mul_f32_e32 v69, v67, v69
	v_mul_f32_e32 v70, v60, v70
	v_fma_f32 v69, v67, v69, v67
	v_fma_f32 v70, v60, v70, v60
	global_store_dwordx4 v[76:77], v[72:75], off offset:256 sc1
	v_mul_f32_e32 v69, 0x3fcc422a, v69
	v_mul_f32_e32 v70, 0x3fcc422a, v70
	v_cvt_pk_bf16_f32 v64, v64, v65
	v_add_f32_e32 v65, 1.0, v71
	v_mul_f32_e32 v69, 0xbfb8aa3b, v69
	v_mul_f32_e32 v70, 0xbfb8aa3b, v70
	v_rcp_f32_e32 v65, v65
	v_exp_f32_e32 v69, v69
	v_exp_f32_e32 v70, v70
	v_add_u32_e32 v68, 0x800, v145
	v_mul_f32_e32 v65, v66, v65
	v_add_f32_e32 v66, 1.0, v69
	v_add_f32_e32 v69, 1.0, v70
	v_rcp_f32_e32 v66, v66
	v_rcp_f32_e32 v69, v69
	v_mul_f32_e32 v70, 0x3d372713, v61
	v_mul_f32_e32 v70, v61, v70
	v_mul_f32_e32 v66, v67, v66
	v_mul_f32_e32 v60, v60, v69
	v_mul_f32_e32 v67, 0x3d372713, v62
	v_mul_f32_e32 v69, 0x3d372713, v63
	v_fma_f32 v70, v61, v70, v61
	v_mul_f32_e32 v67, v62, v67
	v_mul_f32_e32 v69, v63, v69
	v_mul_f32_e32 v70, 0x3fcc422a, v70
	v_fma_f32 v67, v62, v67, v62
	v_fma_f32 v69, v63, v69, v63
	v_mul_f32_e32 v70, 0xbfb8aa3b, v70
	v_mul_f32_e32 v67, 0x3fcc422a, v67
	v_mul_f32_e32 v69, 0x3fcc422a, v69
	v_exp_f32_e32 v70, v70
	v_mul_f32_e32 v67, 0xbfb8aa3b, v67
	v_mul_f32_e32 v69, 0xbfb8aa3b, v69
	v_exp_f32_e32 v67, v67
	v_exp_f32_e32 v69, v69
	v_cvt_pk_bf16_f32 v65, v65, v66
	v_add_f32_e32 v66, 1.0, v70
	v_rcp_f32_e32 v66, v66
	v_add_f32_e32 v67, 1.0, v67
	v_add_f32_e32 v69, 1.0, v69
; __device__ __forceinline__ unsigned cvt_pk_bf16(float lo, float hi) { unsigned r; asm volatile("v_cvt_pk_bf16_f32 %0, %1, %2" : "=v"(r) : "v"(lo), "v"(hi)); return r; }
; __device__ __forceinline__ float gelu_tanh(float x) { const float u = 1.5957691216057308f * (x + 0.044715f * x * x * x); return x * sigmoidf_(u); }
; __device__ __forceinline__ float sigmoidf_(float x) { return __builtin_amdgcn_rcpf(1.0f + __builtin_amdgcn_exp2f(-1.4426950408889634f * x)); }
;     __device__ __forceinline__ void operator()(const f32x4 (&acc)[2][2][4][2], const Unit& u, int wr, int wc, int fr, int fq) const {
;     ...
;                 for (int bj = 0; bj < 2; ++bj) { const f32x4 v0 = acc[ai][bj][m][0], v1 = acc[ai][bj][m][1];
;                     const int j = 8 * bj + 2 * wc + (fq >> 1), p0 = 8 * (fq & 1);
;                     u32x4 w; w.x = cvt_pk_bf16(gelu_tanh(v0[0]), gelu_tanh(v0[1])); w.y = cvt_pk_bf16(gelu_tanh(v0[2]), gelu_tanh(v0[3]));
;                     w.z = cvt_pk_bf16(gelu_tanh(v1[0]), gelu_tanh(v1[1])); w.w = cvt_pk_bf16(gelu_tanh(v1[2]), gelu_tanh(v1[3]));
;                     *(u32x4*)(Zb + (size_t)g * (16384 * 16) + (size_t)(bc * 16 + j) * 16 + p0) = w; asm volatile("" ::: "memory"); } }
	v_rcp_f32_e32 v67, v67
	v_rcp_f32_e32 v69, v69
	v_mul_f32_e32 v61, v61, v66
	v_cvt_pk_bf16_f32 v66, v60, v61
	v_mul_f32_e32 v60, v62, v67
	v_mul_f32_e32 v61, v63, v69
	v_mul_f32_e32 v62, 0x3d372713, v56
	v_mul_f32_e32 v63, 0x3d372713, v57
	v_mul_f32_e32 v62, v56, v62
	v_mul_f32_e32 v63, v57, v63
	v_fma_f32 v62, v56, v62, v56
	v_fma_f32 v63, v57, v63, v57
	v_mul_f32_e32 v62, 0x3fcc422a, v62
	v_mul_f32_e32 v63, 0x3fcc422a, v63
	v_mul_f32_e32 v62, 0xbfb8aa3b, v62
	v_mul_f32_e32 v63, 0xbfb8aa3b, v63
	v_and_or_b32 v68, v68, s56, v144
	v_exp_f32_e32 v62, v62
	v_exp_f32_e32 v63, v63
	v_lshlrev_b32_e32 v140, 5, v68
	v_cvt_pk_bf16_f32 v67, v60, v61
	v_lshl_add_u64 v[60:61], s[6:7], 0, v[140:141]
	v_lshl_add_u64 v[60:61], v[60:61], 0, v[142:143]
	global_store_dwordx4 v[60:61], v[64:67], off sc1
	v_add_f32_e32 v62, 1.0, v62
	v_add_f32_e32 v63, 1.0, v63
	v_mul_f32_e32 v64, 0x3d372713, v58
	v_rcp_f32_e32 v62, v62
	v_rcp_f32_e32 v63, v63
	v_mul_f32_e32 v64, v58, v64
	v_fma_f32 v64, v58, v64, v58
	v_mul_f32_e32 v64, 0x3fcc422a, v64
	v_mul_f32_e32 v64, 0xbfb8aa3b, v64
	v_exp_f32_e32 v64, v64
	v_mul_f32_e32 v56, v56, v62
	v_mul_f32_e32 v57, v57, v63
	v_mul_f32_e32 v62, 0x3d372713, v59
	v_mul_f32_e32 v63, 0x3d372713, v52
	v_mul_f32_e32 v62, v59, v62
	v_mul_f32_e32 v63, v52, v63
	v_fma_f32 v62, v59, v62, v59
	v_fma_f32 v63, v52, v63, v52
	v_mul_f32_e32 v62, 0x3fcc422a, v62
	v_mul_f32_e32 v63, 0x3fcc422a, v63
	v_cvt_pk_bf16_f32 v56, v56, v57
	v_add_f32_e32 v57, 1.0, v64
	v_mul_f32_e32 v62, 0xbfb8aa3b, v62
	v_mul_f32_e32 v63, 0xbfb8aa3b, v63
	v_rcp_f32_e32 v57, v57
	v_exp_f32_e32 v62, v62
	v_exp_f32_e32 v63, v63
	s_mov_b64 s[6:7], -1
	v_mul_f32_e32 v57, v58, v57
	v_add_f32_e32 v58, 1.0, v62
	v_add_f32_e32 v62, 1.0, v63
	v_rcp_f32_e32 v58, v58
	v_rcp_f32_e32 v62, v62
	v_mul_f32_e32 v63, 0x3d372713, v53
	v_mul_f32_e32 v63, v53, v63
	v_mul_f32_e32 v58, v59, v58
	v_mul_f32_e32 v52, v52, v62
	v_mul_f32_e32 v59, 0x3d372713, v54
	v_mul_f32_e32 v62, 0x3d372713, v55
	v_fma_f32 v63, v53, v63, v53
	v_mul_f32_e32 v59, v54, v59
	v_mul_f32_e32 v62, v55, v62
	v_mul_f32_e32 v63, 0x3fcc422a, v63
	v_fma_f32 v59, v54, v59, v54
	v_fma_f32 v62, v55, v62, v55
	v_mul_f32_e32 v63, 0xbfb8aa3b, v63
	v_mul_f32_e32 v59, 0x3fcc422a, v59
	v_mul_f32_e32 v62, 0x3fcc422a, v62
	v_exp_f32_e32 v63, v63
	v_mul_f32_e32 v59, 0xbfb8aa3b, v59
	v_mul_f32_e32 v62, 0xbfb8aa3b, v62
	v_exp_f32_e32 v59, v59
	v_exp_f32_e32 v62, v62
	v_cvt_pk_bf16_f32 v57, v57, v58
	v_add_f32_e32 v58, 1.0, v63
	v_rcp_f32_e32 v58, v58
	v_add_f32_e32 v59, 1.0, v59
	v_add_f32_e32 v62, 1.0, v62
	v_rcp_f32_e32 v59, v59
	v_rcp_f32_e32 v62, v62
	v_mul_f32_e32 v53, v53, v58
	v_cvt_pk_bf16_f32 v58, v52, v53
	v_mul_f32_e32 v52, v54, v59
	v_mul_f32_e32 v53, v55, v62
	v_cvt_pk_bf16_f32 v59, v52, v53
	v_mul_f32_e32 v52, 0x3d372713, v48
	v_mul_f32_e32 v53, 0x3d372713, v49
	v_mul_f32_e32 v52, v48, v52
	v_mul_f32_e32 v53, v49, v53
	v_fma_f32 v52, v48, v52, v48
	v_fma_f32 v53, v49, v53, v49
	v_mul_f32_e32 v52, 0x3fcc422a, v52
	v_mul_f32_e32 v53, 0x3fcc422a, v53
	v_mul_f32_e32 v52, 0xbfb8aa3b, v52
	v_mul_f32_e32 v53, 0xbfb8aa3b, v53
	v_exp_f32_e32 v52, v52
	v_exp_f32_e32 v53, v53
	v_mul_f32_e32 v54, 0x3d372713, v50
	v_mul_f32_e32 v54, v50, v54
	v_add_f32_e32 v52, 1.0, v52
	v_add_f32_e32 v53, 1.0, v53
	v_rcp_f32_e32 v52, v52
	v_rcp_f32_e32 v53, v53
	v_fma_f32 v54, v50, v54, v50
	v_mul_f32_e32 v54, 0x3fcc422a, v54
	v_mul_f32_e32 v54, 0xbfb8aa3b, v54
	v_exp_f32_e32 v54, v54
	v_mul_f32_e32 v48, v48, v52
	v_mul_f32_e32 v49, v49, v53
	v_mul_f32_e32 v52, 0x3d372713, v51
	v_mul_f32_e32 v53, 0x3d372713, v44
	v_mul_f32_e32 v52, v51, v52
	v_mul_f32_e32 v53, v44, v53
	v_fma_f32 v52, v51, v52, v51
	v_fma_f32 v53, v44, v53, v44
	global_store_dwordx4 v[60:61], v[56:59], off offset:256 sc1
	v_mul_f32_e32 v52, 0x3fcc422a, v52
	v_mul_f32_e32 v53, 0x3fcc422a, v53
	v_cvt_pk_bf16_f32 v48, v48, v49
	v_add_f32_e32 v49, 1.0, v54
	v_mul_f32_e32 v52, 0xbfb8aa3b, v52
	v_mul_f32_e32 v53, 0xbfb8aa3b, v53
	v_rcp_f32_e32 v49, v49
	v_exp_f32_e32 v52, v52
	v_exp_f32_e32 v53, v53
	v_mul_f32_e32 v49, v50, v49
	v_add_f32_e32 v50, 1.0, v52
	v_add_f32_e32 v52, 1.0, v53
	v_rcp_f32_e32 v50, v50
	v_rcp_f32_e32 v52, v52
	v_mul_f32_e32 v53, 0x3d372713, v45
	v_mul_f32_e32 v53, v45, v53
	v_mul_f32_e32 v50, v51, v50
	v_mul_f32_e32 v44, v44, v52
	v_mul_f32_e32 v51, 0x3d372713, v46
	v_mul_f32_e32 v52, 0x3d372713, v47
	v_fma_f32 v53, v45, v53, v45
	v_mul_f32_e32 v51, v46, v51
	v_mul_f32_e32 v52, v47, v52
	v_mul_f32_e32 v53, 0x3fcc422a, v53
	v_fma_f32 v51, v46, v51, v46
	v_fma_f32 v52, v47, v52, v47
	v_mul_f32_e32 v53, 0xbfb8aa3b, v53
	v_mul_f32_e32 v51, 0x3fcc422a, v51
	v_mul_f32_e32 v52, 0x3fcc422a, v52
	v_exp_f32_e32 v53, v53
	v_mul_f32_e32 v51, 0xbfb8aa3b, v51
	v_mul_f32_e32 v52, 0xbfb8aa3b, v52
	v_exp_f32_e32 v51, v51
	v_exp_f32_e32 v52, v52
	v_cvt_pk_bf16_f32 v49, v49, v50
	v_add_f32_e32 v50, 1.0, v53
	v_rcp_f32_e32 v50, v50
	v_add_f32_e32 v51, 1.0, v51
	v_add_f32_e32 v52, 1.0, v52
	v_rcp_f32_e32 v51, v51
	v_rcp_f32_e32 v52, v52
	v_mul_f32_e32 v45, v45, v50
	v_cvt_pk_bf16_f32 v50, v44, v45
	v_mul_f32_e32 v44, v46, v51
	v_mul_f32_e32 v45, v47, v52
	v_mul_f32_e32 v46, 0x3d372713, v40
	v_mul_f32_e32 v47, 0x3d372713, v41
	v_mul_f32_e32 v46, v40, v46
	v_mul_f32_e32 v47, v41, v47
	v_fma_f32 v46, v40, v46, v40
	v_fma_f32 v47, v41, v47, v41
	v_mul_f32_e32 v46, 0x3fcc422a, v46
	v_mul_f32_e32 v47, 0x3fcc422a, v47
	v_mul_f32_e32 v46, 0xbfb8aa3b, v46
	v_mul_f32_e32 v47, 0xbfb8aa3b, v47
	v_exp_f32_e32 v46, v46
	v_exp_f32_e32 v47, v47
	v_cvt_pk_bf16_f32 v51, v44, v45
	v_add_co_u32_e32 v44, vcc, s54, v60
	v_add_f32_e32 v46, 1.0, v46
	s_nop 0
	v_addc_co_u32_e32 v45, vcc, 0, v61, vcc
; __device__ __forceinline__ unsigned cvt_pk_bf16(float lo, float hi) { unsigned r; asm volatile("v_cvt_pk_bf16_f32 %0, %1, %2" : "=v"(r) : "v"(lo), "v"(hi)); return r; }
; __device__ __forceinline__ float gelu_tanh(float x) { const float u = 1.5957691216057308f * (x + 0.044715f * x * x * x); return x * sigmoidf_(u); }
; __device__ __forceinline__ float sigmoidf_(float x) { return __builtin_amdgcn_rcpf(1.0f + __builtin_amdgcn_exp2f(-1.4426950408889634f * x)); }
;     __device__ __forceinline__ void operator()(const f32x4 (&acc)[2][2][4][2], const Unit& u, int wr, int wc, int fr, int fq) const {
;     ...
;                 for (int bj = 0; bj < 2; ++bj) { const f32x4 v0 = acc[ai][bj][m][0], v1 = acc[ai][bj][m][1];
;                     const int j = 8 * bj + 2 * wc + (fq >> 1), p0 = 8 * (fq & 1);
;                     u32x4 w; w.x = cvt_pk_bf16(gelu_tanh(v0[0]), gelu_tanh(v0[1])); w.y = cvt_pk_bf16(gelu_tanh(v0[2]), gelu_tanh(v0[3]));
;                     w.z = cvt_pk_bf16(gelu_tanh(v1[0]), gelu_tanh(v1[1])); w.w = cvt_pk_bf16(gelu_tanh(v1[2]), gelu_tanh(v1[3]));
;                     *(u32x4*)(Zb + (size_t)g * (16384 * 16) + (size_t)(bc * 16 + j) * 16 + p0) = w; asm volatile("" ::: "memory"); } }
	global_store_dwordx4 v[44:45], v[48:51], off sc1
	v_add_f32_e32 v47, 1.0, v47
	v_rcp_f32_e32 v46, v46
	v_mul_f32_e32 v48, 0x3d372713, v42
	v_rcp_f32_e32 v47, v47
	v_mul_f32_e32 v48, v42, v48
	v_fma_f32 v48, v42, v48, v42
	v_mul_f32_e32 v48, 0x3fcc422a, v48
	v_mul_f32_e32 v48, 0xbfb8aa3b, v48
	v_exp_f32_e32 v48, v48
	v_mul_f32_e32 v40, v40, v46
	v_mul_f32_e32 v41, v41, v47
	v_mul_f32_e32 v46, 0x3d372713, v43
	v_mul_f32_e32 v47, 0x3d372713, v36
	v_mul_f32_e32 v46, v43, v46
	v_mul_f32_e32 v47, v36, v47
	v_fma_f32 v46, v43, v46, v43
	v_fma_f32 v47, v36, v47, v36
	v_mul_f32_e32 v46, 0x3fcc422a, v46
	v_mul_f32_e32 v47, 0x3fcc422a, v47
	v_cvt_pk_bf16_f32 v40, v40, v41
	v_add_f32_e32 v41, 1.0, v48
	v_mul_f32_e32 v46, 0xbfb8aa3b, v46
	v_mul_f32_e32 v47, 0xbfb8aa3b, v47
	v_rcp_f32_e32 v41, v41
	v_exp_f32_e32 v46, v46
	v_exp_f32_e32 v47, v47
	v_mul_f32_e32 v41, v42, v41
	v_add_f32_e32 v42, 1.0, v46
	v_add_f32_e32 v46, 1.0, v47
	v_rcp_f32_e32 v42, v42
	v_rcp_f32_e32 v46, v46
	v_mul_f32_e32 v47, 0x3d372713, v37
	v_mul_f32_e32 v47, v37, v47
	v_mul_f32_e32 v42, v43, v42
	v_mul_f32_e32 v36, v36, v46
	v_mul_f32_e32 v43, 0x3d372713, v38
	v_mul_f32_e32 v46, 0x3d372713, v39
	v_fma_f32 v47, v37, v47, v37
	v_mul_f32_e32 v43, v38, v43
	v_mul_f32_e32 v46, v39, v46
	v_mul_f32_e32 v47, 0x3fcc422a, v47
	v_fma_f32 v43, v38, v43, v38
	v_fma_f32 v46, v39, v46, v39
	v_mul_f32_e32 v47, 0xbfb8aa3b, v47
	v_mul_f32_e32 v43, 0x3fcc422a, v43
	v_mul_f32_e32 v46, 0x3fcc422a, v46
	v_exp_f32_e32 v47, v47
	v_mul_f32_e32 v43, 0xbfb8aa3b, v43
	v_mul_f32_e32 v46, 0xbfb8aa3b, v46
	v_exp_f32_e32 v43, v43
	v_exp_f32_e32 v46, v46
	v_cvt_pk_bf16_f32 v41, v41, v42
	v_add_f32_e32 v42, 1.0, v47
	v_rcp_f32_e32 v42, v42
	v_add_f32_e32 v43, 1.0, v43
	v_add_f32_e32 v46, 1.0, v46
	v_rcp_f32_e32 v43, v43
	v_rcp_f32_e32 v46, v46
	v_mul_f32_e32 v37, v37, v42
	v_cvt_pk_bf16_f32 v42, v36, v37
	v_mul_f32_e32 v36, v38, v43
	v_mul_f32_e32 v37, v39, v46
	v_cvt_pk_bf16_f32 v43, v36, v37
	v_mul_f32_e32 v36, 0x3d372713, v32
	v_mul_f32_e32 v37, 0x3d372713, v33
	v_mul_f32_e32 v36, v32, v36
	v_mul_f32_e32 v37, v33, v37
	v_fma_f32 v36, v32, v36, v32
	v_fma_f32 v37, v33, v37, v33
	v_mul_f32_e32 v36, 0x3fcc422a, v36
	v_mul_f32_e32 v37, 0x3fcc422a, v37
	v_mul_f32_e32 v36, 0xbfb8aa3b, v36
	v_mul_f32_e32 v37, 0xbfb8aa3b, v37
	v_exp_f32_e32 v36, v36
	v_exp_f32_e32 v37, v37
	v_mul_f32_e32 v38, 0x3d372713, v34
	v_mul_f32_e32 v38, v34, v38
	v_add_f32_e32 v36, 1.0, v36
	v_add_f32_e32 v37, 1.0, v37
	v_rcp_f32_e32 v36, v36
	v_rcp_f32_e32 v37, v37
	v_fma_f32 v38, v34, v38, v34
	v_mul_f32_e32 v38, 0x3fcc422a, v38
	v_mul_f32_e32 v38, 0xbfb8aa3b, v38
	v_exp_f32_e32 v38, v38
	v_mul_f32_e32 v32, v32, v36
	v_mul_f32_e32 v33, v33, v37
	v_mul_f32_e32 v36, 0x3d372713, v35
	v_mul_f32_e32 v37, 0x3d372713, v28
	v_mul_f32_e32 v36, v35, v36
	v_mul_f32_e32 v37, v28, v37
	v_fma_f32 v36, v35, v36, v35
	v_fma_f32 v37, v28, v37, v28
	global_store_dwordx4 v[44:45], v[40:43], off offset:256 sc1
	v_mul_f32_e32 v36, 0x3fcc422a, v36
	v_mul_f32_e32 v37, 0x3fcc422a, v37
	v_cvt_pk_bf16_f32 v32, v32, v33
	v_add_f32_e32 v33, 1.0, v38
	v_mul_f32_e32 v36, 0xbfb8aa3b, v36
	v_mul_f32_e32 v37, 0xbfb8aa3b, v37
	v_rcp_f32_e32 v33, v33
	v_exp_f32_e32 v36, v36
	v_exp_f32_e32 v37, v37
	v_mul_f32_e32 v33, v34, v33
	v_add_f32_e32 v34, 1.0, v36
	v_add_f32_e32 v36, 1.0, v37
	v_rcp_f32_e32 v34, v34
	v_rcp_f32_e32 v36, v36
	v_mul_f32_e32 v37, 0x3d372713, v29
	v_mul_f32_e32 v37, v29, v37
	v_mul_f32_e32 v34, v35, v34
	v_mul_f32_e32 v28, v28, v36
	v_mul_f32_e32 v35, 0x3d372713, v30
	v_mul_f32_e32 v36, 0x3d372713, v31
	v_fma_f32 v37, v29, v37, v29
	v_mul_f32_e32 v35, v30, v35
	v_mul_f32_e32 v36, v31, v36
	v_mul_f32_e32 v37, 0x3fcc422a, v37
	v_fma_f32 v35, v30, v35, v30
	v_fma_f32 v36, v31, v36, v31
	v_mul_f32_e32 v37, 0xbfb8aa3b, v37
	v_mul_f32_e32 v35, 0x3fcc422a, v35
	v_mul_f32_e32 v36, 0x3fcc422a, v36
	v_exp_f32_e32 v37, v37
	v_mul_f32_e32 v35, 0xbfb8aa3b, v35
	v_mul_f32_e32 v36, 0xbfb8aa3b, v36
	v_exp_f32_e32 v35, v35
	v_exp_f32_e32 v36, v36
	v_cvt_pk_bf16_f32 v33, v33, v34
	v_add_f32_e32 v34, 1.0, v37
	v_rcp_f32_e32 v34, v34
	v_add_f32_e32 v35, 1.0, v35
	v_add_f32_e32 v36, 1.0, v36
	v_rcp_f32_e32 v35, v35
	v_rcp_f32_e32 v36, v36
	v_mul_f32_e32 v29, v29, v34
	v_cvt_pk_bf16_f32 v34, v28, v29
	v_mul_f32_e32 v28, v30, v35
	v_mul_f32_e32 v29, v31, v36
	v_mul_f32_e32 v30, 0x3d372713, v24
	v_mul_f32_e32 v31, 0x3d372713, v25
	v_mul_f32_e32 v30, v24, v30
	v_mul_f32_e32 v31, v25, v31
	v_fma_f32 v30, v24, v30, v24
	v_fma_f32 v31, v25, v31, v25
	v_mul_f32_e32 v30, 0x3fcc422a, v30
	v_mul_f32_e32 v31, 0x3fcc422a, v31
	v_mul_f32_e32 v30, 0xbfb8aa3b, v30
	v_mul_f32_e32 v31, 0xbfb8aa3b, v31
	v_exp_f32_e32 v30, v30
	v_exp_f32_e32 v31, v31
	v_cvt_pk_bf16_f32 v35, v28, v29
	v_add_co_u32_e32 v28, vcc, s55, v60
	v_add_f32_e32 v30, 1.0, v30
	s_nop 0
	v_addc_co_u32_e32 v29, vcc, 0, v61, vcc
	global_store_dwordx4 v[28:29], v[32:35], off sc1
	v_add_f32_e32 v31, 1.0, v31
	v_rcp_f32_e32 v30, v30
	v_mul_f32_e32 v32, 0x3d372713, v26
	v_rcp_f32_e32 v31, v31
	v_mul_f32_e32 v32, v26, v32
	v_fma_f32 v32, v26, v32, v26
	v_mul_f32_e32 v32, 0x3fcc422a, v32
	v_mul_f32_e32 v32, 0xbfb8aa3b, v32
	v_exp_f32_e32 v32, v32
	v_mul_f32_e32 v24, v24, v30
	v_mul_f32_e32 v25, v25, v31
	v_mul_f32_e32 v30, 0x3d372713, v27
	v_mul_f32_e32 v31, 0x3d372713, v20
	v_mul_f32_e32 v30, v27, v30
	v_mul_f32_e32 v31, v20, v31
	v_fma_f32 v30, v27, v30, v27
	v_fma_f32 v31, v20, v31, v20
	v_mul_f32_e32 v30, 0x3fcc422a, v30
	v_mul_f32_e32 v31, 0x3fcc422a, v31
	v_cvt_pk_bf16_f32 v24, v24, v25
	v_add_f32_e32 v25, 1.0, v32
	v_mul_f32_e32 v30, 0xbfb8aa3b, v30
	v_mul_f32_e32 v31, 0xbfb8aa3b, v31
	v_rcp_f32_e32 v25, v25
	v_exp_f32_e32 v30, v30
; __device__ __forceinline__ unsigned cvt_pk_bf16(float lo, float hi) { unsigned r; asm volatile("v_cvt_pk_bf16_f32 %0, %1, %2" : "=v"(r) : "v"(lo), "v"(hi)); return r; }
; __device__ __forceinline__ float gelu_tanh(float x) { const float u = 1.5957691216057308f * (x + 0.044715f * x * x * x); return x * sigmoidf_(u); }
; __device__ __forceinline__ float sigmoidf_(float x) { return __builtin_amdgcn_rcpf(1.0f + __builtin_amdgcn_exp2f(-1.4426950408889634f * x)); }
;     __device__ __forceinline__ void operator()(const f32x4 (&acc)[2][2][4][2], const Unit& u, int wr, int wc, int fr, int fq) const {
;     ...
;                 for (int bj = 0; bj < 2; ++bj) { const f32x4 v0 = acc[ai][bj][m][0], v1 = acc[ai][bj][m][1];
;                     const int j = 8 * bj + 2 * wc + (fq >> 1), p0 = 8 * (fq & 1);
;                     u32x4 w; w.x = cvt_pk_bf16(gelu_tanh(v0[0]), gelu_tanh(v0[1])); w.y = cvt_pk_bf16(gelu_tanh(v0[2]), gelu_tanh(v0[3]));
;                     w.z = cvt_pk_bf16(gelu_tanh(v1[0]), gelu_tanh(v1[1])); w.w = cvt_pk_bf16(gelu_tanh(v1[2]), gelu_tanh(v1[3]));
;                     *(u32x4*)(Zb + (size_t)g * (16384 * 16) + (size_t)(bc * 16 + j) * 16 + p0) = w; asm volatile("" ::: "memory"); } }
	v_exp_f32_e32 v31, v31
	v_mul_f32_e32 v25, v26, v25
	v_add_f32_e32 v26, 1.0, v30
	v_add_f32_e32 v30, 1.0, v31
	v_rcp_f32_e32 v26, v26
	v_rcp_f32_e32 v30, v30
	v_mul_f32_e32 v31, 0x3d372713, v21
	v_mul_f32_e32 v31, v21, v31
	v_mul_f32_e32 v26, v27, v26
	v_mul_f32_e32 v20, v20, v30
	v_mul_f32_e32 v27, 0x3d372713, v22
	v_mul_f32_e32 v30, 0x3d372713, v23
	v_fma_f32 v31, v21, v31, v21
	v_mul_f32_e32 v27, v22, v27
	v_mul_f32_e32 v30, v23, v30
	v_mul_f32_e32 v31, 0x3fcc422a, v31
	v_fma_f32 v27, v22, v27, v22
	v_fma_f32 v30, v23, v30, v23
	v_mul_f32_e32 v31, 0xbfb8aa3b, v31
	v_mul_f32_e32 v27, 0x3fcc422a, v27
	v_mul_f32_e32 v30, 0x3fcc422a, v30
	v_exp_f32_e32 v31, v31
	v_mul_f32_e32 v27, 0xbfb8aa3b, v27
	v_mul_f32_e32 v30, 0xbfb8aa3b, v30
	v_exp_f32_e32 v27, v27
	v_exp_f32_e32 v30, v30
	v_cvt_pk_bf16_f32 v25, v25, v26
	v_add_f32_e32 v26, 1.0, v31
	v_rcp_f32_e32 v26, v26
	v_add_f32_e32 v27, 1.0, v27
	v_add_f32_e32 v30, 1.0, v30
	v_rcp_f32_e32 v27, v27
	v_rcp_f32_e32 v30, v30
	v_mul_f32_e32 v21, v21, v26
	v_cvt_pk_bf16_f32 v26, v20, v21
	v_mul_f32_e32 v20, v22, v27
	v_mul_f32_e32 v21, v23, v30
	v_cvt_pk_bf16_f32 v27, v20, v21
	v_mul_f32_e32 v20, 0x3d372713, v16
	v_mul_f32_e32 v21, 0x3d372713, v17
	v_mul_f32_e32 v20, v16, v20
	v_mul_f32_e32 v21, v17, v21
	v_fma_f32 v20, v16, v20, v16
	v_fma_f32 v21, v17, v21, v17
	v_mul_f32_e32 v20, 0x3fcc422a, v20
	v_mul_f32_e32 v21, 0x3fcc422a, v21
	v_mul_f32_e32 v20, 0xbfb8aa3b, v20
	v_mul_f32_e32 v21, 0xbfb8aa3b, v21
	v_exp_f32_e32 v20, v20
	v_exp_f32_e32 v21, v21
	v_mul_f32_e32 v22, 0x3d372713, v18
	v_mul_f32_e32 v22, v18, v22
	v_add_f32_e32 v20, 1.0, v20
	v_add_f32_e32 v21, 1.0, v21
	v_rcp_f32_e32 v20, v20
	v_rcp_f32_e32 v21, v21
	v_fma_f32 v22, v18, v22, v18
	v_mul_f32_e32 v22, 0x3fcc422a, v22
	v_mul_f32_e32 v22, 0xbfb8aa3b, v22
	v_exp_f32_e32 v22, v22
	v_mul_f32_e32 v16, v16, v20
	v_mul_f32_e32 v17, v17, v21
	v_mul_f32_e32 v20, 0x3d372713, v19
	v_mul_f32_e32 v21, 0x3d372713, v12
	v_mul_f32_e32 v20, v19, v20
	v_mul_f32_e32 v21, v12, v21
	v_fma_f32 v20, v19, v20, v19
	v_fma_f32 v21, v12, v21, v12
	global_store_dwordx4 v[28:29], v[24:27], off offset:256 sc1
	v_mul_f32_e32 v20, 0x3fcc422a, v20
	v_mul_f32_e32 v21, 0x3fcc422a, v21
	v_cvt_pk_bf16_f32 v16, v16, v17
	v_add_f32_e32 v17, 1.0, v22
	v_mul_f32_e32 v20, 0xbfb8aa3b, v20
	v_mul_f32_e32 v21, 0xbfb8aa3b, v21
	v_rcp_f32_e32 v17, v17
	v_exp_f32_e32 v20, v20
	v_exp_f32_e32 v21, v21
	v_mul_f32_e32 v17, v18, v17
	v_add_f32_e32 v18, 1.0, v20
	v_add_f32_e32 v20, 1.0, v21
	v_rcp_f32_e32 v18, v18
	v_rcp_f32_e32 v20, v20
	v_mul_f32_e32 v21, 0x3d372713, v13
	v_mul_f32_e32 v21, v13, v21
	v_mul_f32_e32 v18, v19, v18
	v_mul_f32_e32 v12, v12, v20
	v_mul_f32_e32 v19, 0x3d372713, v14
	v_mul_f32_e32 v20, 0x3d372713, v15
	v_fma_f32 v21, v13, v21, v13
	v_mul_f32_e32 v19, v14, v19
	v_mul_f32_e32 v20, v15, v20
	v_mul_f32_e32 v21, 0x3fcc422a, v21
	v_fma_f32 v19, v14, v19, v14
	v_fma_f32 v20, v15, v20, v15
	v_mul_f32_e32 v21, 0xbfb8aa3b, v21
	v_mul_f32_e32 v19, 0x3fcc422a, v19
	v_mul_f32_e32 v20, 0x3fcc422a, v20
	v_exp_f32_e32 v21, v21
	v_mul_f32_e32 v19, 0xbfb8aa3b, v19
	v_mul_f32_e32 v20, 0xbfb8aa3b, v20
	v_exp_f32_e32 v19, v19
	v_exp_f32_e32 v20, v20
	v_cvt_pk_bf16_f32 v17, v17, v18
	v_add_f32_e32 v18, 1.0, v21
	v_rcp_f32_e32 v18, v18
	v_add_f32_e32 v19, 1.0, v19
	v_add_f32_e32 v20, 1.0, v20
	v_rcp_f32_e32 v19, v19
	v_rcp_f32_e32 v20, v20
	v_mul_f32_e32 v13, v13, v18
	v_cvt_pk_bf16_f32 v18, v12, v13
	v_mul_f32_e32 v12, v14, v19
	v_mul_f32_e32 v13, v15, v20
	v_mul_f32_e32 v14, 0x3d372713, v8
	v_mul_f32_e32 v15, 0x3d372713, v9
	v_mul_f32_e32 v14, v8, v14
	v_mul_f32_e32 v15, v9, v15
	v_fma_f32 v14, v8, v14, v8
	v_fma_f32 v15, v9, v15, v9
	v_mul_f32_e32 v14, 0x3fcc422a, v14
	v_mul_f32_e32 v15, 0x3fcc422a, v15
	v_mul_f32_e32 v14, 0xbfb8aa3b, v14
	v_mul_f32_e32 v15, 0xbfb8aa3b, v15
	v_exp_f32_e32 v14, v14
	v_exp_f32_e32 v15, v15
	v_cvt_pk_bf16_f32 v19, v12, v13
	v_add_co_u32_e32 v12, vcc, s46, v60
	v_add_f32_e32 v14, 1.0, v14
	s_nop 0
	v_addc_co_u32_e32 v13, vcc, 0, v61, vcc
	global_store_dwordx4 v[12:13], v[16:19], off sc1
	v_add_f32_e32 v15, 1.0, v15
	v_rcp_f32_e32 v14, v14
	v_mul_f32_e32 v16, 0x3d372713, v10
	v_rcp_f32_e32 v15, v15
	v_mul_f32_e32 v16, v10, v16
	v_fma_f32 v16, v10, v16, v10
	v_mul_f32_e32 v16, 0x3fcc422a, v16
	v_mul_f32_e32 v16, 0xbfb8aa3b, v16
	v_exp_f32_e32 v16, v16
	v_mul_f32_e32 v8, v8, v14
	v_mul_f32_e32 v9, v9, v15
	v_mul_f32_e32 v14, 0x3d372713, v11
	v_mul_f32_e32 v15, 0x3d372713, v4
	v_mul_f32_e32 v14, v11, v14
	v_mul_f32_e32 v15, v4, v15
	v_fma_f32 v14, v11, v14, v11
	v_fma_f32 v15, v4, v15, v4
	v_mul_f32_e32 v14, 0x3fcc422a, v14
	v_mul_f32_e32 v15, 0x3fcc422a, v15
	v_cvt_pk_bf16_f32 v8, v8, v9
	v_add_f32_e32 v9, 1.0, v16
	v_mul_f32_e32 v14, 0xbfb8aa3b, v14
	v_mul_f32_e32 v15, 0xbfb8aa3b, v15
	v_rcp_f32_e32 v9, v9
	v_exp_f32_e32 v14, v14
	v_exp_f32_e32 v15, v15
	s_and_b64 vcc, exec, s[0:1]
	v_mul_f32_e32 v9, v10, v9
	v_add_f32_e32 v10, 1.0, v14
	v_add_f32_e32 v14, 1.0, v15
	v_rcp_f32_e32 v10, v10
	v_rcp_f32_e32 v14, v14
	v_mul_f32_e32 v15, 0x3d372713, v5
	v_mul_f32_e32 v15, v5, v15
	v_mul_f32_e32 v10, v11, v10
	v_mul_f32_e32 v4, v4, v14
	v_mul_f32_e32 v11, 0x3d372713, v6
	v_mul_f32_e32 v14, 0x3d372713, v7
	v_fma_f32 v15, v5, v15, v5
	v_mul_f32_e32 v11, v6, v11
	v_mul_f32_e32 v14, v7, v14
	v_mul_f32_e32 v15, 0x3fcc422a, v15
	v_fma_f32 v11, v6, v11, v6
	v_fma_f32 v14, v7, v14, v7
	v_mul_f32_e32 v15, 0xbfb8aa3b, v15
	v_mul_f32_e32 v11, 0x3fcc422a, v11
	v_mul_f32_e32 v14, 0x3fcc422a, v14
	v_exp_f32_e32 v15, v15
	v_mul_f32_e32 v11, 0xbfb8aa3b, v11
	v_mul_f32_e32 v14, 0xbfb8aa3b, v14
	v_exp_f32_e32 v11, v11
	v_exp_f32_e32 v14, v14
	v_cvt_pk_bf16_f32 v9, v9, v10
	v_add_f32_e32 v10, 1.0, v15
	v_rcp_f32_e32 v10, v10
	v_add_f32_e32 v11, 1.0, v11
	v_add_f32_e32 v14, 1.0, v14
	v_rcp_f32_e32 v11, v11
	v_rcp_f32_e32 v14, v14
	v_mul_f32_e32 v5, v5, v10
	v_cvt_pk_bf16_f32 v10, v4, v5
	v_mul_f32_e32 v4, v6, v11
	v_mul_f32_e32 v5, v7, v14
	v_cvt_pk_bf16_f32 v11, v4, v5
	global_store_dwordx4 v[12:13], v[8:11], off offset:256 sc1
	v_readfirstlane_b32 s0, v0
	s_cbranch_vccnz .LBB0_643
	s_andn2_b64 vcc, exec, s[8:9]
	s_cbranch_vccnz .LBB0_642
	s_barrier
	s_branch .LBB0_642

; __device__ __forceinline__ unsigned cvt_pk_bf16(float lo, float hi) { unsigned r; asm volatile("v_cvt_pk_bf16_f32 %0, %1, %2" : "=v"(r) : "v"(lo), "v"(hi)); return r; }
; __device__ __forceinline__ void attn_phase(LAS unsigned char* lds, int vcu, int G, const bf16* Qp, const bf16* Kp, const bf16* Vt, const float* sinks, bf16* AO, int ldo, float* st) {
;     ...
;             float ssq = 0.f;
; #pragma unroll
;             for (int dh = 0; dh < 2; ++dh)
; #pragma unroll
;                 for (int r = 0; r < 16; ++r) ssq += o[dh][r] * o[dh][r];
;             ssq += __shfl_xor(ssq, 32);
;             ssq_acc += ssq;
;         }
;         bf16* orow = AO + (tok0 + q0 + 32 * qsub + r32) * (size_t)ldo + h * HD + 4 * hi;
; #pragma unroll
;         for (int dh = 0; dh < 2; ++dh)
; #pragma unroll
;             for (int g4 = 0; g4 < 4; ++g4) { v2u w; w.x = cvt_pk_bf16(o[dh][4 * g4], o[dh][4 * g4 + 1]); w.y = cvt_pk_bf16(o[dh][4 * g4 + 2], o[dh][4 * g4 + 3]);
;                 *(v2u*)(orow + dh * 32 + 8 * g4) = w; }
.LBB0_655:
	s_nop 7
	v_mul_f32_e32 v3, v35, v35
	v_fmac_f32_e32 v3, v34, v34
	v_fmac_f32_e32 v3, v36, v36
	v_fmac_f32_e32 v3, v37, v37
	v_fmac_f32_e32 v3, v38, v38
	v_fmac_f32_e32 v3, v39, v39
	v_fmac_f32_e32 v3, v40, v40
	v_fmac_f32_e32 v3, v41, v41
	v_fmac_f32_e32 v3, v42, v42
	v_fmac_f32_e32 v3, v43, v43
	v_fmac_f32_e32 v3, v44, v44
	v_fmac_f32_e32 v3, v45, v45
	v_fmac_f32_e32 v3, v46, v46
	v_fmac_f32_e32 v3, v47, v47
	v_fmac_f32_e32 v3, v48, v48
	v_fmac_f32_e32 v3, v49, v49
	v_fmac_f32_e32 v3, v18, v18
	v_fmac_f32_e32 v3, v19, v19
	v_fmac_f32_e32 v3, v20, v20
	v_fmac_f32_e32 v3, v21, v21
	v_fmac_f32_e32 v3, v22, v22
	v_fmac_f32_e32 v3, v23, v23
	v_pk_mul_f32 v[12:13], v[24:25], v[24:25]
	v_pk_mul_f32 v[10:11], v[26:27], v[26:27]
	v_add_f32_e32 v3, v12, v3
	v_add_f32_e32 v3, v13, v3
	v_add_f32_e32 v3, v10, v3
	v_pk_mul_f32 v[8:9], v[28:29], v[28:29]
	v_add_f32_e32 v3, v11, v3
	v_add_f32_e32 v3, v8, v3
	v_pk_mul_f32 v[6:7], v[30:31], v[30:31]
	v_add_f32_e32 v3, v9, v3
	v_add_f32_e32 v3, v6, v3
	v_pk_mul_f32 v[4:5], v[32:33], v[32:33]
	v_add_f32_e32 v3, v7, v3
	v_add_f32_e32 v3, v4, v3
	v_add_f32_e32 v3, v5, v3
	ds_bpermute_b32 v4, v172, v3
	v_cvt_pk_bf16_f32 v6, v34, v35
	v_cvt_pk_bf16_f32 v7, v36, v37
	s_add_u32 s76, s76, 16
	s_addc_u32 s77, s77, 0
	s_waitcnt lgkmcnt(0)
	v_add_f32_e32 v3, v3, v4
	v_lshl_add_u64 v[4:5], s[94:95], 0, v[136:137]
	global_store_dwordx2 v[4:5], v[6:7], off offset:-64 sc1
	v_cvt_pk_bf16_f32 v6, v38, v39
	v_cvt_pk_bf16_f32 v7, v40, v41
	global_store_dwordx2 v[4:5], v[6:7], off offset:-48 sc1
	v_cvt_pk_bf16_f32 v6, v42, v43
	v_cvt_pk_bf16_f32 v7, v44, v45
	global_store_dwordx2 v[4:5], v[6:7], off offset:-32 sc1
	v_cvt_pk_bf16_f32 v6, v46, v47
	v_cvt_pk_bf16_f32 v7, v48, v49
	global_store_dwordx2 v[4:5], v[6:7], off offset:-16 sc1
	v_cvt_pk_bf16_f32 v6, v18, v19
	v_cvt_pk_bf16_f32 v7, v20, v21
	global_store_dwordx2 v[4:5], v[6:7], off sc1
	v_cvt_pk_bf16_f32 v6, v22, v23
	v_cvt_pk_bf16_f32 v7, v24, v25
	global_store_dwordx2 v[4:5], v[6:7], off offset:16 sc1
	v_cvt_pk_bf16_f32 v6, v26, v27
	v_cvt_pk_bf16_f32 v7, v28, v29
	global_store_dwordx2 v[4:5], v[6:7], off offset:32 sc1
	v_cvt_pk_bf16_f32 v6, v30, v31
	v_cvt_pk_bf16_f32 v7, v32, v33
	global_store_dwordx2 v[4:5], v[6:7], off offset:48 sc1
	s_waitcnt lgkmcnt(0)
	v_add_f32_e32 v159, v159, v3
	v_lshl_add_u64 v[124:125], v[124:125], 0, s[78:79]
	v_lshl_add_u64 v[126:127], v[126:127], 0, s[78:79]
	v_lshl_add_u64 v[128:129], v[128:129], 0, s[78:79]
	v_lshl_add_u64 v[130:131], v[130:131], 0, s[90:91]
	v_lshl_add_u64 v[132:133], v[132:133], 0, s[90:91]
	v_lshl_add_u64 v[134:135], v[134:135], 0, s[90:91]
	v_lshl_add_u64 v[136:137], v[136:137], 0, s[86:87]
	s_cmp_eq_u32 s76, 64
	v_lshl_add_u64 v[138:139], v[138:139], 0, s[86:87]
	s_barrier
	s_cbranch_scc1 .LBB0_700

; #define LAS __attribute__((address_space(3)))
; #define LDS_WAIT() asm volatile("s_waitcnt lgkmcnt(0)" ::: "memory")
; __device__ __forceinline__ void attn_phase(LAS unsigned char* lds, int vcu, int G, const bf16* Qp, const bf16* Kp, const bf16* Vt, const float* sinks, bf16* AO, int ldo, float* st) {
;     ...
;     {
;         LAS float* Xs = (LAS float*)lds;
;         if (hi == 0) Xs[(qsub * 4 + hq) * 32 + r32] = ssq_acc;
;         LDS_WAIT(); __syncthreads();
;         if (hq == 0 && hi == 0) { const float tot = (Xs[(qsub * 4 + 0) * 32 + r32] + Xs[(qsub * 4 + 1) * 32 + r32]) + (Xs[(qsub * 4 + 2) * 32 + r32] + Xs[(qsub * 4 + 3) * 32 + r32]);
;             st[(size_t)(vcu >> 5) * SEQ + 64 * (vcu & 31) + 32 * qsub + r32] = tot; }
;         LDS_WAIT(); __syncthreads();
.LBB0_702:
	s_or_b64 exec, exec, s[0:1]
	s_waitcnt lgkmcnt(0)
	s_add_u32 s12, s94, 0x40000
	v_or_b32_e32 v2, s4, v141
	s_addc_u32 s13, s95, 0
	v_cmp_eq_u32_e32 vcc, 0, v2
	s_waitcnt lgkmcnt(0)
	s_barrier
	s_and_saveexec_b64 s[0:1], vcc
	v_readlane_b32 s66, v254, 55
	v_readlane_b32 s72, v254, 53
	v_readlane_b32 s76, v254, 43
	v_readlane_b32 s78, v254, 41
	v_readlane_b32 s82, v254, 39
	v_readlane_b32 s86, v254, 37
	s_mov_b32 s74, s66
	v_readlane_b32 s73, v254, 54
	v_readlane_b32 s54, v254, 52
	v_readlane_b32 s50, v254, 51
	v_readlane_b32 s3, v254, 58
	v_readlane_b32 s77, v254, 44
	v_readlane_b32 s79, v254, 42
	v_readlane_b32 s83, v254, 40
	v_readlane_b32 s87, v254, 38
	v_readlane_b32 s67, v254, 56
	s_cbranch_execz .LBB0_704
	s_lshl_b32 s2, s2, 9
	s_add_i32 s2, s2, 0
	v_lshlrev_b32_e32 v8, 2, v140
	s_ashr_i32 s4, s3, 5
	v_add_u32_e32 v4, s2, v8
	s_ashr_i32 s5, s4, 31
	ds_read2_b32 v[2:3], v4 offset1:32
	ds_read2_b32 v[4:5], v4 offset0:64 offset1:96
	s_lshl_b64 s[4:5], s[4:5], 13
	s_add_u32 s2, s12, s4
	v_readlane_b32 s4, v254, 61
	s_addc_u32 s3, s13, s5
	s_lshl_b32 s4, s4, 2
	s_add_u32 s2, s2, s4
	v_readlane_b32 s4, v254, 59
	v_readlane_b32 s5, v254, 60
	s_waitcnt lgkmcnt(1)
	v_mov_b32_e32 v6, v2
	s_waitcnt lgkmcnt(0)
	v_mov_b32_e32 v7, v4
	v_mov_b32_e32 v4, v3
	s_addc_u32 s3, s3, 0
	s_lshl_b64 s[4:5], s[4:5], 2
	v_pk_add_f32 v[2:3], v[6:7], v[4:5]
	s_add_u32 s4, s2, s4
	v_add_f32_e32 v2, v2, v3
	s_addc_u32 s5, s3, s5
	global_store_dword v8, v2, s[4:5] sc1
